# delayed ALIGN_EPI barrier: leading half starts its epilogue beside the trailing half's last MFMA block and takes the alignment barrier part-way into the epilogue (all 4 GEMMs)
# speedup vs baseline: 1.0214x; 1.0016x over previous
; #define PG8_STAGE(bufoff, gbase, voff) do { _Pragma("unroll") for (int _i = 0; _i < 2; ++_i) \
;         __builtin_amdgcn_global_load_lds((const unsigned*)((const char*)(gbase) + (voff)[_i]), (PG8_LAS unsigned*)(lds + (bufoff) + ldsw + _i * 8192), 16, 0, 0); } while (0)
; #define PG8_LDA(dst, b, h) do { _Pragma("unroll") for (int m = 0; m < 4; ++m) _Pragma("unroll") for (int k = 0; k < 2; ++k) dst[m][k] = *(const PG8_LAS bf16x8*)(lds + PG8_SA(b, h) + aoff + m * 2048 + k * 1024); } while (0)
; #define PG8_LDB(dst, b, h) do { _Pragma("unroll") for (int n = 0; n < 2; ++n) _Pragma("unroll") for (int k = 0; k < 2; ++k) dst[n][k] = *(const PG8_LAS bf16x8*)(lds + PG8_SB(b, h) + boff + n * 2048 + k * 1024); } while (0)
; #define PG8_MMA(ai, bj, At, Bt) do { __builtin_amdgcn_s_setprio(1); _Pragma("unroll") for (int m = 0; m < 4; ++m) _Pragma("unroll") for (int n = 0; n < 2; ++n) _Pragma("unroll") for (int k = 0; k < 2; ++k) \
;         acc[ai][bj][m][n] = __builtin_amdgcn_mfma_f32_16x16x32_bf16(Bt[n][k], At[m][k], acc[ai][bj][m][n], 0, 0, 0); __builtin_amdgcn_s_setprio(0); } while (0)
; #define PG8_WAIT_V(n) asm volatile("s_waitcnt vmcnt(" #n ")" ::: "memory")
; #define PG8_BAR __builtin_amdgcn_s_barrier()
; template <class Epi, class Sched, bool ALIGN_EPI = false, bool SP2 = false>
; __device__ __forceinline__ void gemm_phase(PG8_LAS unsigned char* lds, const Gemm g, const Sched& S, const Epi& E) {
;     ...
;         for (int t = 0; t < nt; t += 2) {
;             const bool last = (t == nt - 2);
;             const char* a1 = cA + (size_t)(t + 1) * kstep;
;             const char* a2 = last ? nA : cA + (size_t)(t + 2) * kstep; const char* b2 = last ? nB : cB + (size_t)(t + 2) * kstep;
;             const char* a3 = a2 + kstep; const char* b3 = b2 + kstep;
;             if (last && has_next) S.a_ready(nxt);
;             if constexpr (SP2) {
;             PG8_LDB(B0, 0, 0); PG8_LDB(B1, 0, 1); PG8_SCHED; PG8_LDA(At, 0, 0); PG8_STAGE(PG8_SA(1, 1), a1 + hstep, voffA);
;             PG8_WAIT_V(8); PG8_WAIT_L(0); PG8_BAR; PG8_MMA(0, 0, At, B0); PG8_MMA(0, 1, At, B1); PG8_BAR; PG8_SCHED;
;             PG8_LDA(At, 0, 1); PG8_STAGE(PG8_SB(0, 0), b2, voffB); PG8_STAGE(PG8_SB(0, 1), b2 + hstep, voffB); PG8_STAGE(PG8_SA(0, 0), a2, voffA);
;             PG8_WAIT_V(8); PG8_WAIT_L(0); PG8_BAR; PG8_MMA(1, 0, At, B0); PG8_MMA(1, 1, At, B1); PG8_BAR; PG8_SCHED;
.LBB0_219:
	s_add_u32 s46, s38, 0xfffc0080
	s_addc_u32 s47, s39, -1
	s_add_i32 s56, 0, 0x10000
	s_cmp_eq_u32 vcc_lo, 12
	s_cselect_b32 s49, s50, s47
	s_cselect_b32 s48, s51, s46
	s_cselect_b32 s47, s52, s73
	s_cselect_b32 s46, s53, s71
	s_add_i32 vcc_hi, 0, 0x14000
	v_add_u32_e32 v152, s56, v165
	v_add_u32_e32 v169, vcc_hi, v165
	ds_read_b128 v[128:131], v152
	ds_read_b128 v[144:147], v152 offset:1024
	ds_read_b128 v[148:151], v152 offset:2048
	ds_read_b128 v[152:155], v152 offset:3072
	ds_read_b128 v[156:159], v169
	ds_read_b128 v[160:163], v169 offset:1024
	ds_read_b128 v[170:173], v169 offset:2048
	ds_read_b128 v[180:183], v169 offset:3072
	v_lshl_add_u64 v[176:177], s[38:39], 0, v[140:141]
	s_add_i32 m0, s9, 0xc000
	ds_read_b128 v[184:187], v168
	ds_read_b128 v[188:191], v168 offset:1024
	ds_read_b128 v[192:195], v168 offset:2048
	ds_read_b128 v[196:199], v168 offset:3072
	ds_read_b128 v[200:203], v168 offset:4096
	ds_read_b128 v[204:207], v168 offset:5120
	ds_read_b128 v[218:221], v168 offset:6144
	ds_read_b128 v[222:225], v168 offset:7168
	global_load_lds_dwordx4 v[176:177], off
	v_lshl_add_u64 v[176:177], s[38:39], 0, v[142:143]
	s_add_i32 m0, s9, 0xe000
	s_nop 0
	global_load_lds_dwordx4 v[176:177], off
	s_waitcnt vmcnt(8)
	s_waitcnt lgkmcnt(0)
	s_setprio 1
	s_barrier
	v_mfma_f32_16x16x32_bf16 v[124:127], v[128:131], v[184:187], v[124:127]
	v_mfma_f32_16x16x32_bf16 v[120:123], v[148:151], v[184:187], v[120:123]
	v_mfma_f32_16x16x32_bf16 v[108:111], v[128:131], v[192:195], v[108:111]
	v_mfma_f32_16x16x32_bf16 v[104:107], v[148:151], v[192:195], v[104:107]
	v_mfma_f32_16x16x32_bf16 v[92:95], v[128:131], v[200:203], v[92:95]
	v_mfma_f32_16x16x32_bf16 v[88:91], v[148:151], v[200:203], v[88:91]
	v_mfma_f32_16x16x32_bf16 v[76:79], v[128:131], v[218:221], v[76:79]
	v_mfma_f32_16x16x32_bf16 v[72:75], v[148:151], v[218:221], v[72:75]
	v_mfma_f32_16x16x32_bf16 v[124:127], v[144:147], v[188:191], v[124:127]
	v_mfma_f32_16x16x32_bf16 v[120:123], v[152:155], v[188:191], v[120:123]
	v_mfma_f32_16x16x32_bf16 v[108:111], v[144:147], v[196:199], v[108:111]
	v_mfma_f32_16x16x32_bf16 v[104:107], v[152:155], v[196:199], v[104:107]
	v_mfma_f32_16x16x32_bf16 v[92:95], v[144:147], v[204:207], v[92:95]
	v_mfma_f32_16x16x32_bf16 v[88:91], v[152:155], v[204:207], v[88:91]
	v_mfma_f32_16x16x32_bf16 v[76:79], v[144:147], v[222:225], v[76:79]
	v_mfma_f32_16x16x32_bf16 v[72:75], v[152:155], v[222:225], v[72:75]
	v_mfma_f32_16x16x32_bf16 v[116:119], v[156:159], v[184:187], v[116:119]
	v_mfma_f32_16x16x32_bf16 v[112:115], v[170:173], v[184:187], v[112:115]
	v_mfma_f32_16x16x32_bf16 v[100:103], v[156:159], v[192:195], v[100:103]
	v_mfma_f32_16x16x32_bf16 v[96:99], v[170:173], v[192:195], v[96:99]
	v_mfma_f32_16x16x32_bf16 v[84:87], v[156:159], v[200:203], v[84:87]
	v_mfma_f32_16x16x32_bf16 v[80:83], v[170:173], v[200:203], v[80:83]
	v_mfma_f32_16x16x32_bf16 v[68:71], v[156:159], v[218:221], v[68:71]
	v_mfma_f32_16x16x32_bf16 v[64:67], v[170:173], v[218:221], v[64:67]
	v_mfma_f32_16x16x32_bf16 v[116:119], v[160:163], v[188:191], v[116:119]
	v_mfma_f32_16x16x32_bf16 v[112:115], v[180:183], v[188:191], v[112:115]
	v_mfma_f32_16x16x32_bf16 v[100:103], v[160:163], v[196:199], v[100:103]
	v_mfma_f32_16x16x32_bf16 v[96:99], v[180:183], v[196:199], v[96:99]
	v_mfma_f32_16x16x32_bf16 v[84:87], v[160:163], v[204:207], v[84:87]
	v_mfma_f32_16x16x32_bf16 v[80:83], v[180:183], v[204:207], v[80:83]
	v_mfma_f32_16x16x32_bf16 v[68:71], v[160:163], v[222:225], v[68:71]
	v_mfma_f32_16x16x32_bf16 v[64:67], v[180:183], v[222:225], v[64:67]
	s_barrier
	s_setprio 0
	s_add_i32 s56, s56, s8
	v_lshl_add_u64 v[176:177], s[46:47], 0, v[174:175]
	s_mov_b32 m0, s56
	ds_read_b128 v[184:187], v168 offset:16384
	ds_read_b128 v[188:191], v168 offset:17408
	ds_read_b128 v[192:195], v168 offset:18432
	ds_read_b128 v[196:199], v168 offset:19456
	ds_read_b128 v[200:203], v168 offset:20480
	ds_read_b128 v[204:207], v168 offset:21504
	ds_read_b128 v[218:221], v168 offset:22528
	ds_read_b128 v[222:225], v168 offset:23552
	global_load_lds_dwordx4 v[176:177], off
	s_add_i32 m0, s56, 0x2000
	s_add_u32 s56, s46, 0x40000
	v_lshl_add_u64 v[178:179], s[46:47], 0, v[136:137]
	s_addc_u32 s57, s47, 0
	s_add_i32 vcc_hi, vcc_hi, s8
	global_load_lds_dwordx4 v[178:179], off
	v_lshl_add_u64 v[208:209], s[56:57], 0, v[174:175]
	s_mov_b32 m0, vcc_hi
	v_lshl_add_u64 v[226:227], s[48:49], 0, v[134:135]
	global_load_lds_dwordx4 v[208:209], off
	v_lshl_add_u64 v[208:209], s[56:57], 0, v[136:137]
	s_add_i32 m0, vcc_hi, 0x2000
	s_nop 0
	global_load_lds_dwordx4 v[208:209], off
	v_lshl_add_u64 v[208:209], s[48:49], 0, v[132:133]
	s_mov_b32 m0, s9
	s_nop 0
	global_load_lds_dwordx4 v[208:209], off
	s_mov_b32 m0, s79
	s_nop 0
	global_load_lds_dwordx4 v[226:227], off
	s_waitcnt vmcnt(8)
	s_waitcnt lgkmcnt(0)
	s_setprio 1
	s_barrier
; #define PG8_STAGE(bufoff, gbase, voff) do { _Pragma("unroll") for (int _i = 0; _i < 2; ++_i) \
;         __builtin_amdgcn_global_load_lds((const unsigned*)((const char*)(gbase) + (voff)[_i]), (PG8_LAS unsigned*)(lds + (bufoff) + ldsw + _i * 8192), 16, 0, 0); } while (0)
; #define PG8_LDA(dst, b, h) do { _Pragma("unroll") for (int m = 0; m < 4; ++m) _Pragma("unroll") for (int k = 0; k < 2; ++k) dst[m][k] = *(const PG8_LAS bf16x8*)(lds + PG8_SA(b, h) + aoff + m * 2048 + k * 1024); } while (0)
; #define PG8_LDB(dst, b, h) do { _Pragma("unroll") for (int n = 0; n < 2; ++n) _Pragma("unroll") for (int k = 0; k < 2; ++k) dst[n][k] = *(const PG8_LAS bf16x8*)(lds + PG8_SB(b, h) + boff + n * 2048 + k * 1024); } while (0)
; #define PG8_MMA(ai, bj, At, Bt) do { __builtin_amdgcn_s_setprio(1); _Pragma("unroll") for (int m = 0; m < 4; ++m) _Pragma("unroll") for (int n = 0; n < 2; ++n) _Pragma("unroll") for (int k = 0; k < 2; ++k) \
;         acc[ai][bj][m][n] = __builtin_amdgcn_mfma_f32_16x16x32_bf16(Bt[n][k], At[m][k], acc[ai][bj][m][n], 0, 0, 0); __builtin_amdgcn_s_setprio(0); } while (0)
; #define PG8_WAIT_V(n) asm volatile("s_waitcnt vmcnt(" #n ")" ::: "memory")
; #define PG8_WAIT_L(n) asm volatile("s_waitcnt lgkmcnt(" #n ")" ::: "memory")
; #define PG8_BAR __builtin_amdgcn_s_barrier()
; #define PG8_SCHED __builtin_amdgcn_sched_barrier(0)
; template <class Epi, class Sched, bool ALIGN_EPI = false, bool SP2 = false>
; __device__ __forceinline__ void gemm_phase(PG8_LAS unsigned char* lds, const Gemm g, const Sched& S, const Epi& E) {
;     ...
;             PG8_WAIT_V(8); PG8_WAIT_L(0); PG8_BAR; PG8_MMA(1, 0, At, B0); PG8_MMA(1, 1, At, B1); PG8_BAR; PG8_SCHED;
;             PG8_LDB(B0, 1, 0); PG8_LDB(B1, 1, 1); PG8_SCHED; PG8_LDA(At, 1, 0); PG8_STAGE(PG8_SA(0, 1), a2 + hstep, voffA);
;             PG8_WAIT_V(8); PG8_WAIT_L(0); PG8_BAR; PG8_MMA(0, 0, At, B0); PG8_MMA(0, 1, At, B1); PG8_BAR; PG8_SCHED;
	v_mfma_f32_16x16x32_bf16 v[60:63], v[128:131], v[184:187], v[60:63]
	v_mfma_f32_16x16x32_bf16 v[56:59], v[148:151], v[184:187], v[56:59]
	v_mfma_f32_16x16x32_bf16 v[44:47], v[128:131], v[192:195], v[44:47]
	v_mfma_f32_16x16x32_bf16 v[40:43], v[148:151], v[192:195], v[40:43]
	v_mfma_f32_16x16x32_bf16 v[28:31], v[128:131], v[200:203], v[28:31]
	v_mfma_f32_16x16x32_bf16 v[24:27], v[148:151], v[200:203], v[24:27]
	v_mfma_f32_16x16x32_bf16 v[12:15], v[128:131], v[218:221], v[12:15]
	v_mfma_f32_16x16x32_bf16 v[8:11], v[148:151], v[218:221], v[8:11]
	v_mfma_f32_16x16x32_bf16 v[60:63], v[144:147], v[188:191], v[60:63]
	v_mfma_f32_16x16x32_bf16 v[56:59], v[152:155], v[188:191], v[56:59]
	v_mfma_f32_16x16x32_bf16 v[44:47], v[144:147], v[196:199], v[44:47]
	v_mfma_f32_16x16x32_bf16 v[40:43], v[152:155], v[196:199], v[40:43]
	v_mfma_f32_16x16x32_bf16 v[28:31], v[144:147], v[204:207], v[28:31]
	v_mfma_f32_16x16x32_bf16 v[24:27], v[152:155], v[204:207], v[24:27]
	v_mfma_f32_16x16x32_bf16 v[12:15], v[144:147], v[222:225], v[12:15]
	v_mfma_f32_16x16x32_bf16 v[8:11], v[152:155], v[222:225], v[8:11]
	v_mfma_f32_16x16x32_bf16 v[52:55], v[156:159], v[184:187], v[52:55]
	v_mfma_f32_16x16x32_bf16 v[48:51], v[170:173], v[184:187], v[48:51]
	v_mfma_f32_16x16x32_bf16 v[36:39], v[156:159], v[192:195], v[36:39]
	v_mfma_f32_16x16x32_bf16 v[32:35], v[170:173], v[192:195], v[32:35]
	v_mfma_f32_16x16x32_bf16 v[20:23], v[156:159], v[200:203], v[20:23]
	v_mfma_f32_16x16x32_bf16 v[16:19], v[170:173], v[200:203], v[16:19]
	v_mfma_f32_16x16x32_bf16 v[4:7], v[156:159], v[218:221], v[4:7]
	v_mfma_f32_16x16x32_bf16 v[0:3], v[170:173], v[218:221], v[0:3]
	v_mfma_f32_16x16x32_bf16 v[52:55], v[160:163], v[188:191], v[52:55]
	v_mfma_f32_16x16x32_bf16 v[48:51], v[180:183], v[188:191], v[48:51]
	v_mfma_f32_16x16x32_bf16 v[36:39], v[160:163], v[196:199], v[36:39]
	v_mfma_f32_16x16x32_bf16 v[32:35], v[180:183], v[196:199], v[32:35]
	v_mfma_f32_16x16x32_bf16 v[20:23], v[160:163], v[204:207], v[20:23]
	v_mfma_f32_16x16x32_bf16 v[16:19], v[180:183], v[204:207], v[16:19]
	v_mfma_f32_16x16x32_bf16 v[4:7], v[160:163], v[222:225], v[4:7]
	v_mfma_f32_16x16x32_bf16 v[0:3], v[180:183], v[222:225], v[0:3]
	s_barrier
	s_setprio 0
	s_add_i32 s56, 0, 0x18000
	s_add_i32 s57, 0, 0x1c000
	v_add_u32_e32 v152, s56, v165
	v_add_u32_e32 v169, s57, v165
	ds_read_b128 v[128:131], v152
	ds_read_b128 v[144:147], v152 offset:1024
	ds_read_b128 v[148:151], v152 offset:2048
	ds_read_b128 v[152:155], v152 offset:3072
	ds_read_b128 v[156:159], v169
	ds_read_b128 v[160:163], v169 offset:1024
	ds_read_b128 v[170:173], v169 offset:2048
	ds_read_b128 v[180:183], v169 offset:3072
	s_add_u32 s48, s48, 0x40000
	s_addc_u32 s49, s49, 0
	s_mov_b32 m0, s54
	v_lshl_add_u64 v[228:229], s[48:49], 0, v[132:133]
	ds_read_b128 v[184:187], v168 offset:32768
	ds_read_b128 v[188:191], v168 offset:33792
	ds_read_b128 v[192:195], v168 offset:34816
	ds_read_b128 v[196:199], v168 offset:35840
	ds_read_b128 v[200:203], v168 offset:36864
	ds_read_b128 v[204:207], v168 offset:37888
	ds_read_b128 v[218:221], v168 offset:38912
	ds_read_b128 v[222:225], v168 offset:39936
	global_load_lds_dwordx4 v[228:229], off
	v_lshl_add_u64 v[228:229], s[48:49], 0, v[134:135]
	s_mov_b32 m0, s55
	s_nop 0
	global_load_lds_dwordx4 v[228:229], off
	s_waitcnt vmcnt(8)
	s_waitcnt lgkmcnt(0)
	s_setprio 1
	s_barrier
	v_mfma_f32_16x16x32_bf16 v[124:127], v[128:131], v[184:187], v[124:127]
	v_mfma_f32_16x16x32_bf16 v[120:123], v[148:151], v[184:187], v[120:123]
	v_mfma_f32_16x16x32_bf16 v[108:111], v[128:131], v[192:195], v[108:111]
	v_mfma_f32_16x16x32_bf16 v[104:107], v[148:151], v[192:195], v[104:107]
	v_mfma_f32_16x16x32_bf16 v[92:95], v[128:131], v[200:203], v[92:95]
	v_mfma_f32_16x16x32_bf16 v[88:91], v[148:151], v[200:203], v[88:91]
	v_mfma_f32_16x16x32_bf16 v[76:79], v[128:131], v[218:221], v[76:79]
	v_mfma_f32_16x16x32_bf16 v[72:75], v[148:151], v[218:221], v[72:75]
	v_mfma_f32_16x16x32_bf16 v[124:127], v[144:147], v[188:191], v[124:127]
	v_mfma_f32_16x16x32_bf16 v[120:123], v[152:155], v[188:191], v[120:123]
	v_mfma_f32_16x16x32_bf16 v[108:111], v[144:147], v[196:199], v[108:111]
	v_mfma_f32_16x16x32_bf16 v[104:107], v[152:155], v[196:199], v[104:107]
	v_mfma_f32_16x16x32_bf16 v[92:95], v[144:147], v[204:207], v[92:95]
	v_mfma_f32_16x16x32_bf16 v[88:91], v[152:155], v[204:207], v[88:91]
	v_mfma_f32_16x16x32_bf16 v[76:79], v[144:147], v[222:225], v[76:79]
	v_mfma_f32_16x16x32_bf16 v[72:75], v[152:155], v[222:225], v[72:75]
	v_mfma_f32_16x16x32_bf16 v[116:119], v[156:159], v[184:187], v[116:119]
	v_mfma_f32_16x16x32_bf16 v[112:115], v[170:173], v[184:187], v[112:115]
	v_mfma_f32_16x16x32_bf16 v[100:103], v[156:159], v[192:195], v[100:103]
	v_mfma_f32_16x16x32_bf16 v[96:99], v[170:173], v[192:195], v[96:99]
	v_mfma_f32_16x16x32_bf16 v[84:87], v[156:159], v[200:203], v[84:87]
	v_mfma_f32_16x16x32_bf16 v[80:83], v[170:173], v[200:203], v[80:83]
	v_mfma_f32_16x16x32_bf16 v[68:71], v[156:159], v[218:221], v[68:71]
	v_mfma_f32_16x16x32_bf16 v[64:67], v[170:173], v[218:221], v[64:67]
	v_mfma_f32_16x16x32_bf16 v[116:119], v[160:163], v[188:191], v[116:119]
	v_mfma_f32_16x16x32_bf16 v[112:115], v[180:183], v[188:191], v[112:115]
	v_mfma_f32_16x16x32_bf16 v[100:103], v[160:163], v[196:199], v[100:103]
	v_mfma_f32_16x16x32_bf16 v[96:99], v[180:183], v[196:199], v[96:99]
	v_mfma_f32_16x16x32_bf16 v[84:87], v[160:163], v[204:207], v[84:87]
	v_mfma_f32_16x16x32_bf16 v[80:83], v[180:183], v[204:207], v[80:83]
	v_mfma_f32_16x16x32_bf16 v[68:71], v[160:163], v[222:225], v[68:71]
	v_mfma_f32_16x16x32_bf16 v[64:67], v[180:183], v[222:225], v[64:67]
	s_barrier
; #define PG8_STAGE(bufoff, gbase, voff) do { _Pragma("unroll") for (int _i = 0; _i < 2; ++_i) \
;         __builtin_amdgcn_global_load_lds((const unsigned*)((const char*)(gbase) + (voff)[_i]), (PG8_LAS unsigned*)(lds + (bufoff) + ldsw + _i * 8192), 16, 0, 0); } while (0)
; #define PG8_LDA(dst, b, h) do { _Pragma("unroll") for (int m = 0; m < 4; ++m) _Pragma("unroll") for (int k = 0; k < 2; ++k) dst[m][k] = *(const PG8_LAS bf16x8*)(lds + PG8_SA(b, h) + aoff + m * 2048 + k * 1024); } while (0)
; #define PG8_MMA(ai, bj, At, Bt) do { __builtin_amdgcn_s_setprio(1); _Pragma("unroll") for (int m = 0; m < 4; ++m) _Pragma("unroll") for (int n = 0; n < 2; ++n) _Pragma("unroll") for (int k = 0; k < 2; ++k) \
;         acc[ai][bj][m][n] = __builtin_amdgcn_mfma_f32_16x16x32_bf16(Bt[n][k], At[m][k], acc[ai][bj][m][n], 0, 0, 0); __builtin_amdgcn_s_setprio(0); } while (0)
; #define PG8_WAIT_V(n) asm volatile("s_waitcnt vmcnt(" #n ")" ::: "memory")
; #define PG8_WAIT_L(n) asm volatile("s_waitcnt lgkmcnt(" #n ")" ::: "memory")
; #define PG8_BAR __builtin_amdgcn_s_barrier()
; #define PG8_SCHED __builtin_amdgcn_sched_barrier(0)
;     __device__ __forceinline__ void operator()(const f32x4 (&acc)[2][2][4][2], const Unit& u, int wr, int wc, int fr, int fq, int ui, PG8_LAS unsigned char* lds) const {
;     ...
;         const int sec = (u.pn * BM) >> 10;
;         int act = 0; float sc = 1.f;
;         if (mode == 0) act = (sec == 0 || sec == 3) ? 1 : (sec == 1 ? 2 : 0);
;         else if (mode == 1) sc = (sec == 0) ? qscale : 1.f;
;         else act = 3;
;         const bool ksum = (mode == 1) && (sec == 1);
; template <class Epi, class Sched, bool ALIGN_EPI = false, bool SP2 = false>
; __device__ __forceinline__ void gemm_phase(PG8_LAS unsigned char* lds, const Gemm g, const Sched& S, const Epi& E) {
;     ...
;             PG8_LDA(At, 1, 1); PG8_STAGE(PG8_SB(1, 0), b3, voffB); PG8_STAGE(PG8_SB(1, 1), b3 + hstep, voffB); PG8_STAGE(PG8_SA(1, 0), a3, voffA);
;             PG8_WAIT_V(8); PG8_WAIT_L(0); PG8_BAR; PG8_MMA(1, 0, At, B0); PG8_MMA(1, 1, At, B1); PG8_BAR; PG8_SCHED;
;     ...
;         if constexpr (ALIGN_EPI) { if (wr == 0) PG8_BAR; }
	s_setprio 0
	s_add_i32 s48, s56, s8
	v_lshl_add_u64 v[176:177], v[176:177], 0, s[4:5]
	s_mov_b32 m0, s48
	ds_read_b128 v[184:187], v168 offset:49152
	ds_read_b128 v[188:191], v168 offset:50176
	ds_read_b128 v[192:195], v168 offset:51200
	ds_read_b128 v[196:199], v168 offset:52224
	ds_read_b128 v[200:203], v168 offset:53248
	ds_read_b128 v[204:207], v168 offset:54272
	ds_read_b128 v[218:221], v168 offset:55296
	ds_read_b128 v[222:225], v168 offset:56320
	global_load_lds_dwordx4 v[176:177], off
	s_add_i32 m0, s48, 0x2000
	s_add_u32 s46, s46, 0x40080
	v_lshl_add_u64 v[176:177], v[178:179], 0, s[4:5]
	s_addc_u32 s47, s47, 0
	s_add_i32 s48, s57, s8
	global_load_lds_dwordx4 v[176:177], off
	v_lshl_add_u64 v[176:177], s[46:47], 0, v[174:175]
	s_mov_b32 m0, s48
	s_nop 0
	global_load_lds_dwordx4 v[176:177], off
	v_lshl_add_u64 v[176:177], s[46:47], 0, v[136:137]
	s_add_i32 m0, s48, 0x2000
	s_nop 0
	global_load_lds_dwordx4 v[176:177], off
	v_lshl_add_u64 v[176:177], v[208:209], 0, s[4:5]
	s_mov_b32 m0, s93
	s_nop 0
	global_load_lds_dwordx4 v[176:177], off
	v_lshl_add_u64 v[176:177], v[226:227], 0, s[4:5]
	s_mov_b32 m0, s66
	s_nop 0
	global_load_lds_dwordx4 v[176:177], off
	s_waitcnt vmcnt(8)
	s_waitcnt lgkmcnt(0)
	s_setprio 1
	s_barrier
	v_mfma_f32_16x16x32_bf16 v[60:63], v[128:131], v[184:187], v[60:63]
	v_mfma_f32_16x16x32_bf16 v[56:59], v[148:151], v[184:187], v[56:59]
	v_mfma_f32_16x16x32_bf16 v[44:47], v[128:131], v[192:195], v[44:47]
	v_mfma_f32_16x16x32_bf16 v[40:43], v[148:151], v[192:195], v[40:43]
	v_mfma_f32_16x16x32_bf16 v[28:31], v[128:131], v[200:203], v[28:31]
	v_mfma_f32_16x16x32_bf16 v[24:27], v[148:151], v[200:203], v[24:27]
	v_mfma_f32_16x16x32_bf16 v[12:15], v[128:131], v[218:221], v[12:15]
	v_mfma_f32_16x16x32_bf16 v[8:11], v[148:151], v[218:221], v[8:11]
	v_mfma_f32_16x16x32_bf16 v[60:63], v[144:147], v[188:191], v[60:63]
	v_mfma_f32_16x16x32_bf16 v[56:59], v[152:155], v[188:191], v[56:59]
	v_mfma_f32_16x16x32_bf16 v[44:47], v[144:147], v[196:199], v[44:47]
	v_mfma_f32_16x16x32_bf16 v[40:43], v[152:155], v[196:199], v[40:43]
	v_mfma_f32_16x16x32_bf16 v[28:31], v[144:147], v[204:207], v[28:31]
	v_mfma_f32_16x16x32_bf16 v[24:27], v[152:155], v[204:207], v[24:27]
	v_mfma_f32_16x16x32_bf16 v[12:15], v[144:147], v[222:225], v[12:15]
	v_mfma_f32_16x16x32_bf16 v[8:11], v[152:155], v[222:225], v[8:11]
	v_mfma_f32_16x16x32_bf16 v[52:55], v[156:159], v[184:187], v[52:55]
	v_mfma_f32_16x16x32_bf16 v[48:51], v[170:173], v[184:187], v[48:51]
	v_mfma_f32_16x16x32_bf16 v[36:39], v[156:159], v[192:195], v[36:39]
	v_mfma_f32_16x16x32_bf16 v[32:35], v[170:173], v[192:195], v[32:35]
	v_mfma_f32_16x16x32_bf16 v[20:23], v[156:159], v[200:203], v[20:23]
	v_mfma_f32_16x16x32_bf16 v[16:19], v[170:173], v[200:203], v[16:19]
	v_mfma_f32_16x16x32_bf16 v[4:7], v[156:159], v[218:221], v[4:7]
	v_mfma_f32_16x16x32_bf16 v[0:3], v[170:173], v[218:221], v[0:3]
	v_mfma_f32_16x16x32_bf16 v[52:55], v[160:163], v[188:191], v[52:55]
	v_mfma_f32_16x16x32_bf16 v[48:51], v[180:183], v[188:191], v[48:51]
	v_mfma_f32_16x16x32_bf16 v[36:39], v[160:163], v[196:199], v[36:39]
	v_mfma_f32_16x16x32_bf16 v[32:35], v[180:183], v[196:199], v[32:35]
	v_mfma_f32_16x16x32_bf16 v[20:23], v[160:163], v[204:207], v[20:23]
	v_mfma_f32_16x16x32_bf16 v[16:19], v[180:183], v[204:207], v[16:19]
	v_mfma_f32_16x16x32_bf16 v[4:7], v[160:163], v[222:225], v[4:7]
	v_mfma_f32_16x16x32_bf16 v[0:3], v[180:183], v[222:225], v[0:3]
	s_barrier
	s_setprio 0
	s_add_i32 vcc_lo, vcc_lo, 2
	s_add_u32 s38, s38, 0x100
	s_addc_u32 s39, s39, 0
	s_add_u32 s71, s71, 0x100
	s_addc_u32 s73, s73, 0
	s_cmp_gt_u32 vcc_lo, 13
	s_cbranch_scc0 .LBB0_219
.LBB0_222:
	s_ashr_i32 s71, s0, 2
	s_cmp_lt_u32 s0, 4
	s_cselect_b64 s[46:47], -1, 0
	s_andn2_b64 vcc, exec, s[60:61]
	s_mov_b64 s[38:39], -1
	s_cbranch_vccnz .LBB0_224
	s_cmp_eq_u32 s71, 3
	s_cselect_b64 s[38:39], -1, 0
	s_or_b64 s[38:39], s[46:47], s[38:39]
	s_cmp_eq_u32 s71, 1
	s_cselect_b32 s48, 2, 0
	s_and_b64 s[38:39], s[38:39], exec
	s_cselect_b32 s48, 1, s48
	s_mov_b64 s[38:39], 0

;     __device__ __forceinline__ void operator()(const f32x4 (&acc)[2][2][4][2], const Unit& u, int wr, int wc, int fr, int fq, int ui, PG8_LAS unsigned char* lds) const {
;         const int row0 = u.pm * BM + wr * 64 + fr, col0 = u.pn * BM + wc * 32 + 8 * fq;
;         const PG8_LAS float* tab = (const PG8_LAS float*)(lds + RSTD_TAB) + ui * 256 + wr * 64 + fr;
;         const int sec = (u.pn * BM) >> 10;
;         int act = 0; float sc = 1.f;
;         if (mode == 0) act = (sec == 0 || sec == 3) ? 1 : (sec == 1 ? 2 : 0);
;         else if (mode == 1) sc = (sec == 0) ? qscale : 1.f;
;         else act = 3;
;         const bool ksum = (mode == 1) && (sec == 1);
;         f32x4 csum[2][2] = {{(f32x4){0.f, 0.f, 0.f, 0.f}, (f32x4){0.f, 0.f, 0.f, 0.f}}, {(f32x4){0.f, 0.f, 0.f, 0.f}, (f32x4){0.f, 0.f, 0.f, 0.f}}};
; #pragma unroll
;         for (int ai = 0; ai < 2; ++ai) {
;             float rs4[4];
; #pragma unroll
;             for (int m = 0; m < 4; ++m) {
;                 if ((m & 1) == 0) {
;                     if (use_tab) { rs4[m] = tab[ai * HALF + m * 16] * sc; rs4[m + 1] = tab[ai * HALF + (m + 1) * 16] * sc; }
;                     else {
;                         asm volatile("" ::: "memory");
;                         rs4[m] = __builtin_amdgcn_rsqf(ssq_row(ssq, row0 + ai * HALF + m * 16) * (1.0f / 1024.0f) + RMS_EPS) * sc;
;                         rs4[m + 1] = __builtin_amdgcn_rsqf(ssq_row(ssq, row0 + ai * HALF + (m + 1) * 16) * (1.0f / 1024.0f) + RMS_EPS) * sc;
;                     }
;                 }
;                 const int row = row0 + ai * HALF + m * 16;
;                 const float rs = rs4[m];
;                 bf16_t* rowp = O + (size_t)row * ldc + col0;
; #pragma unroll
;                 for (int bj = 0; bj < 2; ++bj) {
;                     f32x4 v[2] = {acc[ai][bj][m][0] * rs, acc[ai][bj][m][1] * rs};
;                     if (ksum) { csum[bj][0] += v[0]; csum[bj][1] += v[1]; }
; #pragma unroll
;                     for (int n = 0; n < 2; ++n) {
;                         f32x4 lbv = (f32x4){0.f, 0.f, 0.f, 0.f};
;                         if (act == 2) lbv = *(const f32x4*)(lb + (col0 - 1024) + bj * HALF + 4 * n);
; #pragma unroll
;                         for (int e = 0; e < 4; ++e) {
;                             float x = v[n][e];
;                             if (act == 1) x = silu_f(x);
.Lepi_id:
	v_lshl_add_u32 v150, s78, 8, v164
	s_lshl_b32 s1, s1, 10
	v_add_u32_e32 v170, s1, v166
	ds_read_b32 v128, v170
	ds_read_b32 v130, v170 offset:64
	ds_read_b32 v144, v170 offset:128
	ds_read_b32 v146, v170 offset:192
	ds_read_b32 v148, v170 offset:512
	ds_read_b32 v156, v170 offset:576
	ds_read_b32 v158, v170 offset:640
	ds_read_b32 v160, v170 offset:704
	s_lshl_b32 s73, s0, 8
	v_or_b32_e32 v172, s73, v167
	v_mov_b32_e32 v173, 0
	v_mad_u64_u32 v[162:163], s[38:39], v150, s96, 0
	s_lshl_b32 s46, s96, 5
	s_mov_b32 s47, 0
	s_lshl_b32 s52, s96, 8
	s_mov_b32 s53, 0
	v_lshl_add_u64 v[162:163], v[162:163], 1, s[14:15]
	v_lshl_add_u64 v[162:163], v[172:173], 1, v[162:163]
	v_lshl_add_u64 v[178:179], v[162:163], 0, s[52:53]
	s_waitcnt lgkmcnt(0)
	v_mul_f32_e32 v128, v169, v128
	v_mul_f32_e32 v130, v169, v130
	v_mul_f32_e32 v144, v169, v144
	v_mul_f32_e32 v146, v169, v146
	v_mul_f32_e32 v148, v169, v148
	v_mul_f32_e32 v156, v169, v156
	v_mul_f32_e32 v158, v169, v158
	v_mul_f32_e32 v160, v169, v160
	v_pk_mul_f32 v[124:125], v[124:125], v[128:129] op_sel_hi:[1,0]
	v_pk_mul_f32 v[126:127], v[126:127], v[128:129] op_sel_hi:[1,0]
	v_pk_mul_f32 v[120:121], v[120:121], v[128:129] op_sel_hi:[1,0]
	v_pk_mul_f32 v[122:123], v[122:123], v[128:129] op_sel_hi:[1,0]
	v_cvt_pk_bf16_f32 v124, v124, v125
	v_cvt_pk_bf16_f32 v125, v126, v127
	v_cvt_pk_bf16_f32 v126, v120, v121
	v_cvt_pk_bf16_f32 v127, v122, v123
	global_store_dwordx4 v[162:163], v[124:127], off
	v_pk_mul_f32 v[116:117], v[116:117], v[128:129] op_sel_hi:[1,0]
	v_pk_mul_f32 v[118:119], v[118:119], v[128:129] op_sel_hi:[1,0]
	v_pk_mul_f32 v[112:113], v[112:113], v[128:129] op_sel_hi:[1,0]
	v_pk_mul_f32 v[114:115], v[114:115], v[128:129] op_sel_hi:[1,0]
	v_cvt_pk_bf16_f32 v116, v116, v117
	v_cvt_pk_bf16_f32 v117, v118, v119
	v_cvt_pk_bf16_f32 v118, v112, v113
	v_cvt_pk_bf16_f32 v119, v114, v115
	global_store_dwordx4 v[162:163], v[116:119], off offset:256
	v_lshl_add_u64 v[176:177], v[162:163], 0, s[46:47]
	v_pk_mul_f32 v[108:109], v[108:109], v[130:131] op_sel_hi:[1,0]
	v_pk_mul_f32 v[110:111], v[110:111], v[130:131] op_sel_hi:[1,0]
	v_pk_mul_f32 v[104:105], v[104:105], v[130:131] op_sel_hi:[1,0]
	v_pk_mul_f32 v[106:107], v[106:107], v[130:131] op_sel_hi:[1,0]
	v_cvt_pk_bf16_f32 v108, v108, v109
	v_cvt_pk_bf16_f32 v109, v110, v111
	v_cvt_pk_bf16_f32 v110, v104, v105
	v_cvt_pk_bf16_f32 v111, v106, v107
	global_store_dwordx4 v[176:177], v[108:111], off
	v_pk_mul_f32 v[100:101], v[100:101], v[130:131] op_sel_hi:[1,0]
	v_pk_mul_f32 v[102:103], v[102:103], v[130:131] op_sel_hi:[1,0]
	v_pk_mul_f32 v[96:97], v[96:97], v[130:131] op_sel_hi:[1,0]
	v_pk_mul_f32 v[98:99], v[98:99], v[130:131] op_sel_hi:[1,0]
	v_cvt_pk_bf16_f32 v100, v100, v101
	v_cvt_pk_bf16_f32 v101, v102, v103
	v_cvt_pk_bf16_f32 v102, v96, v97
	v_cvt_pk_bf16_f32 v103, v98, v99
	global_store_dwordx4 v[176:177], v[100:103], off offset:256
	s_cmp_eq_u64 s[68:69], 0
	s_cbranch_scc1 .Lal1id_skip
	s_barrier
.Lal1id_skip:
	v_lshl_add_u64 v[162:163], v[176:177], 0, s[46:47]
	v_pk_mul_f32 v[92:93], v[92:93], v[144:145] op_sel_hi:[1,0]
	v_pk_mul_f32 v[94:95], v[94:95], v[144:145] op_sel_hi:[1,0]
	v_pk_mul_f32 v[88:89], v[88:89], v[144:145] op_sel_hi:[1,0]
	v_pk_mul_f32 v[90:91], v[90:91], v[144:145] op_sel_hi:[1,0]
	v_cvt_pk_bf16_f32 v92, v92, v93
	v_cvt_pk_bf16_f32 v93, v94, v95
	v_cvt_pk_bf16_f32 v94, v88, v89
	v_cvt_pk_bf16_f32 v95, v90, v91
	global_store_dwordx4 v[162:163], v[92:95], off
	v_pk_mul_f32 v[84:85], v[84:85], v[144:145] op_sel_hi:[1,0]
	v_pk_mul_f32 v[86:87], v[86:87], v[144:145] op_sel_hi:[1,0]
	v_pk_mul_f32 v[80:81], v[80:81], v[144:145] op_sel_hi:[1,0]
	v_pk_mul_f32 v[82:83], v[82:83], v[144:145] op_sel_hi:[1,0]
	v_cvt_pk_bf16_f32 v84, v84, v85
	v_cvt_pk_bf16_f32 v85, v86, v87
	v_cvt_pk_bf16_f32 v86, v80, v81
	v_cvt_pk_bf16_f32 v87, v82, v83
	global_store_dwordx4 v[162:163], v[84:87], off offset:256
	v_lshl_add_u64 v[176:177], v[162:163], 0, s[46:47]
	v_pk_mul_f32 v[76:77], v[76:77], v[146:147] op_sel_hi:[1,0]
	v_pk_mul_f32 v[78:79], v[78:79], v[146:147] op_sel_hi:[1,0]
	v_pk_mul_f32 v[72:73], v[72:73], v[146:147] op_sel_hi:[1,0]
	v_pk_mul_f32 v[74:75], v[74:75], v[146:147] op_sel_hi:[1,0]
	v_cvt_pk_bf16_f32 v76, v76, v77
	v_cvt_pk_bf16_f32 v77, v78, v79
	v_cvt_pk_bf16_f32 v78, v72, v73
	v_cvt_pk_bf16_f32 v79, v74, v75
	global_store_dwordx4 v[176:177], v[76:79], off
	v_pk_mul_f32 v[68:69], v[68:69], v[146:147] op_sel_hi:[1,0]
	v_pk_mul_f32 v[70:71], v[70:71], v[146:147] op_sel_hi:[1,0]
	v_pk_mul_f32 v[64:65], v[64:65], v[146:147] op_sel_hi:[1,0]
	v_pk_mul_f32 v[66:67], v[66:67], v[146:147] op_sel_hi:[1,0]
	v_cvt_pk_bf16_f32 v68, v68, v69
	v_cvt_pk_bf16_f32 v69, v70, v71
	v_cvt_pk_bf16_f32 v70, v64, v65
	v_cvt_pk_bf16_f32 v71, v66, v67
	global_store_dwordx4 v[176:177], v[68:71], off offset:256
	v_lshl_add_u64 v[162:163], v[178:179], 0, 0
	v_pk_mul_f32 v[60:61], v[60:61], v[148:149] op_sel_hi:[1,0]
	v_pk_mul_f32 v[62:63], v[62:63], v[148:149] op_sel_hi:[1,0]
	v_pk_mul_f32 v[56:57], v[56:57], v[148:149] op_sel_hi:[1,0]
	v_pk_mul_f32 v[58:59], v[58:59], v[148:149] op_sel_hi:[1,0]
	v_cvt_pk_bf16_f32 v60, v60, v61
	v_cvt_pk_bf16_f32 v61, v62, v63
	v_cvt_pk_bf16_f32 v62, v56, v57
	v_cvt_pk_bf16_f32 v63, v58, v59
	global_store_dwordx4 v[162:163], v[60:63], off
	v_pk_mul_f32 v[52:53], v[52:53], v[148:149] op_sel_hi:[1,0]
	v_pk_mul_f32 v[54:55], v[54:55], v[148:149] op_sel_hi:[1,0]
	v_pk_mul_f32 v[48:49], v[48:49], v[148:149] op_sel_hi:[1,0]
	v_pk_mul_f32 v[50:51], v[50:51], v[148:149] op_sel_hi:[1,0]
	v_cvt_pk_bf16_f32 v52, v52, v53
	v_cvt_pk_bf16_f32 v53, v54, v55
	v_cvt_pk_bf16_f32 v54, v48, v49
	v_cvt_pk_bf16_f32 v55, v50, v51
; __device__ __forceinline__ float silu_f(float v) { return v * __builtin_amdgcn_rcpf(1.f + __expf(-v)); }
;     __device__ __forceinline__ void operator()(const f32x4 (&acc)[2][2][4][2], const Unit& u, int wr, int wc, int fr, int fq, int ui, PG8_LAS unsigned char* lds) const {
;     ...
;         for (int ai = 0; ai < 2; ++ai) {
;             float rs4[4];
; #pragma unroll
;             for (int m = 0; m < 4; ++m) {
;                 if ((m & 1) == 0) {
;                     if (use_tab) { rs4[m] = tab[ai * HALF + m * 16] * sc; rs4[m + 1] = tab[ai * HALF + (m + 1) * 16] * sc; }
;                     else {
;                         asm volatile("" ::: "memory");
;                         rs4[m] = __builtin_amdgcn_rsqf(ssq_row(ssq, row0 + ai * HALF + m * 16) * (1.0f / 1024.0f) + RMS_EPS) * sc;
;                         rs4[m + 1] = __builtin_amdgcn_rsqf(ssq_row(ssq, row0 + ai * HALF + (m + 1) * 16) * (1.0f / 1024.0f) + RMS_EPS) * sc;
;                     }
;                 }
;                 const int row = row0 + ai * HALF + m * 16;
;                 const float rs = rs4[m];
;                 bf16_t* rowp = O + (size_t)row * ldc + col0;
; #pragma unroll
;                 for (int bj = 0; bj < 2; ++bj) {
;                     f32x4 v[2] = {acc[ai][bj][m][0] * rs, acc[ai][bj][m][1] * rs};
;                     if (ksum) { csum[bj][0] += v[0]; csum[bj][1] += v[1]; }
; #pragma unroll
;                     for (int n = 0; n < 2; ++n) {
;                         f32x4 lbv = (f32x4){0.f, 0.f, 0.f, 0.f};
;                         if (act == 2) lbv = *(const f32x4*)(lb + (col0 - 1024) + bj * HALF + 4 * n);
; #pragma unroll
;                         for (int e = 0; e < 4; ++e) {
;                             float x = v[n][e];
;                             if (act == 1) x = silu_f(x);
;                             else if (act == 2) { const float l = lbv[e]; x = __logf(l + (1.f - l) * __builtin_amdgcn_rcpf(1.f + __expf(-x))); }
;                             else if (act == 3) { x = fmaxf(x, 0.f); x = x * x; }
;                             v[n][e] = x;
;                         }
;                     }
;                     u32x4 w; w.x = cvt_pk_bf16(v[0][0], v[0][1]); w.y = cvt_pk_bf16(v[0][2], v[0][3]); w.z = cvt_pk_bf16(v[1][0], v[1][1]); w.w = cvt_pk_bf16(v[1][2], v[1][3]);
;                     *(u32x4*)(rowp + bj * HALF) = w;
	global_store_dwordx4 v[162:163], v[52:55], off offset:256
	v_lshl_add_u64 v[176:177], v[162:163], 0, s[46:47]
	v_pk_mul_f32 v[44:45], v[44:45], v[156:157] op_sel_hi:[1,0]
	v_pk_mul_f32 v[46:47], v[46:47], v[156:157] op_sel_hi:[1,0]
	v_pk_mul_f32 v[40:41], v[40:41], v[156:157] op_sel_hi:[1,0]
	v_pk_mul_f32 v[42:43], v[42:43], v[156:157] op_sel_hi:[1,0]
	v_cvt_pk_bf16_f32 v44, v44, v45
	v_cvt_pk_bf16_f32 v45, v46, v47
	v_cvt_pk_bf16_f32 v46, v40, v41
	v_cvt_pk_bf16_f32 v47, v42, v43
	global_store_dwordx4 v[176:177], v[44:47], off
	v_pk_mul_f32 v[36:37], v[36:37], v[156:157] op_sel_hi:[1,0]
	v_pk_mul_f32 v[38:39], v[38:39], v[156:157] op_sel_hi:[1,0]
	v_pk_mul_f32 v[32:33], v[32:33], v[156:157] op_sel_hi:[1,0]
	v_pk_mul_f32 v[34:35], v[34:35], v[156:157] op_sel_hi:[1,0]
	v_cvt_pk_bf16_f32 v36, v36, v37
	v_cvt_pk_bf16_f32 v37, v38, v39
	v_cvt_pk_bf16_f32 v38, v32, v33
	v_cvt_pk_bf16_f32 v39, v34, v35
	global_store_dwordx4 v[176:177], v[36:39], off offset:256
	v_lshl_add_u64 v[162:163], v[176:177], 0, s[46:47]
	v_pk_mul_f32 v[28:29], v[28:29], v[158:159] op_sel_hi:[1,0]
	v_pk_mul_f32 v[30:31], v[30:31], v[158:159] op_sel_hi:[1,0]
	v_pk_mul_f32 v[24:25], v[24:25], v[158:159] op_sel_hi:[1,0]
	v_pk_mul_f32 v[26:27], v[26:27], v[158:159] op_sel_hi:[1,0]
	v_cvt_pk_bf16_f32 v28, v28, v29
	v_cvt_pk_bf16_f32 v29, v30, v31
	v_cvt_pk_bf16_f32 v30, v24, v25
	v_cvt_pk_bf16_f32 v31, v26, v27
	global_store_dwordx4 v[162:163], v[28:31], off
	v_pk_mul_f32 v[20:21], v[20:21], v[158:159] op_sel_hi:[1,0]
	v_pk_mul_f32 v[22:23], v[22:23], v[158:159] op_sel_hi:[1,0]
	v_pk_mul_f32 v[16:17], v[16:17], v[158:159] op_sel_hi:[1,0]
	v_pk_mul_f32 v[18:19], v[18:19], v[158:159] op_sel_hi:[1,0]
	v_cvt_pk_bf16_f32 v20, v20, v21
	v_cvt_pk_bf16_f32 v21, v22, v23
	v_cvt_pk_bf16_f32 v22, v16, v17
	v_cvt_pk_bf16_f32 v23, v18, v19
	global_store_dwordx4 v[162:163], v[20:23], off offset:256
	v_lshl_add_u64 v[176:177], v[162:163], 0, s[46:47]
	v_pk_mul_f32 v[12:13], v[12:13], v[160:161] op_sel_hi:[1,0]
	v_pk_mul_f32 v[14:15], v[14:15], v[160:161] op_sel_hi:[1,0]
	v_pk_mul_f32 v[8:9], v[8:9], v[160:161] op_sel_hi:[1,0]
	v_pk_mul_f32 v[10:11], v[10:11], v[160:161] op_sel_hi:[1,0]
	v_cvt_pk_bf16_f32 v12, v12, v13
	v_cvt_pk_bf16_f32 v13, v14, v15
	v_cvt_pk_bf16_f32 v14, v8, v9
	v_cvt_pk_bf16_f32 v15, v10, v11
	global_store_dwordx4 v[176:177], v[12:15], off
	v_pk_mul_f32 v[4:5], v[4:5], v[160:161] op_sel_hi:[1,0]
	v_pk_mul_f32 v[6:7], v[6:7], v[160:161] op_sel_hi:[1,0]
	v_pk_mul_f32 v[0:1], v[0:1], v[160:161] op_sel_hi:[1,0]
	v_pk_mul_f32 v[2:3], v[2:3], v[160:161] op_sel_hi:[1,0]
	v_cvt_pk_bf16_f32 v4, v4, v5
	v_cvt_pk_bf16_f32 v5, v6, v7
	v_cvt_pk_bf16_f32 v6, v0, v1
	v_cvt_pk_bf16_f32 v7, v2, v3
	global_store_dwordx4 v[176:177], v[4:7], off offset:256
	s_branch .LBB0_1108
.Lepi_silu:
	v_lshl_add_u32 v150, s78, 8, v164
	s_lshl_b32 s1, s1, 10
	v_add_u32_e32 v170, s1, v166
	ds_read_b32 v128, v170
	ds_read_b32 v130, v170 offset:64
	ds_read_b32 v144, v170 offset:128
	ds_read_b32 v146, v170 offset:192
	ds_read_b32 v148, v170 offset:512
	ds_read_b32 v156, v170 offset:576
	ds_read_b32 v158, v170 offset:640
	ds_read_b32 v160, v170 offset:704
	s_lshl_b32 s73, s0, 8
	v_or_b32_e32 v172, s73, v167
	v_mov_b32_e32 v173, 0
	v_mad_u64_u32 v[162:163], s[38:39], v150, s96, 0
	s_lshl_b32 s46, s96, 5
	s_mov_b32 s47, 0
	s_lshl_b32 s52, s96, 8
	s_mov_b32 s53, 0
	v_lshl_add_u64 v[162:163], v[162:163], 1, s[14:15]
	v_lshl_add_u64 v[162:163], v[172:173], 1, v[162:163]
	v_lshl_add_u64 v[178:179], v[162:163], 0, s[52:53]
	s_waitcnt lgkmcnt(0)
	v_mul_f32_e32 v128, v169, v128
	v_mul_f32_e32 v130, v169, v130
	v_mul_f32_e32 v144, v169, v144
	v_mul_f32_e32 v146, v169, v146
	v_mul_f32_e32 v148, v169, v148
	v_mul_f32_e32 v156, v169, v156
	v_mul_f32_e32 v158, v169, v158
	v_mul_f32_e32 v160, v169, v160
	v_pk_mul_f32 v[124:125], v[124:125], v[128:129] op_sel_hi:[1,0]
	v_pk_mul_f32 v[126:127], v[126:127], v[128:129] op_sel_hi:[1,0]
	v_pk_mul_f32 v[120:121], v[120:121], v[128:129] op_sel_hi:[1,0]
	v_pk_mul_f32 v[122:123], v[122:123], v[128:129] op_sel_hi:[1,0]
	v_mul_f32_e32 v184, 0xbfb8aa3b, v124
	v_mul_f32_e32 v185, 0xbfb8aa3b, v125
	v_mul_f32_e32 v186, 0xbfb8aa3b, v126
	v_mul_f32_e32 v187, 0xbfb8aa3b, v127
	v_mul_f32_e32 v188, 0xbfb8aa3b, v120
	v_mul_f32_e32 v189, 0xbfb8aa3b, v121
	v_mul_f32_e32 v190, 0xbfb8aa3b, v122
	v_mul_f32_e32 v191, 0xbfb8aa3b, v123
	v_exp_f32_e32 v184, v184
	v_exp_f32_e32 v185, v185
	v_exp_f32_e32 v186, v186
	v_exp_f32_e32 v187, v187
	v_exp_f32_e32 v188, v188
	v_exp_f32_e32 v189, v189
	v_exp_f32_e32 v190, v190
	v_exp_f32_e32 v191, v191
	v_add_f32_e32 v184, 1.0, v184
	v_add_f32_e32 v185, 1.0, v185
	v_add_f32_e32 v186, 1.0, v186
	v_add_f32_e32 v187, 1.0, v187
	v_add_f32_e32 v188, 1.0, v188
	v_add_f32_e32 v189, 1.0, v189
	v_add_f32_e32 v190, 1.0, v190
	v_add_f32_e32 v191, 1.0, v191
	v_rcp_f32_e32 v184, v184
	v_rcp_f32_e32 v185, v185
	v_rcp_f32_e32 v186, v186
	v_rcp_f32_e32 v187, v187
	v_rcp_f32_e32 v188, v188
	v_rcp_f32_e32 v189, v189
	v_rcp_f32_e32 v190, v190
	v_rcp_f32_e32 v191, v191
	v_mul_f32_e32 v124, v124, v184
	v_mul_f32_e32 v125, v125, v185
	v_mul_f32_e32 v126, v126, v186
	v_mul_f32_e32 v127, v127, v187
	v_mul_f32_e32 v120, v120, v188
	v_mul_f32_e32 v121, v121, v189
	v_mul_f32_e32 v122, v122, v190
	v_mul_f32_e32 v123, v123, v191
	v_cvt_pk_bf16_f32 v124, v124, v125
	v_cvt_pk_bf16_f32 v125, v126, v127
	v_cvt_pk_bf16_f32 v126, v120, v121
	v_cvt_pk_bf16_f32 v127, v122, v123
	global_store_dwordx4 v[162:163], v[124:127], off
	v_pk_mul_f32 v[116:117], v[116:117], v[128:129] op_sel_hi:[1,0]
	v_pk_mul_f32 v[118:119], v[118:119], v[128:129] op_sel_hi:[1,0]
	v_pk_mul_f32 v[112:113], v[112:113], v[128:129] op_sel_hi:[1,0]
; __device__ __forceinline__ float silu_f(float v) { return v * __builtin_amdgcn_rcpf(1.f + __expf(-v)); }
;     __device__ __forceinline__ void operator()(const f32x4 (&acc)[2][2][4][2], const Unit& u, int wr, int wc, int fr, int fq, int ui, PG8_LAS unsigned char* lds) const {
;     ...
;         for (int ai = 0; ai < 2; ++ai) {
;             float rs4[4];
; #pragma unroll
;             for (int m = 0; m < 4; ++m) {
;                 if ((m & 1) == 0) {
;                     if (use_tab) { rs4[m] = tab[ai * HALF + m * 16] * sc; rs4[m + 1] = tab[ai * HALF + (m + 1) * 16] * sc; }
;                     else {
;                         asm volatile("" ::: "memory");
;                         rs4[m] = __builtin_amdgcn_rsqf(ssq_row(ssq, row0 + ai * HALF + m * 16) * (1.0f / 1024.0f) + RMS_EPS) * sc;
;                         rs4[m + 1] = __builtin_amdgcn_rsqf(ssq_row(ssq, row0 + ai * HALF + (m + 1) * 16) * (1.0f / 1024.0f) + RMS_EPS) * sc;
;                     }
;                 }
;                 const int row = row0 + ai * HALF + m * 16;
;                 const float rs = rs4[m];
;                 bf16_t* rowp = O + (size_t)row * ldc + col0;
; #pragma unroll
;                 for (int bj = 0; bj < 2; ++bj) {
;                     f32x4 v[2] = {acc[ai][bj][m][0] * rs, acc[ai][bj][m][1] * rs};
;                     if (ksum) { csum[bj][0] += v[0]; csum[bj][1] += v[1]; }
; #pragma unroll
;                     for (int n = 0; n < 2; ++n) {
;                         f32x4 lbv = (f32x4){0.f, 0.f, 0.f, 0.f};
;                         if (act == 2) lbv = *(const f32x4*)(lb + (col0 - 1024) + bj * HALF + 4 * n);
; #pragma unroll
;                         for (int e = 0; e < 4; ++e) {
;                             float x = v[n][e];
;                             if (act == 1) x = silu_f(x);
;                             else if (act == 2) { const float l = lbv[e]; x = __logf(l + (1.f - l) * __builtin_amdgcn_rcpf(1.f + __expf(-x))); }
;                             else if (act == 3) { x = fmaxf(x, 0.f); x = x * x; }
;                             v[n][e] = x;
;                         }
;                     }
;                     u32x4 w; w.x = cvt_pk_bf16(v[0][0], v[0][1]); w.y = cvt_pk_bf16(v[0][2], v[0][3]); w.z = cvt_pk_bf16(v[1][0], v[1][1]); w.w = cvt_pk_bf16(v[1][2], v[1][3]);
;                     *(u32x4*)(rowp + bj * HALF) = w;
	v_pk_mul_f32 v[114:115], v[114:115], v[128:129] op_sel_hi:[1,0]
	v_mul_f32_e32 v184, 0xbfb8aa3b, v116
	v_mul_f32_e32 v185, 0xbfb8aa3b, v117
	v_mul_f32_e32 v186, 0xbfb8aa3b, v118
	v_mul_f32_e32 v187, 0xbfb8aa3b, v119
	v_mul_f32_e32 v188, 0xbfb8aa3b, v112
	v_mul_f32_e32 v189, 0xbfb8aa3b, v113
	v_mul_f32_e32 v190, 0xbfb8aa3b, v114
	v_mul_f32_e32 v191, 0xbfb8aa3b, v115
	v_exp_f32_e32 v184, v184
	v_exp_f32_e32 v185, v185
	v_exp_f32_e32 v186, v186
	v_exp_f32_e32 v187, v187
	v_exp_f32_e32 v188, v188
	v_exp_f32_e32 v189, v189
	v_exp_f32_e32 v190, v190
	v_exp_f32_e32 v191, v191
	v_add_f32_e32 v184, 1.0, v184
	v_add_f32_e32 v185, 1.0, v185
	v_add_f32_e32 v186, 1.0, v186
	v_add_f32_e32 v187, 1.0, v187
	v_add_f32_e32 v188, 1.0, v188
	v_add_f32_e32 v189, 1.0, v189
	v_add_f32_e32 v190, 1.0, v190
	v_add_f32_e32 v191, 1.0, v191
	v_rcp_f32_e32 v184, v184
	v_rcp_f32_e32 v185, v185
	v_rcp_f32_e32 v186, v186
	v_rcp_f32_e32 v187, v187
	v_rcp_f32_e32 v188, v188
	v_rcp_f32_e32 v189, v189
	v_rcp_f32_e32 v190, v190
	v_rcp_f32_e32 v191, v191
	v_mul_f32_e32 v116, v116, v184
	v_mul_f32_e32 v117, v117, v185
	v_mul_f32_e32 v118, v118, v186
	v_mul_f32_e32 v119, v119, v187
	v_mul_f32_e32 v112, v112, v188
	v_mul_f32_e32 v113, v113, v189
	v_mul_f32_e32 v114, v114, v190
	v_mul_f32_e32 v115, v115, v191
	v_cvt_pk_bf16_f32 v116, v116, v117
	v_cvt_pk_bf16_f32 v117, v118, v119
	v_cvt_pk_bf16_f32 v118, v112, v113
	v_cvt_pk_bf16_f32 v119, v114, v115
	global_store_dwordx4 v[162:163], v[116:119], off offset:256
	s_cmp_eq_u64 s[68:69], 0
	s_cbranch_scc1 .Lal1si_skip
	s_barrier
.Lal1si_skip:
	v_lshl_add_u64 v[176:177], v[162:163], 0, s[46:47]
	v_pk_mul_f32 v[108:109], v[108:109], v[130:131] op_sel_hi:[1,0]
	v_pk_mul_f32 v[110:111], v[110:111], v[130:131] op_sel_hi:[1,0]
	v_pk_mul_f32 v[104:105], v[104:105], v[130:131] op_sel_hi:[1,0]
	v_pk_mul_f32 v[106:107], v[106:107], v[130:131] op_sel_hi:[1,0]
	v_mul_f32_e32 v184, 0xbfb8aa3b, v108
	v_mul_f32_e32 v185, 0xbfb8aa3b, v109
	v_mul_f32_e32 v186, 0xbfb8aa3b, v110
	v_mul_f32_e32 v187, 0xbfb8aa3b, v111
	v_mul_f32_e32 v188, 0xbfb8aa3b, v104
	v_mul_f32_e32 v189, 0xbfb8aa3b, v105
	v_mul_f32_e32 v190, 0xbfb8aa3b, v106
	v_mul_f32_e32 v191, 0xbfb8aa3b, v107
	v_exp_f32_e32 v184, v184
	v_exp_f32_e32 v185, v185
	v_exp_f32_e32 v186, v186
	v_exp_f32_e32 v187, v187
	v_exp_f32_e32 v188, v188
	v_exp_f32_e32 v189, v189
	v_exp_f32_e32 v190, v190
	v_exp_f32_e32 v191, v191
	v_add_f32_e32 v184, 1.0, v184
	v_add_f32_e32 v185, 1.0, v185
	v_add_f32_e32 v186, 1.0, v186
	v_add_f32_e32 v187, 1.0, v187
	v_add_f32_e32 v188, 1.0, v188
	v_add_f32_e32 v189, 1.0, v189
	v_add_f32_e32 v190, 1.0, v190
	v_add_f32_e32 v191, 1.0, v191
	v_rcp_f32_e32 v184, v184
	v_rcp_f32_e32 v185, v185
	v_rcp_f32_e32 v186, v186
	v_rcp_f32_e32 v187, v187
	v_rcp_f32_e32 v188, v188
	v_rcp_f32_e32 v189, v189
	v_rcp_f32_e32 v190, v190
	v_rcp_f32_e32 v191, v191
	v_mul_f32_e32 v108, v108, v184
	v_mul_f32_e32 v109, v109, v185
	v_mul_f32_e32 v110, v110, v186
	v_mul_f32_e32 v111, v111, v187
	v_mul_f32_e32 v104, v104, v188
	v_mul_f32_e32 v105, v105, v189
	v_mul_f32_e32 v106, v106, v190
	v_mul_f32_e32 v107, v107, v191
	v_cvt_pk_bf16_f32 v108, v108, v109
	v_cvt_pk_bf16_f32 v109, v110, v111
	v_cvt_pk_bf16_f32 v110, v104, v105
	v_cvt_pk_bf16_f32 v111, v106, v107
	global_store_dwordx4 v[176:177], v[108:111], off
	v_pk_mul_f32 v[100:101], v[100:101], v[130:131] op_sel_hi:[1,0]
	v_pk_mul_f32 v[102:103], v[102:103], v[130:131] op_sel_hi:[1,0]
	v_pk_mul_f32 v[96:97], v[96:97], v[130:131] op_sel_hi:[1,0]
	v_pk_mul_f32 v[98:99], v[98:99], v[130:131] op_sel_hi:[1,0]
	v_mul_f32_e32 v184, 0xbfb8aa3b, v100
	v_mul_f32_e32 v185, 0xbfb8aa3b, v101
	v_mul_f32_e32 v186, 0xbfb8aa3b, v102
	v_mul_f32_e32 v187, 0xbfb8aa3b, v103
	v_mul_f32_e32 v188, 0xbfb8aa3b, v96
	v_mul_f32_e32 v189, 0xbfb8aa3b, v97
	v_mul_f32_e32 v190, 0xbfb8aa3b, v98
	v_mul_f32_e32 v191, 0xbfb8aa3b, v99
	v_exp_f32_e32 v184, v184
	v_exp_f32_e32 v185, v185
	v_exp_f32_e32 v186, v186
	v_exp_f32_e32 v187, v187
	v_exp_f32_e32 v188, v188
	v_exp_f32_e32 v189, v189
	v_exp_f32_e32 v190, v190
	v_exp_f32_e32 v191, v191
	v_add_f32_e32 v184, 1.0, v184
	v_add_f32_e32 v185, 1.0, v185
	v_add_f32_e32 v186, 1.0, v186
	v_add_f32_e32 v187, 1.0, v187
	v_add_f32_e32 v188, 1.0, v188
	v_add_f32_e32 v189, 1.0, v189
	v_add_f32_e32 v190, 1.0, v190
	v_add_f32_e32 v191, 1.0, v191
	v_rcp_f32_e32 v184, v184
	v_rcp_f32_e32 v185, v185
	v_rcp_f32_e32 v186, v186
	v_rcp_f32_e32 v187, v187
	v_rcp_f32_e32 v188, v188
	v_rcp_f32_e32 v189, v189
	v_rcp_f32_e32 v190, v190
	v_rcp_f32_e32 v191, v191
	v_mul_f32_e32 v100, v100, v184
	v_mul_f32_e32 v101, v101, v185
	v_mul_f32_e32 v102, v102, v186
	v_mul_f32_e32 v103, v103, v187
	v_mul_f32_e32 v96, v96, v188
	v_mul_f32_e32 v97, v97, v189
	v_mul_f32_e32 v98, v98, v190
	v_mul_f32_e32 v99, v99, v191
	v_cvt_pk_bf16_f32 v100, v100, v101
	v_cvt_pk_bf16_f32 v101, v102, v103
	v_cvt_pk_bf16_f32 v102, v96, v97
	v_cvt_pk_bf16_f32 v103, v98, v99
	global_store_dwordx4 v[176:177], v[100:103], off offset:256
	v_lshl_add_u64 v[162:163], v[176:177], 0, s[46:47]
	v_pk_mul_f32 v[92:93], v[92:93], v[144:145] op_sel_hi:[1,0]
	v_pk_mul_f32 v[94:95], v[94:95], v[144:145] op_sel_hi:[1,0]
	v_pk_mul_f32 v[88:89], v[88:89], v[144:145] op_sel_hi:[1,0]
	v_pk_mul_f32 v[90:91], v[90:91], v[144:145] op_sel_hi:[1,0]
	v_mul_f32_e32 v184, 0xbfb8aa3b, v92
	v_mul_f32_e32 v185, 0xbfb8aa3b, v93
	v_mul_f32_e32 v186, 0xbfb8aa3b, v94
	v_mul_f32_e32 v187, 0xbfb8aa3b, v95
	v_mul_f32_e32 v188, 0xbfb8aa3b, v88
	v_mul_f32_e32 v189, 0xbfb8aa3b, v89
	v_mul_f32_e32 v190, 0xbfb8aa3b, v90
	v_mul_f32_e32 v191, 0xbfb8aa3b, v91
	v_exp_f32_e32 v184, v184
	v_exp_f32_e32 v185, v185
	v_exp_f32_e32 v186, v186
; __device__ __forceinline__ float silu_f(float v) { return v * __builtin_amdgcn_rcpf(1.f + __expf(-v)); }
;     __device__ __forceinline__ void operator()(const f32x4 (&acc)[2][2][4][2], const Unit& u, int wr, int wc, int fr, int fq, int ui, PG8_LAS unsigned char* lds) const {
;     ...
;         for (int ai = 0; ai < 2; ++ai) {
;             float rs4[4];
; #pragma unroll
;             for (int m = 0; m < 4; ++m) {
;                 if ((m & 1) == 0) {
;                     if (use_tab) { rs4[m] = tab[ai * HALF + m * 16] * sc; rs4[m + 1] = tab[ai * HALF + (m + 1) * 16] * sc; }
;                     else {
;                         asm volatile("" ::: "memory");
;                         rs4[m] = __builtin_amdgcn_rsqf(ssq_row(ssq, row0 + ai * HALF + m * 16) * (1.0f / 1024.0f) + RMS_EPS) * sc;
;                         rs4[m + 1] = __builtin_amdgcn_rsqf(ssq_row(ssq, row0 + ai * HALF + (m + 1) * 16) * (1.0f / 1024.0f) + RMS_EPS) * sc;
;                     }
;                 }
;                 const int row = row0 + ai * HALF + m * 16;
;                 const float rs = rs4[m];
;                 bf16_t* rowp = O + (size_t)row * ldc + col0;
; #pragma unroll
;                 for (int bj = 0; bj < 2; ++bj) {
;                     f32x4 v[2] = {acc[ai][bj][m][0] * rs, acc[ai][bj][m][1] * rs};
;                     if (ksum) { csum[bj][0] += v[0]; csum[bj][1] += v[1]; }
; #pragma unroll
;                     for (int n = 0; n < 2; ++n) {
;                         f32x4 lbv = (f32x4){0.f, 0.f, 0.f, 0.f};
;                         if (act == 2) lbv = *(const f32x4*)(lb + (col0 - 1024) + bj * HALF + 4 * n);
; #pragma unroll
;                         for (int e = 0; e < 4; ++e) {
;                             float x = v[n][e];
;                             if (act == 1) x = silu_f(x);
;                             else if (act == 2) { const float l = lbv[e]; x = __logf(l + (1.f - l) * __builtin_amdgcn_rcpf(1.f + __expf(-x))); }
;                             else if (act == 3) { x = fmaxf(x, 0.f); x = x * x; }
;                             v[n][e] = x;
;                         }
;                     }
;                     u32x4 w; w.x = cvt_pk_bf16(v[0][0], v[0][1]); w.y = cvt_pk_bf16(v[0][2], v[0][3]); w.z = cvt_pk_bf16(v[1][0], v[1][1]); w.w = cvt_pk_bf16(v[1][2], v[1][3]);
;                     *(u32x4*)(rowp + bj * HALF) = w;
	v_exp_f32_e32 v187, v187
	v_exp_f32_e32 v188, v188
	v_exp_f32_e32 v189, v189
	v_exp_f32_e32 v190, v190
	v_exp_f32_e32 v191, v191
	v_add_f32_e32 v184, 1.0, v184
	v_add_f32_e32 v185, 1.0, v185
	v_add_f32_e32 v186, 1.0, v186
	v_add_f32_e32 v187, 1.0, v187
	v_add_f32_e32 v188, 1.0, v188
	v_add_f32_e32 v189, 1.0, v189
	v_add_f32_e32 v190, 1.0, v190
	v_add_f32_e32 v191, 1.0, v191
	v_rcp_f32_e32 v184, v184
	v_rcp_f32_e32 v185, v185
	v_rcp_f32_e32 v186, v186
	v_rcp_f32_e32 v187, v187
	v_rcp_f32_e32 v188, v188
	v_rcp_f32_e32 v189, v189
	v_rcp_f32_e32 v190, v190
	v_rcp_f32_e32 v191, v191
	v_mul_f32_e32 v92, v92, v184
	v_mul_f32_e32 v93, v93, v185
	v_mul_f32_e32 v94, v94, v186
	v_mul_f32_e32 v95, v95, v187
	v_mul_f32_e32 v88, v88, v188
	v_mul_f32_e32 v89, v89, v189
	v_mul_f32_e32 v90, v90, v190
	v_mul_f32_e32 v91, v91, v191
	v_cvt_pk_bf16_f32 v92, v92, v93
	v_cvt_pk_bf16_f32 v93, v94, v95
	v_cvt_pk_bf16_f32 v94, v88, v89
	v_cvt_pk_bf16_f32 v95, v90, v91
	global_store_dwordx4 v[162:163], v[92:95], off
	v_pk_mul_f32 v[84:85], v[84:85], v[144:145] op_sel_hi:[1,0]
	v_pk_mul_f32 v[86:87], v[86:87], v[144:145] op_sel_hi:[1,0]
	v_pk_mul_f32 v[80:81], v[80:81], v[144:145] op_sel_hi:[1,0]
	v_pk_mul_f32 v[82:83], v[82:83], v[144:145] op_sel_hi:[1,0]
	v_mul_f32_e32 v184, 0xbfb8aa3b, v84
	v_mul_f32_e32 v185, 0xbfb8aa3b, v85
	v_mul_f32_e32 v186, 0xbfb8aa3b, v86
	v_mul_f32_e32 v187, 0xbfb8aa3b, v87
	v_mul_f32_e32 v188, 0xbfb8aa3b, v80
	v_mul_f32_e32 v189, 0xbfb8aa3b, v81
	v_mul_f32_e32 v190, 0xbfb8aa3b, v82
	v_mul_f32_e32 v191, 0xbfb8aa3b, v83
	v_exp_f32_e32 v184, v184
	v_exp_f32_e32 v185, v185
	v_exp_f32_e32 v186, v186
	v_exp_f32_e32 v187, v187
	v_exp_f32_e32 v188, v188
	v_exp_f32_e32 v189, v189
	v_exp_f32_e32 v190, v190
	v_exp_f32_e32 v191, v191
	v_add_f32_e32 v184, 1.0, v184
	v_add_f32_e32 v185, 1.0, v185
	v_add_f32_e32 v186, 1.0, v186
	v_add_f32_e32 v187, 1.0, v187
	v_add_f32_e32 v188, 1.0, v188
	v_add_f32_e32 v189, 1.0, v189
	v_add_f32_e32 v190, 1.0, v190
	v_add_f32_e32 v191, 1.0, v191
	v_rcp_f32_e32 v184, v184
	v_rcp_f32_e32 v185, v185
	v_rcp_f32_e32 v186, v186
	v_rcp_f32_e32 v187, v187
	v_rcp_f32_e32 v188, v188
	v_rcp_f32_e32 v189, v189
	v_rcp_f32_e32 v190, v190
	v_rcp_f32_e32 v191, v191
	v_mul_f32_e32 v84, v84, v184
	v_mul_f32_e32 v85, v85, v185
	v_mul_f32_e32 v86, v86, v186
	v_mul_f32_e32 v87, v87, v187
	v_mul_f32_e32 v80, v80, v188
	v_mul_f32_e32 v81, v81, v189
	v_mul_f32_e32 v82, v82, v190
	v_mul_f32_e32 v83, v83, v191
	v_cvt_pk_bf16_f32 v84, v84, v85
	v_cvt_pk_bf16_f32 v85, v86, v87
	v_cvt_pk_bf16_f32 v86, v80, v81
	v_cvt_pk_bf16_f32 v87, v82, v83
	global_store_dwordx4 v[162:163], v[84:87], off offset:256
	v_lshl_add_u64 v[176:177], v[162:163], 0, s[46:47]
	v_pk_mul_f32 v[76:77], v[76:77], v[146:147] op_sel_hi:[1,0]
	v_pk_mul_f32 v[78:79], v[78:79], v[146:147] op_sel_hi:[1,0]
	v_pk_mul_f32 v[72:73], v[72:73], v[146:147] op_sel_hi:[1,0]
	v_pk_mul_f32 v[74:75], v[74:75], v[146:147] op_sel_hi:[1,0]
	v_mul_f32_e32 v184, 0xbfb8aa3b, v76
	v_mul_f32_e32 v185, 0xbfb8aa3b, v77
	v_mul_f32_e32 v186, 0xbfb8aa3b, v78
	v_mul_f32_e32 v187, 0xbfb8aa3b, v79
	v_mul_f32_e32 v188, 0xbfb8aa3b, v72
	v_mul_f32_e32 v189, 0xbfb8aa3b, v73
	v_mul_f32_e32 v190, 0xbfb8aa3b, v74
	v_mul_f32_e32 v191, 0xbfb8aa3b, v75
	v_exp_f32_e32 v184, v184
	v_exp_f32_e32 v185, v185
	v_exp_f32_e32 v186, v186
	v_exp_f32_e32 v187, v187
	v_exp_f32_e32 v188, v188
	v_exp_f32_e32 v189, v189
	v_exp_f32_e32 v190, v190
	v_exp_f32_e32 v191, v191
	v_add_f32_e32 v184, 1.0, v184
	v_add_f32_e32 v185, 1.0, v185
	v_add_f32_e32 v186, 1.0, v186
	v_add_f32_e32 v187, 1.0, v187
	v_add_f32_e32 v188, 1.0, v188
	v_add_f32_e32 v189, 1.0, v189
	v_add_f32_e32 v190, 1.0, v190
	v_add_f32_e32 v191, 1.0, v191
	v_rcp_f32_e32 v184, v184
	v_rcp_f32_e32 v185, v185
	v_rcp_f32_e32 v186, v186
	v_rcp_f32_e32 v187, v187
	v_rcp_f32_e32 v188, v188
	v_rcp_f32_e32 v189, v189
	v_rcp_f32_e32 v190, v190
	v_rcp_f32_e32 v191, v191
	v_mul_f32_e32 v76, v76, v184
	v_mul_f32_e32 v77, v77, v185
	v_mul_f32_e32 v78, v78, v186
	v_mul_f32_e32 v79, v79, v187
	v_mul_f32_e32 v72, v72, v188
	v_mul_f32_e32 v73, v73, v189
	v_mul_f32_e32 v74, v74, v190
	v_mul_f32_e32 v75, v75, v191
	v_cvt_pk_bf16_f32 v76, v76, v77
	v_cvt_pk_bf16_f32 v77, v78, v79
	v_cvt_pk_bf16_f32 v78, v72, v73
	v_cvt_pk_bf16_f32 v79, v74, v75
	global_store_dwordx4 v[176:177], v[76:79], off
	v_pk_mul_f32 v[68:69], v[68:69], v[146:147] op_sel_hi:[1,0]
	v_pk_mul_f32 v[70:71], v[70:71], v[146:147] op_sel_hi:[1,0]
	v_pk_mul_f32 v[64:65], v[64:65], v[146:147] op_sel_hi:[1,0]
	v_pk_mul_f32 v[66:67], v[66:67], v[146:147] op_sel_hi:[1,0]
	v_mul_f32_e32 v184, 0xbfb8aa3b, v68
	v_mul_f32_e32 v185, 0xbfb8aa3b, v69
	v_mul_f32_e32 v186, 0xbfb8aa3b, v70
	v_mul_f32_e32 v187, 0xbfb8aa3b, v71
	v_mul_f32_e32 v188, 0xbfb8aa3b, v64
	v_mul_f32_e32 v189, 0xbfb8aa3b, v65
	v_mul_f32_e32 v190, 0xbfb8aa3b, v66
	v_mul_f32_e32 v191, 0xbfb8aa3b, v67
	v_exp_f32_e32 v184, v184
	v_exp_f32_e32 v185, v185
	v_exp_f32_e32 v186, v186
	v_exp_f32_e32 v187, v187
	v_exp_f32_e32 v188, v188
	v_exp_f32_e32 v189, v189
	v_exp_f32_e32 v190, v190
	v_exp_f32_e32 v191, v191
	v_add_f32_e32 v184, 1.0, v184
	v_add_f32_e32 v185, 1.0, v185
	v_add_f32_e32 v186, 1.0, v186
	v_add_f32_e32 v187, 1.0, v187
	v_add_f32_e32 v188, 1.0, v188
	v_add_f32_e32 v189, 1.0, v189
	v_add_f32_e32 v190, 1.0, v190
	v_add_f32_e32 v191, 1.0, v191
	v_rcp_f32_e32 v184, v184
	v_rcp_f32_e32 v185, v185
	v_rcp_f32_e32 v186, v186
	v_rcp_f32_e32 v187, v187
	v_rcp_f32_e32 v188, v188
	v_rcp_f32_e32 v189, v189
	v_rcp_f32_e32 v190, v190
	v_rcp_f32_e32 v191, v191
	v_mul_f32_e32 v68, v68, v184
	v_mul_f32_e32 v69, v69, v185
	v_mul_f32_e32 v70, v70, v186
	v_mul_f32_e32 v71, v71, v187
; __device__ __forceinline__ float silu_f(float v) { return v * __builtin_amdgcn_rcpf(1.f + __expf(-v)); }
;     __device__ __forceinline__ void operator()(const f32x4 (&acc)[2][2][4][2], const Unit& u, int wr, int wc, int fr, int fq, int ui, PG8_LAS unsigned char* lds) const {
;     ...
;         for (int ai = 0; ai < 2; ++ai) {
;             float rs4[4];
; #pragma unroll
;             for (int m = 0; m < 4; ++m) {
;                 if ((m & 1) == 0) {
;                     if (use_tab) { rs4[m] = tab[ai * HALF + m * 16] * sc; rs4[m + 1] = tab[ai * HALF + (m + 1) * 16] * sc; }
;                     else {
;                         asm volatile("" ::: "memory");
;                         rs4[m] = __builtin_amdgcn_rsqf(ssq_row(ssq, row0 + ai * HALF + m * 16) * (1.0f / 1024.0f) + RMS_EPS) * sc;
;                         rs4[m + 1] = __builtin_amdgcn_rsqf(ssq_row(ssq, row0 + ai * HALF + (m + 1) * 16) * (1.0f / 1024.0f) + RMS_EPS) * sc;
;                     }
;                 }
;                 const int row = row0 + ai * HALF + m * 16;
;                 const float rs = rs4[m];
;                 bf16_t* rowp = O + (size_t)row * ldc + col0;
; #pragma unroll
;                 for (int bj = 0; bj < 2; ++bj) {
;                     f32x4 v[2] = {acc[ai][bj][m][0] * rs, acc[ai][bj][m][1] * rs};
;                     if (ksum) { csum[bj][0] += v[0]; csum[bj][1] += v[1]; }
; #pragma unroll
;                     for (int n = 0; n < 2; ++n) {
;                         f32x4 lbv = (f32x4){0.f, 0.f, 0.f, 0.f};
;                         if (act == 2) lbv = *(const f32x4*)(lb + (col0 - 1024) + bj * HALF + 4 * n);
; #pragma unroll
;                         for (int e = 0; e < 4; ++e) {
;                             float x = v[n][e];
;                             if (act == 1) x = silu_f(x);
;                             else if (act == 2) { const float l = lbv[e]; x = __logf(l + (1.f - l) * __builtin_amdgcn_rcpf(1.f + __expf(-x))); }
;                             else if (act == 3) { x = fmaxf(x, 0.f); x = x * x; }
;                             v[n][e] = x;
;                         }
;                     }
;                     u32x4 w; w.x = cvt_pk_bf16(v[0][0], v[0][1]); w.y = cvt_pk_bf16(v[0][2], v[0][3]); w.z = cvt_pk_bf16(v[1][0], v[1][1]); w.w = cvt_pk_bf16(v[1][2], v[1][3]);
;                     *(u32x4*)(rowp + bj * HALF) = w;
	v_mul_f32_e32 v64, v64, v188
	v_mul_f32_e32 v65, v65, v189
	v_mul_f32_e32 v66, v66, v190
	v_mul_f32_e32 v67, v67, v191
	v_cvt_pk_bf16_f32 v68, v68, v69
	v_cvt_pk_bf16_f32 v69, v70, v71
	v_cvt_pk_bf16_f32 v70, v64, v65
	v_cvt_pk_bf16_f32 v71, v66, v67
	global_store_dwordx4 v[176:177], v[68:71], off offset:256
	v_lshl_add_u64 v[162:163], v[178:179], 0, 0
	v_pk_mul_f32 v[60:61], v[60:61], v[148:149] op_sel_hi:[1,0]
	v_pk_mul_f32 v[62:63], v[62:63], v[148:149] op_sel_hi:[1,0]
	v_pk_mul_f32 v[56:57], v[56:57], v[148:149] op_sel_hi:[1,0]
	v_pk_mul_f32 v[58:59], v[58:59], v[148:149] op_sel_hi:[1,0]
	v_mul_f32_e32 v184, 0xbfb8aa3b, v60
	v_mul_f32_e32 v185, 0xbfb8aa3b, v61
	v_mul_f32_e32 v186, 0xbfb8aa3b, v62
	v_mul_f32_e32 v187, 0xbfb8aa3b, v63
	v_mul_f32_e32 v188, 0xbfb8aa3b, v56
	v_mul_f32_e32 v189, 0xbfb8aa3b, v57
	v_mul_f32_e32 v190, 0xbfb8aa3b, v58
	v_mul_f32_e32 v191, 0xbfb8aa3b, v59
	v_exp_f32_e32 v184, v184
	v_exp_f32_e32 v185, v185
	v_exp_f32_e32 v186, v186
	v_exp_f32_e32 v187, v187
	v_exp_f32_e32 v188, v188
	v_exp_f32_e32 v189, v189
	v_exp_f32_e32 v190, v190
	v_exp_f32_e32 v191, v191
	v_add_f32_e32 v184, 1.0, v184
	v_add_f32_e32 v185, 1.0, v185
	v_add_f32_e32 v186, 1.0, v186
	v_add_f32_e32 v187, 1.0, v187
	v_add_f32_e32 v188, 1.0, v188
	v_add_f32_e32 v189, 1.0, v189
	v_add_f32_e32 v190, 1.0, v190
	v_add_f32_e32 v191, 1.0, v191
	v_rcp_f32_e32 v184, v184
	v_rcp_f32_e32 v185, v185
	v_rcp_f32_e32 v186, v186
	v_rcp_f32_e32 v187, v187
	v_rcp_f32_e32 v188, v188
	v_rcp_f32_e32 v189, v189
	v_rcp_f32_e32 v190, v190
	v_rcp_f32_e32 v191, v191
	v_mul_f32_e32 v60, v60, v184
	v_mul_f32_e32 v61, v61, v185
	v_mul_f32_e32 v62, v62, v186
	v_mul_f32_e32 v63, v63, v187
	v_mul_f32_e32 v56, v56, v188
	v_mul_f32_e32 v57, v57, v189
	v_mul_f32_e32 v58, v58, v190
	v_mul_f32_e32 v59, v59, v191
	v_cvt_pk_bf16_f32 v60, v60, v61
	v_cvt_pk_bf16_f32 v61, v62, v63
	v_cvt_pk_bf16_f32 v62, v56, v57
	v_cvt_pk_bf16_f32 v63, v58, v59
	global_store_dwordx4 v[162:163], v[60:63], off
	v_pk_mul_f32 v[52:53], v[52:53], v[148:149] op_sel_hi:[1,0]
	v_pk_mul_f32 v[54:55], v[54:55], v[148:149] op_sel_hi:[1,0]
	v_pk_mul_f32 v[48:49], v[48:49], v[148:149] op_sel_hi:[1,0]
	v_pk_mul_f32 v[50:51], v[50:51], v[148:149] op_sel_hi:[1,0]
	v_mul_f32_e32 v184, 0xbfb8aa3b, v52
	v_mul_f32_e32 v185, 0xbfb8aa3b, v53
	v_mul_f32_e32 v186, 0xbfb8aa3b, v54
	v_mul_f32_e32 v187, 0xbfb8aa3b, v55
	v_mul_f32_e32 v188, 0xbfb8aa3b, v48
	v_mul_f32_e32 v189, 0xbfb8aa3b, v49
	v_mul_f32_e32 v190, 0xbfb8aa3b, v50
	v_mul_f32_e32 v191, 0xbfb8aa3b, v51
	v_exp_f32_e32 v184, v184
	v_exp_f32_e32 v185, v185
	v_exp_f32_e32 v186, v186
	v_exp_f32_e32 v187, v187
	v_exp_f32_e32 v188, v188
	v_exp_f32_e32 v189, v189
	v_exp_f32_e32 v190, v190
	v_exp_f32_e32 v191, v191
	v_add_f32_e32 v184, 1.0, v184
	v_add_f32_e32 v185, 1.0, v185
	v_add_f32_e32 v186, 1.0, v186
	v_add_f32_e32 v187, 1.0, v187
	v_add_f32_e32 v188, 1.0, v188
	v_add_f32_e32 v189, 1.0, v189
	v_add_f32_e32 v190, 1.0, v190
	v_add_f32_e32 v191, 1.0, v191
	v_rcp_f32_e32 v184, v184
	v_rcp_f32_e32 v185, v185
	v_rcp_f32_e32 v186, v186
	v_rcp_f32_e32 v187, v187
	v_rcp_f32_e32 v188, v188
	v_rcp_f32_e32 v189, v189
	v_rcp_f32_e32 v190, v190
	v_rcp_f32_e32 v191, v191
	v_mul_f32_e32 v52, v52, v184
	v_mul_f32_e32 v53, v53, v185
	v_mul_f32_e32 v54, v54, v186
	v_mul_f32_e32 v55, v55, v187
	v_mul_f32_e32 v48, v48, v188
	v_mul_f32_e32 v49, v49, v189
	v_mul_f32_e32 v50, v50, v190
	v_mul_f32_e32 v51, v51, v191
	v_cvt_pk_bf16_f32 v52, v52, v53
	v_cvt_pk_bf16_f32 v53, v54, v55
	v_cvt_pk_bf16_f32 v54, v48, v49
	v_cvt_pk_bf16_f32 v55, v50, v51
	global_store_dwordx4 v[162:163], v[52:55], off offset:256
	v_lshl_add_u64 v[176:177], v[162:163], 0, s[46:47]
	v_pk_mul_f32 v[44:45], v[44:45], v[156:157] op_sel_hi:[1,0]
	v_pk_mul_f32 v[46:47], v[46:47], v[156:157] op_sel_hi:[1,0]
	v_pk_mul_f32 v[40:41], v[40:41], v[156:157] op_sel_hi:[1,0]
	v_pk_mul_f32 v[42:43], v[42:43], v[156:157] op_sel_hi:[1,0]
	v_mul_f32_e32 v184, 0xbfb8aa3b, v44
	v_mul_f32_e32 v185, 0xbfb8aa3b, v45
	v_mul_f32_e32 v186, 0xbfb8aa3b, v46
	v_mul_f32_e32 v187, 0xbfb8aa3b, v47
	v_mul_f32_e32 v188, 0xbfb8aa3b, v40
	v_mul_f32_e32 v189, 0xbfb8aa3b, v41
	v_mul_f32_e32 v190, 0xbfb8aa3b, v42
	v_mul_f32_e32 v191, 0xbfb8aa3b, v43
	v_exp_f32_e32 v184, v184
	v_exp_f32_e32 v185, v185
	v_exp_f32_e32 v186, v186
	v_exp_f32_e32 v187, v187
	v_exp_f32_e32 v188, v188
	v_exp_f32_e32 v189, v189
	v_exp_f32_e32 v190, v190
	v_exp_f32_e32 v191, v191
	v_add_f32_e32 v184, 1.0, v184
	v_add_f32_e32 v185, 1.0, v185
	v_add_f32_e32 v186, 1.0, v186
	v_add_f32_e32 v187, 1.0, v187
	v_add_f32_e32 v188, 1.0, v188
	v_add_f32_e32 v189, 1.0, v189
	v_add_f32_e32 v190, 1.0, v190
	v_add_f32_e32 v191, 1.0, v191
	v_rcp_f32_e32 v184, v184
	v_rcp_f32_e32 v185, v185
	v_rcp_f32_e32 v186, v186
	v_rcp_f32_e32 v187, v187
	v_rcp_f32_e32 v188, v188
	v_rcp_f32_e32 v189, v189
	v_rcp_f32_e32 v190, v190
	v_rcp_f32_e32 v191, v191
	v_mul_f32_e32 v44, v44, v184
	v_mul_f32_e32 v45, v45, v185
	v_mul_f32_e32 v46, v46, v186
	v_mul_f32_e32 v47, v47, v187
	v_mul_f32_e32 v40, v40, v188
	v_mul_f32_e32 v41, v41, v189
	v_mul_f32_e32 v42, v42, v190
	v_mul_f32_e32 v43, v43, v191
	v_cvt_pk_bf16_f32 v44, v44, v45
	v_cvt_pk_bf16_f32 v45, v46, v47
	v_cvt_pk_bf16_f32 v46, v40, v41
	v_cvt_pk_bf16_f32 v47, v42, v43
	global_store_dwordx4 v[176:177], v[44:47], off
	v_pk_mul_f32 v[36:37], v[36:37], v[156:157] op_sel_hi:[1,0]
	v_pk_mul_f32 v[38:39], v[38:39], v[156:157] op_sel_hi:[1,0]
	v_pk_mul_f32 v[32:33], v[32:33], v[156:157] op_sel_hi:[1,0]
	v_pk_mul_f32 v[34:35], v[34:35], v[156:157] op_sel_hi:[1,0]
	v_mul_f32_e32 v184, 0xbfb8aa3b, v36
	v_mul_f32_e32 v185, 0xbfb8aa3b, v37
	v_mul_f32_e32 v186, 0xbfb8aa3b, v38
; __device__ __forceinline__ float silu_f(float v) { return v * __builtin_amdgcn_rcpf(1.f + __expf(-v)); }
;     __device__ __forceinline__ void operator()(const f32x4 (&acc)[2][2][4][2], const Unit& u, int wr, int wc, int fr, int fq, int ui, PG8_LAS unsigned char* lds) const {
;     ...
;         for (int ai = 0; ai < 2; ++ai) {
;             float rs4[4];
; #pragma unroll
;             for (int m = 0; m < 4; ++m) {
;                 if ((m & 1) == 0) {
;                     if (use_tab) { rs4[m] = tab[ai * HALF + m * 16] * sc; rs4[m + 1] = tab[ai * HALF + (m + 1) * 16] * sc; }
;                     else {
;                         asm volatile("" ::: "memory");
;                         rs4[m] = __builtin_amdgcn_rsqf(ssq_row(ssq, row0 + ai * HALF + m * 16) * (1.0f / 1024.0f) + RMS_EPS) * sc;
;                         rs4[m + 1] = __builtin_amdgcn_rsqf(ssq_row(ssq, row0 + ai * HALF + (m + 1) * 16) * (1.0f / 1024.0f) + RMS_EPS) * sc;
;                     }
;                 }
;                 const int row = row0 + ai * HALF + m * 16;
;                 const float rs = rs4[m];
;                 bf16_t* rowp = O + (size_t)row * ldc + col0;
; #pragma unroll
;                 for (int bj = 0; bj < 2; ++bj) {
;                     f32x4 v[2] = {acc[ai][bj][m][0] * rs, acc[ai][bj][m][1] * rs};
;                     if (ksum) { csum[bj][0] += v[0]; csum[bj][1] += v[1]; }
; #pragma unroll
;                     for (int n = 0; n < 2; ++n) {
;                         f32x4 lbv = (f32x4){0.f, 0.f, 0.f, 0.f};
;                         if (act == 2) lbv = *(const f32x4*)(lb + (col0 - 1024) + bj * HALF + 4 * n);
; #pragma unroll
;                         for (int e = 0; e < 4; ++e) {
;                             float x = v[n][e];
;                             if (act == 1) x = silu_f(x);
;                             else if (act == 2) { const float l = lbv[e]; x = __logf(l + (1.f - l) * __builtin_amdgcn_rcpf(1.f + __expf(-x))); }
;                             else if (act == 3) { x = fmaxf(x, 0.f); x = x * x; }
;                             v[n][e] = x;
;                         }
;                     }
;                     u32x4 w; w.x = cvt_pk_bf16(v[0][0], v[0][1]); w.y = cvt_pk_bf16(v[0][2], v[0][3]); w.z = cvt_pk_bf16(v[1][0], v[1][1]); w.w = cvt_pk_bf16(v[1][2], v[1][3]);
;                     *(u32x4*)(rowp + bj * HALF) = w;
	v_mul_f32_e32 v187, 0xbfb8aa3b, v39
	v_mul_f32_e32 v188, 0xbfb8aa3b, v32
	v_mul_f32_e32 v189, 0xbfb8aa3b, v33
	v_mul_f32_e32 v190, 0xbfb8aa3b, v34
	v_mul_f32_e32 v191, 0xbfb8aa3b, v35
	v_exp_f32_e32 v184, v184
	v_exp_f32_e32 v185, v185
	v_exp_f32_e32 v186, v186
	v_exp_f32_e32 v187, v187
	v_exp_f32_e32 v188, v188
	v_exp_f32_e32 v189, v189
	v_exp_f32_e32 v190, v190
	v_exp_f32_e32 v191, v191
	v_add_f32_e32 v184, 1.0, v184
	v_add_f32_e32 v185, 1.0, v185
	v_add_f32_e32 v186, 1.0, v186
	v_add_f32_e32 v187, 1.0, v187
	v_add_f32_e32 v188, 1.0, v188
	v_add_f32_e32 v189, 1.0, v189
	v_add_f32_e32 v190, 1.0, v190
	v_add_f32_e32 v191, 1.0, v191
	v_rcp_f32_e32 v184, v184
	v_rcp_f32_e32 v185, v185
	v_rcp_f32_e32 v186, v186
	v_rcp_f32_e32 v187, v187
	v_rcp_f32_e32 v188, v188
	v_rcp_f32_e32 v189, v189
	v_rcp_f32_e32 v190, v190
	v_rcp_f32_e32 v191, v191
	v_mul_f32_e32 v36, v36, v184
	v_mul_f32_e32 v37, v37, v185
	v_mul_f32_e32 v38, v38, v186
	v_mul_f32_e32 v39, v39, v187
	v_mul_f32_e32 v32, v32, v188
	v_mul_f32_e32 v33, v33, v189
	v_mul_f32_e32 v34, v34, v190
	v_mul_f32_e32 v35, v35, v191
	v_cvt_pk_bf16_f32 v36, v36, v37
	v_cvt_pk_bf16_f32 v37, v38, v39
	v_cvt_pk_bf16_f32 v38, v32, v33
	v_cvt_pk_bf16_f32 v39, v34, v35
	global_store_dwordx4 v[176:177], v[36:39], off offset:256
	v_lshl_add_u64 v[162:163], v[176:177], 0, s[46:47]
	v_pk_mul_f32 v[28:29], v[28:29], v[158:159] op_sel_hi:[1,0]
	v_pk_mul_f32 v[30:31], v[30:31], v[158:159] op_sel_hi:[1,0]
	v_pk_mul_f32 v[24:25], v[24:25], v[158:159] op_sel_hi:[1,0]
	v_pk_mul_f32 v[26:27], v[26:27], v[158:159] op_sel_hi:[1,0]
	v_mul_f32_e32 v184, 0xbfb8aa3b, v28
	v_mul_f32_e32 v185, 0xbfb8aa3b, v29
	v_mul_f32_e32 v186, 0xbfb8aa3b, v30
	v_mul_f32_e32 v187, 0xbfb8aa3b, v31
	v_mul_f32_e32 v188, 0xbfb8aa3b, v24
	v_mul_f32_e32 v189, 0xbfb8aa3b, v25
	v_mul_f32_e32 v190, 0xbfb8aa3b, v26
	v_mul_f32_e32 v191, 0xbfb8aa3b, v27
	v_exp_f32_e32 v184, v184
	v_exp_f32_e32 v185, v185
	v_exp_f32_e32 v186, v186
	v_exp_f32_e32 v187, v187
	v_exp_f32_e32 v188, v188
	v_exp_f32_e32 v189, v189
	v_exp_f32_e32 v190, v190
	v_exp_f32_e32 v191, v191
	v_add_f32_e32 v184, 1.0, v184
	v_add_f32_e32 v185, 1.0, v185
	v_add_f32_e32 v186, 1.0, v186
	v_add_f32_e32 v187, 1.0, v187
	v_add_f32_e32 v188, 1.0, v188
	v_add_f32_e32 v189, 1.0, v189
	v_add_f32_e32 v190, 1.0, v190
	v_add_f32_e32 v191, 1.0, v191
	v_rcp_f32_e32 v184, v184
	v_rcp_f32_e32 v185, v185
	v_rcp_f32_e32 v186, v186
	v_rcp_f32_e32 v187, v187
	v_rcp_f32_e32 v188, v188
	v_rcp_f32_e32 v189, v189
	v_rcp_f32_e32 v190, v190
	v_rcp_f32_e32 v191, v191
	v_mul_f32_e32 v28, v28, v184
	v_mul_f32_e32 v29, v29, v185
	v_mul_f32_e32 v30, v30, v186
	v_mul_f32_e32 v31, v31, v187
	v_mul_f32_e32 v24, v24, v188
	v_mul_f32_e32 v25, v25, v189
	v_mul_f32_e32 v26, v26, v190
	v_mul_f32_e32 v27, v27, v191
	v_cvt_pk_bf16_f32 v28, v28, v29
	v_cvt_pk_bf16_f32 v29, v30, v31
	v_cvt_pk_bf16_f32 v30, v24, v25
	v_cvt_pk_bf16_f32 v31, v26, v27
	global_store_dwordx4 v[162:163], v[28:31], off
	v_pk_mul_f32 v[20:21], v[20:21], v[158:159] op_sel_hi:[1,0]
	v_pk_mul_f32 v[22:23], v[22:23], v[158:159] op_sel_hi:[1,0]
	v_pk_mul_f32 v[16:17], v[16:17], v[158:159] op_sel_hi:[1,0]
	v_pk_mul_f32 v[18:19], v[18:19], v[158:159] op_sel_hi:[1,0]
	v_mul_f32_e32 v184, 0xbfb8aa3b, v20
	v_mul_f32_e32 v185, 0xbfb8aa3b, v21
	v_mul_f32_e32 v186, 0xbfb8aa3b, v22
	v_mul_f32_e32 v187, 0xbfb8aa3b, v23
	v_mul_f32_e32 v188, 0xbfb8aa3b, v16
	v_mul_f32_e32 v189, 0xbfb8aa3b, v17
	v_mul_f32_e32 v190, 0xbfb8aa3b, v18
	v_mul_f32_e32 v191, 0xbfb8aa3b, v19
	v_exp_f32_e32 v184, v184
	v_exp_f32_e32 v185, v185
	v_exp_f32_e32 v186, v186
	v_exp_f32_e32 v187, v187
	v_exp_f32_e32 v188, v188
	v_exp_f32_e32 v189, v189
	v_exp_f32_e32 v190, v190
	v_exp_f32_e32 v191, v191
	v_add_f32_e32 v184, 1.0, v184
	v_add_f32_e32 v185, 1.0, v185
	v_add_f32_e32 v186, 1.0, v186
	v_add_f32_e32 v187, 1.0, v187
	v_add_f32_e32 v188, 1.0, v188
	v_add_f32_e32 v189, 1.0, v189
	v_add_f32_e32 v190, 1.0, v190
	v_add_f32_e32 v191, 1.0, v191
	v_rcp_f32_e32 v184, v184
	v_rcp_f32_e32 v185, v185
	v_rcp_f32_e32 v186, v186
	v_rcp_f32_e32 v187, v187
	v_rcp_f32_e32 v188, v188
	v_rcp_f32_e32 v189, v189
	v_rcp_f32_e32 v190, v190
	v_rcp_f32_e32 v191, v191
	v_mul_f32_e32 v20, v20, v184
	v_mul_f32_e32 v21, v21, v185
	v_mul_f32_e32 v22, v22, v186
	v_mul_f32_e32 v23, v23, v187
	v_mul_f32_e32 v16, v16, v188
	v_mul_f32_e32 v17, v17, v189
	v_mul_f32_e32 v18, v18, v190
	v_mul_f32_e32 v19, v19, v191
	v_cvt_pk_bf16_f32 v20, v20, v21
	v_cvt_pk_bf16_f32 v21, v22, v23
	v_cvt_pk_bf16_f32 v22, v16, v17
	v_cvt_pk_bf16_f32 v23, v18, v19
	global_store_dwordx4 v[162:163], v[20:23], off offset:256
	v_lshl_add_u64 v[176:177], v[162:163], 0, s[46:47]
	v_pk_mul_f32 v[12:13], v[12:13], v[160:161] op_sel_hi:[1,0]
	v_pk_mul_f32 v[14:15], v[14:15], v[160:161] op_sel_hi:[1,0]
	v_pk_mul_f32 v[8:9], v[8:9], v[160:161] op_sel_hi:[1,0]
	v_pk_mul_f32 v[10:11], v[10:11], v[160:161] op_sel_hi:[1,0]
	v_mul_f32_e32 v184, 0xbfb8aa3b, v12
	v_mul_f32_e32 v185, 0xbfb8aa3b, v13
	v_mul_f32_e32 v186, 0xbfb8aa3b, v14
	v_mul_f32_e32 v187, 0xbfb8aa3b, v15
	v_mul_f32_e32 v188, 0xbfb8aa3b, v8
	v_mul_f32_e32 v189, 0xbfb8aa3b, v9
	v_mul_f32_e32 v190, 0xbfb8aa3b, v10
	v_mul_f32_e32 v191, 0xbfb8aa3b, v11
	v_exp_f32_e32 v184, v184
	v_exp_f32_e32 v185, v185
	v_exp_f32_e32 v186, v186
	v_exp_f32_e32 v187, v187
	v_exp_f32_e32 v188, v188
	v_exp_f32_e32 v189, v189
	v_exp_f32_e32 v190, v190
	v_exp_f32_e32 v191, v191
	v_add_f32_e32 v184, 1.0, v184
	v_add_f32_e32 v185, 1.0, v185
	v_add_f32_e32 v186, 1.0, v186
	v_add_f32_e32 v187, 1.0, v187
	v_add_f32_e32 v188, 1.0, v188
	v_add_f32_e32 v189, 1.0, v189
	v_add_f32_e32 v190, 1.0, v190
	v_add_f32_e32 v191, 1.0, v191
; __device__ __forceinline__ unsigned cvt_pk_bf16(float lo, float hi) { unsigned r; asm volatile("v_cvt_pk_bf16_f32 %0, %1, %2" : "=v"(r) : "v"(lo), "v"(hi)); return r; }
; __device__ __forceinline__ float silu_f(float v) { return v * __builtin_amdgcn_rcpf(1.f + __expf(-v)); }
;     __device__ __forceinline__ void operator()(const f32x4 (&acc)[2][2][4][2], const Unit& u, int wr, int wc, int fr, int fq, int ui, PG8_LAS unsigned char* lds) const {
;     ...
;                     if (use_tab) { rs4[m] = tab[ai * HALF + m * 16] * sc; rs4[m + 1] = tab[ai * HALF + (m + 1) * 16] * sc; }
;                     else {
;                         asm volatile("" ::: "memory");
;                         rs4[m] = __builtin_amdgcn_rsqf(ssq_row(ssq, row0 + ai * HALF + m * 16) * (1.0f / 1024.0f) + RMS_EPS) * sc;
;                         rs4[m + 1] = __builtin_amdgcn_rsqf(ssq_row(ssq, row0 + ai * HALF + (m + 1) * 16) * (1.0f / 1024.0f) + RMS_EPS) * sc;
;                     }
;                 }
;                 const int row = row0 + ai * HALF + m * 16;
;                 const float rs = rs4[m];
;                 bf16_t* rowp = O + (size_t)row * ldc + col0;
; #pragma unroll
;                 for (int bj = 0; bj < 2; ++bj) {
;                     f32x4 v[2] = {acc[ai][bj][m][0] * rs, acc[ai][bj][m][1] * rs};
;                     if (ksum) { csum[bj][0] += v[0]; csum[bj][1] += v[1]; }
; #pragma unroll
;                     for (int n = 0; n < 2; ++n) {
;                         f32x4 lbv = (f32x4){0.f, 0.f, 0.f, 0.f};
;                         if (act == 2) lbv = *(const f32x4*)(lb + (col0 - 1024) + bj * HALF + 4 * n);
; #pragma unroll
;                         for (int e = 0; e < 4; ++e) {
;                             float x = v[n][e];
;                             if (act == 1) x = silu_f(x);
;                             else if (act == 2) { const float l = lbv[e]; x = __logf(l + (1.f - l) * __builtin_amdgcn_rcpf(1.f + __expf(-x))); }
;                             else if (act == 3) { x = fmaxf(x, 0.f); x = x * x; }
;                             v[n][e] = x;
;                         }
;                     }
;                     u32x4 w; w.x = cvt_pk_bf16(v[0][0], v[0][1]); w.y = cvt_pk_bf16(v[0][2], v[0][3]); w.z = cvt_pk_bf16(v[1][0], v[1][1]); w.w = cvt_pk_bf16(v[1][2], v[1][3]);
;                     *(u32x4*)(rowp + bj * HALF) = w;
	v_rcp_f32_e32 v184, v184
	v_rcp_f32_e32 v185, v185
	v_rcp_f32_e32 v186, v186
	v_rcp_f32_e32 v187, v187
	v_rcp_f32_e32 v188, v188
	v_rcp_f32_e32 v189, v189
	v_rcp_f32_e32 v190, v190
	v_rcp_f32_e32 v191, v191
	v_mul_f32_e32 v12, v12, v184
	v_mul_f32_e32 v13, v13, v185
	v_mul_f32_e32 v14, v14, v186
	v_mul_f32_e32 v15, v15, v187
	v_mul_f32_e32 v8, v8, v188
	v_mul_f32_e32 v9, v9, v189
	v_mul_f32_e32 v10, v10, v190
	v_mul_f32_e32 v11, v11, v191
	v_cvt_pk_bf16_f32 v12, v12, v13
	v_cvt_pk_bf16_f32 v13, v14, v15
	v_cvt_pk_bf16_f32 v14, v8, v9
	v_cvt_pk_bf16_f32 v15, v10, v11
	global_store_dwordx4 v[176:177], v[12:15], off
	v_pk_mul_f32 v[4:5], v[4:5], v[160:161] op_sel_hi:[1,0]
	v_pk_mul_f32 v[6:7], v[6:7], v[160:161] op_sel_hi:[1,0]
	v_pk_mul_f32 v[0:1], v[0:1], v[160:161] op_sel_hi:[1,0]
	v_pk_mul_f32 v[2:3], v[2:3], v[160:161] op_sel_hi:[1,0]
	v_mul_f32_e32 v184, 0xbfb8aa3b, v4
	v_mul_f32_e32 v185, 0xbfb8aa3b, v5
	v_mul_f32_e32 v186, 0xbfb8aa3b, v6
	v_mul_f32_e32 v187, 0xbfb8aa3b, v7
	v_mul_f32_e32 v188, 0xbfb8aa3b, v0
	v_mul_f32_e32 v189, 0xbfb8aa3b, v1
	v_mul_f32_e32 v190, 0xbfb8aa3b, v2
	v_mul_f32_e32 v191, 0xbfb8aa3b, v3
	v_exp_f32_e32 v184, v184
	v_exp_f32_e32 v185, v185
	v_exp_f32_e32 v186, v186
	v_exp_f32_e32 v187, v187
	v_exp_f32_e32 v188, v188
	v_exp_f32_e32 v189, v189
	v_exp_f32_e32 v190, v190
	v_exp_f32_e32 v191, v191
	v_add_f32_e32 v184, 1.0, v184
	v_add_f32_e32 v185, 1.0, v185
	v_add_f32_e32 v186, 1.0, v186
	v_add_f32_e32 v187, 1.0, v187
	v_add_f32_e32 v188, 1.0, v188
	v_add_f32_e32 v189, 1.0, v189
	v_add_f32_e32 v190, 1.0, v190
	v_add_f32_e32 v191, 1.0, v191
	v_rcp_f32_e32 v184, v184
	v_rcp_f32_e32 v185, v185
	v_rcp_f32_e32 v186, v186
	v_rcp_f32_e32 v187, v187
	v_rcp_f32_e32 v188, v188
	v_rcp_f32_e32 v189, v189
	v_rcp_f32_e32 v190, v190
	v_rcp_f32_e32 v191, v191
	v_mul_f32_e32 v4, v4, v184
	v_mul_f32_e32 v5, v5, v185
	v_mul_f32_e32 v6, v6, v186
	v_mul_f32_e32 v7, v7, v187
	v_mul_f32_e32 v0, v0, v188
	v_mul_f32_e32 v1, v1, v189
	v_mul_f32_e32 v2, v2, v190
	v_mul_f32_e32 v3, v3, v191
	v_cvt_pk_bf16_f32 v4, v4, v5
	v_cvt_pk_bf16_f32 v5, v6, v7
	v_cvt_pk_bf16_f32 v6, v0, v1
	v_cvt_pk_bf16_f32 v7, v2, v3
	global_store_dwordx4 v[176:177], v[4:7], off offset:256
	s_branch .LBB0_1108
.Lepi_logf:
	v_lshl_add_u32 v150, s78, 8, v164
	s_lshl_b32 s1, s1, 10
	v_add_u32_e32 v170, s1, v166
	ds_read_b32 v128, v170
	ds_read_b32 v130, v170 offset:64
	ds_read_b32 v144, v170 offset:128
	ds_read_b32 v146, v170 offset:192
	ds_read_b32 v148, v170 offset:512
	ds_read_b32 v156, v170 offset:576
	ds_read_b32 v158, v170 offset:640
	ds_read_b32 v160, v170 offset:704
	s_lshl_b32 s73, s0, 8
	v_or_b32_e32 v172, s73, v167
	v_mov_b32_e32 v173, 0
	v_mad_u64_u32 v[162:163], s[38:39], v150, s96, 0
	s_lshl_b32 s46, s96, 5
	s_mov_b32 s47, 0
	s_lshl_b32 s52, s96, 8
	s_mov_b32 s53, 0
	v_lshl_add_u64 v[162:163], v[162:163], 1, s[14:15]
	v_lshl_add_u64 v[162:163], v[172:173], 1, v[162:163]
	v_lshl_add_u64 v[178:179], v[162:163], 0, s[52:53]
	s_waitcnt lgkmcnt(0)
	v_mul_f32_e32 v128, v169, v128
	v_mul_f32_e32 v130, v169, v130
	v_mul_f32_e32 v144, v169, v144
	v_mul_f32_e32 v146, v169, v146
	v_mul_f32_e32 v148, v169, v148
	v_mul_f32_e32 v156, v169, v156
	v_mul_f32_e32 v158, v169, v158
	v_mul_f32_e32 v160, v169, v160
	v_lshl_add_u64 v[170:171], v[172:173], 2, s[64:65]
	global_load_dwordx4 v[152:155], v[170:171], off offset:-4096
	global_load_dwordx4 v[180:183], v[170:171], off offset:-4080
	global_load_dwordx4 v[218:221], v[170:171], off offset:-3584
	global_load_dwordx4 v[222:225], v[170:171], off offset:-3568
	s_waitcnt vmcnt(0)
	v_pk_mul_f32 v[124:125], v[124:125], v[128:129] op_sel_hi:[1,0]
	v_pk_mul_f32 v[126:127], v[126:127], v[128:129] op_sel_hi:[1,0]
	v_pk_mul_f32 v[120:121], v[120:121], v[128:129] op_sel_hi:[1,0]
	v_pk_mul_f32 v[122:123], v[122:123], v[128:129] op_sel_hi:[1,0]
	v_mul_f32_e32 v184, 0xbfb8aa3b, v124
	v_mul_f32_e32 v185, 0xbfb8aa3b, v125
	v_mul_f32_e32 v186, 0xbfb8aa3b, v126
	v_mul_f32_e32 v187, 0xbfb8aa3b, v127
	v_mul_f32_e32 v188, 0xbfb8aa3b, v120
	v_mul_f32_e32 v189, 0xbfb8aa3b, v121
	v_mul_f32_e32 v190, 0xbfb8aa3b, v122
	v_mul_f32_e32 v191, 0xbfb8aa3b, v123
	v_exp_f32_e32 v184, v184
	v_exp_f32_e32 v185, v185
	v_exp_f32_e32 v186, v186
	v_exp_f32_e32 v187, v187
	v_exp_f32_e32 v188, v188
	v_exp_f32_e32 v189, v189
	v_exp_f32_e32 v190, v190
	v_exp_f32_e32 v191, v191
	v_sub_f32_e32 v192, 1.0, v152
	v_sub_f32_e32 v193, 1.0, v153
	v_sub_f32_e32 v194, 1.0, v154
	v_sub_f32_e32 v195, 1.0, v155
	v_sub_f32_e32 v196, 1.0, v180
	v_sub_f32_e32 v197, 1.0, v181
	v_sub_f32_e32 v198, 1.0, v182
	v_sub_f32_e32 v199, 1.0, v183
	v_add_f32_e32 v184, 1.0, v184
	v_add_f32_e32 v185, 1.0, v185
	v_add_f32_e32 v186, 1.0, v186
	v_add_f32_e32 v187, 1.0, v187
	v_add_f32_e32 v188, 1.0, v188
	v_add_f32_e32 v189, 1.0, v189
	v_add_f32_e32 v190, 1.0, v190
	v_add_f32_e32 v191, 1.0, v191
	v_rcp_f32_e32 v184, v184
	v_rcp_f32_e32 v185, v185
	v_rcp_f32_e32 v186, v186
	v_rcp_f32_e32 v187, v187
	v_rcp_f32_e32 v188, v188
	v_rcp_f32_e32 v189, v189
	v_rcp_f32_e32 v190, v190
	v_rcp_f32_e32 v191, v191
	v_fma_f32 v200, v184, v192, v152
	v_fma_f32 v201, v185, v193, v153
	v_fma_f32 v202, v186, v194, v154
	v_fma_f32 v203, v187, v195, v155
	v_fma_f32 v204, v188, v196, v180
	v_fma_f32 v205, v189, v197, v181
	v_fma_f32 v206, v190, v198, v182
	v_fma_f32 v207, v191, v199, v183
	v_cmp_gt_f32_e64 vcc, s35, v200
	v_cmp_gt_f32_e64 s[38:39], s35, v201
	v_cmp_gt_f32_e64 s[48:49], s35, v202
	v_cmp_gt_f32_e64 s[50:51], s35, v203
	v_cndmask_b32_e64 v184, 0, 32, vcc
	v_cndmask_b32_e64 v185, 0, 32, s[38:39]
	v_cndmask_b32_e64 v186, 0, 32, s[48:49]
	v_cndmask_b32_e64 v187, 0, 32, s[50:51]
	v_cndmask_b32_e64 v192, 0, v214, vcc
; __device__ __forceinline__ unsigned cvt_pk_bf16(float lo, float hi) { unsigned r; asm volatile("v_cvt_pk_bf16_f32 %0, %1, %2" : "=v"(r) : "v"(lo), "v"(hi)); return r; }
; __device__ __forceinline__ float silu_f(float v) { return v * __builtin_amdgcn_rcpf(1.f + __expf(-v)); }
;     __device__ __forceinline__ void operator()(const f32x4 (&acc)[2][2][4][2], const Unit& u, int wr, int wc, int fr, int fq, int ui, PG8_LAS unsigned char* lds) const {
;     ...
;                     f32x4 v[2] = {acc[ai][bj][m][0] * rs, acc[ai][bj][m][1] * rs};
;                     if (ksum) { csum[bj][0] += v[0]; csum[bj][1] += v[1]; }
; #pragma unroll
;                     for (int n = 0; n < 2; ++n) {
;                         f32x4 lbv = (f32x4){0.f, 0.f, 0.f, 0.f};
;                         if (act == 2) lbv = *(const f32x4*)(lb + (col0 - 1024) + bj * HALF + 4 * n);
; #pragma unroll
;                         for (int e = 0; e < 4; ++e) {
;                             float x = v[n][e];
;                             if (act == 1) x = silu_f(x);
;                             else if (act == 2) { const float l = lbv[e]; x = __logf(l + (1.f - l) * __builtin_amdgcn_rcpf(1.f + __expf(-x))); }
;                             else if (act == 3) { x = fmaxf(x, 0.f); x = x * x; }
;                             v[n][e] = x;
;                         }
;                     }
;                     u32x4 w; w.x = cvt_pk_bf16(v[0][0], v[0][1]); w.y = cvt_pk_bf16(v[0][2], v[0][3]); w.z = cvt_pk_bf16(v[1][0], v[1][1]); w.w = cvt_pk_bf16(v[1][2], v[1][3]);
;                     *(u32x4*)(rowp + bj * HALF) = w;
	v_cndmask_b32_e64 v193, 0, v214, s[38:39]
	v_cndmask_b32_e64 v194, 0, v214, s[48:49]
	v_cndmask_b32_e64 v195, 0, v214, s[50:51]
	v_cmp_gt_f32_e64 vcc, s35, v204
	v_cmp_gt_f32_e64 s[38:39], s35, v205
	v_cmp_gt_f32_e64 s[48:49], s35, v206
	v_cmp_gt_f32_e64 s[50:51], s35, v207
	v_cndmask_b32_e64 v188, 0, 32, vcc
	v_cndmask_b32_e64 v189, 0, 32, s[38:39]
	v_cndmask_b32_e64 v190, 0, 32, s[48:49]
	v_cndmask_b32_e64 v191, 0, 32, s[50:51]
	v_cndmask_b32_e64 v196, 0, v214, vcc
	v_cndmask_b32_e64 v197, 0, v214, s[38:39]
	v_cndmask_b32_e64 v198, 0, v214, s[48:49]
	v_cndmask_b32_e64 v199, 0, v214, s[50:51]
	v_ldexp_f32 v184, v200, v184
	v_ldexp_f32 v185, v201, v185
	v_ldexp_f32 v186, v202, v186
	v_ldexp_f32 v187, v203, v187
	v_ldexp_f32 v188, v204, v188
	v_ldexp_f32 v189, v205, v189
	v_ldexp_f32 v190, v206, v190
	v_ldexp_f32 v191, v207, v191
	v_log_f32_e32 v184, v184
	v_log_f32_e32 v185, v185
	v_log_f32_e32 v186, v186
	v_log_f32_e32 v187, v187
	v_log_f32_e32 v188, v188
	v_log_f32_e32 v189, v189
	v_log_f32_e32 v190, v190
	v_log_f32_e32 v191, v191
	v_mul_f32_e32 v200, 0x3f317217, v184
	v_mul_f32_e32 v201, 0x3f317217, v185
	v_mul_f32_e32 v202, 0x3f317217, v186
	v_mul_f32_e32 v203, 0x3f317217, v187
	v_mul_f32_e32 v204, 0x3f317217, v188
	v_mul_f32_e32 v205, 0x3f317217, v189
	v_mul_f32_e32 v206, 0x3f317217, v190
	v_mul_f32_e32 v207, 0x3f317217, v191
	v_fma_f32 v200, v184, s13, -v200
	v_fma_f32 v201, v185, s13, -v201
	v_fma_f32 v202, v186, s13, -v202
	v_fma_f32 v203, v187, s13, -v203
	v_fma_f32 v204, v188, s13, -v204
	v_fma_f32 v205, v189, s13, -v205
	v_fma_f32 v206, v190, s13, -v206
	v_fma_f32 v207, v191, s13, -v207
	v_fmac_f32_e32 v200, 0x3377d1cf, v184
	v_fmac_f32_e32 v201, 0x3377d1cf, v185
	v_fmac_f32_e32 v202, 0x3377d1cf, v186
	v_fmac_f32_e32 v203, 0x3377d1cf, v187
	v_fmac_f32_e32 v204, 0x3377d1cf, v188
	v_fmac_f32_e32 v205, 0x3377d1cf, v189
	v_fmac_f32_e32 v206, 0x3377d1cf, v190
	v_fmac_f32_e32 v207, 0x3377d1cf, v191
	v_fmac_f32_e32 v200, 0x3f317217, v184
	v_fmac_f32_e32 v201, 0x3f317217, v185
	v_fmac_f32_e32 v202, 0x3f317217, v186
	v_fmac_f32_e32 v203, 0x3f317217, v187
	v_fmac_f32_e32 v204, 0x3f317217, v188
	v_fmac_f32_e32 v205, 0x3f317217, v189
	v_fmac_f32_e32 v206, 0x3f317217, v190
	v_fmac_f32_e32 v207, 0x3f317217, v191
	v_cmp_lt_f32_e64 vcc, |v184|, s36
	v_cmp_lt_f32_e64 s[38:39], |v185|, s36
	v_cmp_lt_f32_e64 s[48:49], |v186|, s36
	v_cmp_lt_f32_e64 s[50:51], |v187|, s36
	v_cndmask_b32_e64 v184, v184, v200, vcc
	v_cndmask_b32_e64 v185, v185, v201, s[38:39]
	v_cndmask_b32_e64 v186, v186, v202, s[48:49]
	v_cndmask_b32_e64 v187, v187, v203, s[50:51]
	v_cmp_lt_f32_e64 vcc, |v188|, s36
	v_cmp_lt_f32_e64 s[38:39], |v189|, s36
	v_cmp_lt_f32_e64 s[48:49], |v190|, s36
	v_cmp_lt_f32_e64 s[50:51], |v191|, s36
	v_cndmask_b32_e64 v188, v188, v204, vcc
	v_cndmask_b32_e64 v189, v189, v205, s[38:39]
	v_cndmask_b32_e64 v190, v190, v206, s[48:49]
	v_cndmask_b32_e64 v191, v191, v207, s[50:51]
	v_sub_f32_e32 v124, v184, v192
	v_sub_f32_e32 v125, v185, v193
	v_sub_f32_e32 v126, v186, v194
	v_sub_f32_e32 v127, v187, v195
	v_sub_f32_e32 v120, v188, v196
	v_sub_f32_e32 v121, v189, v197
	v_sub_f32_e32 v122, v190, v198
	v_sub_f32_e32 v123, v191, v199
	v_cvt_pk_bf16_f32 v124, v124, v125
	v_cvt_pk_bf16_f32 v125, v126, v127
	v_cvt_pk_bf16_f32 v126, v120, v121
	v_cvt_pk_bf16_f32 v127, v122, v123
	global_store_dwordx4 v[162:163], v[124:127], off
	v_pk_mul_f32 v[116:117], v[116:117], v[128:129] op_sel_hi:[1,0]
	v_pk_mul_f32 v[118:119], v[118:119], v[128:129] op_sel_hi:[1,0]
	v_pk_mul_f32 v[112:113], v[112:113], v[128:129] op_sel_hi:[1,0]
	v_pk_mul_f32 v[114:115], v[114:115], v[128:129] op_sel_hi:[1,0]
	v_mul_f32_e32 v184, 0xbfb8aa3b, v116
	v_mul_f32_e32 v185, 0xbfb8aa3b, v117
	v_mul_f32_e32 v186, 0xbfb8aa3b, v118
	v_mul_f32_e32 v187, 0xbfb8aa3b, v119
	v_mul_f32_e32 v188, 0xbfb8aa3b, v112
	v_mul_f32_e32 v189, 0xbfb8aa3b, v113
	v_mul_f32_e32 v190, 0xbfb8aa3b, v114
	v_mul_f32_e32 v191, 0xbfb8aa3b, v115
	v_exp_f32_e32 v184, v184
	v_exp_f32_e32 v185, v185
	v_exp_f32_e32 v186, v186
	v_exp_f32_e32 v187, v187
	v_exp_f32_e32 v188, v188
	v_exp_f32_e32 v189, v189
	v_exp_f32_e32 v190, v190
	v_exp_f32_e32 v191, v191
	v_sub_f32_e32 v192, 1.0, v218
	v_sub_f32_e32 v193, 1.0, v219
	v_sub_f32_e32 v194, 1.0, v220
	v_sub_f32_e32 v195, 1.0, v221
	v_sub_f32_e32 v196, 1.0, v222
	v_sub_f32_e32 v197, 1.0, v223
	v_sub_f32_e32 v198, 1.0, v224
	v_sub_f32_e32 v199, 1.0, v225
	v_add_f32_e32 v184, 1.0, v184
	v_add_f32_e32 v185, 1.0, v185
	v_add_f32_e32 v186, 1.0, v186
	v_add_f32_e32 v187, 1.0, v187
	v_add_f32_e32 v188, 1.0, v188
	v_add_f32_e32 v189, 1.0, v189
	v_add_f32_e32 v190, 1.0, v190
	v_add_f32_e32 v191, 1.0, v191
	v_rcp_f32_e32 v184, v184
	v_rcp_f32_e32 v185, v185
	v_rcp_f32_e32 v186, v186
	v_rcp_f32_e32 v187, v187
	v_rcp_f32_e32 v188, v188
	v_rcp_f32_e32 v189, v189
	v_rcp_f32_e32 v190, v190
	v_rcp_f32_e32 v191, v191
	v_fma_f32 v200, v184, v192, v218
	v_fma_f32 v201, v185, v193, v219
	v_fma_f32 v202, v186, v194, v220
	v_fma_f32 v203, v187, v195, v221
	v_fma_f32 v204, v188, v196, v222
	v_fma_f32 v205, v189, v197, v223
	v_fma_f32 v206, v190, v198, v224
	v_fma_f32 v207, v191, v199, v225
	v_cmp_gt_f32_e64 vcc, s35, v200
	v_cmp_gt_f32_e64 s[38:39], s35, v201
	v_cmp_gt_f32_e64 s[48:49], s35, v202
	v_cmp_gt_f32_e64 s[50:51], s35, v203
	v_cndmask_b32_e64 v184, 0, 32, vcc
	v_cndmask_b32_e64 v185, 0, 32, s[38:39]
	v_cndmask_b32_e64 v186, 0, 32, s[48:49]
	v_cndmask_b32_e64 v187, 0, 32, s[50:51]
	v_cndmask_b32_e64 v192, 0, v214, vcc
	v_cndmask_b32_e64 v193, 0, v214, s[38:39]
	v_cndmask_b32_e64 v194, 0, v214, s[48:49]
	v_cndmask_b32_e64 v195, 0, v214, s[50:51]
	v_cmp_gt_f32_e64 vcc, s35, v204
; __device__ __forceinline__ unsigned cvt_pk_bf16(float lo, float hi) { unsigned r; asm volatile("v_cvt_pk_bf16_f32 %0, %1, %2" : "=v"(r) : "v"(lo), "v"(hi)); return r; }
; __device__ __forceinline__ float silu_f(float v) { return v * __builtin_amdgcn_rcpf(1.f + __expf(-v)); }
; #define PG8_BAR __builtin_amdgcn_s_barrier()
;     __device__ __forceinline__ void operator()(const f32x4 (&acc)[2][2][4][2], const Unit& u, int wr, int wc, int fr, int fq, int ui, PG8_LAS unsigned char* lds) const {
;     ...
;                     f32x4 v[2] = {acc[ai][bj][m][0] * rs, acc[ai][bj][m][1] * rs};
;                     if (ksum) { csum[bj][0] += v[0]; csum[bj][1] += v[1]; }
; #pragma unroll
;                     for (int n = 0; n < 2; ++n) {
;                         f32x4 lbv = (f32x4){0.f, 0.f, 0.f, 0.f};
;                         if (act == 2) lbv = *(const f32x4*)(lb + (col0 - 1024) + bj * HALF + 4 * n);
; #pragma unroll
;                         for (int e = 0; e < 4; ++e) {
;                             float x = v[n][e];
;                             if (act == 1) x = silu_f(x);
;                             else if (act == 2) { const float l = lbv[e]; x = __logf(l + (1.f - l) * __builtin_amdgcn_rcpf(1.f + __expf(-x))); }
;                             else if (act == 3) { x = fmaxf(x, 0.f); x = x * x; }
;                             v[n][e] = x;
;                         }
;                     }
;                     u32x4 w; w.x = cvt_pk_bf16(v[0][0], v[0][1]); w.y = cvt_pk_bf16(v[0][2], v[0][3]); w.z = cvt_pk_bf16(v[1][0], v[1][1]); w.w = cvt_pk_bf16(v[1][2], v[1][3]);
;                     *(u32x4*)(rowp + bj * HALF) = w;
; template <class Epi, class Sched, bool ALIGN_EPI = false, bool SP2 = false>
; __device__ __forceinline__ void gemm_phase(PG8_LAS unsigned char* lds, const Gemm g, const Sched& S, const Epi& E) {
;     ...
;         if constexpr (ALIGN_EPI) { if (wr == 0) PG8_BAR; }
	v_cmp_gt_f32_e64 s[38:39], s35, v205
	v_cmp_gt_f32_e64 s[48:49], s35, v206
	v_cmp_gt_f32_e64 s[50:51], s35, v207
	v_cndmask_b32_e64 v188, 0, 32, vcc
	v_cndmask_b32_e64 v189, 0, 32, s[38:39]
	v_cndmask_b32_e64 v190, 0, 32, s[48:49]
	v_cndmask_b32_e64 v191, 0, 32, s[50:51]
	v_cndmask_b32_e64 v196, 0, v214, vcc
	v_cndmask_b32_e64 v197, 0, v214, s[38:39]
	v_cndmask_b32_e64 v198, 0, v214, s[48:49]
	v_cndmask_b32_e64 v199, 0, v214, s[50:51]
	v_ldexp_f32 v184, v200, v184
	v_ldexp_f32 v185, v201, v185
	v_ldexp_f32 v186, v202, v186
	v_ldexp_f32 v187, v203, v187
	v_ldexp_f32 v188, v204, v188
	v_ldexp_f32 v189, v205, v189
	v_ldexp_f32 v190, v206, v190
	v_ldexp_f32 v191, v207, v191
	v_log_f32_e32 v184, v184
	v_log_f32_e32 v185, v185
	v_log_f32_e32 v186, v186
	v_log_f32_e32 v187, v187
	v_log_f32_e32 v188, v188
	v_log_f32_e32 v189, v189
	v_log_f32_e32 v190, v190
	v_log_f32_e32 v191, v191
	v_mul_f32_e32 v200, 0x3f317217, v184
	v_mul_f32_e32 v201, 0x3f317217, v185
	v_mul_f32_e32 v202, 0x3f317217, v186
	v_mul_f32_e32 v203, 0x3f317217, v187
	v_mul_f32_e32 v204, 0x3f317217, v188
	v_mul_f32_e32 v205, 0x3f317217, v189
	v_mul_f32_e32 v206, 0x3f317217, v190
	v_mul_f32_e32 v207, 0x3f317217, v191
	v_fma_f32 v200, v184, s13, -v200
	v_fma_f32 v201, v185, s13, -v201
	v_fma_f32 v202, v186, s13, -v202
	v_fma_f32 v203, v187, s13, -v203
	v_fma_f32 v204, v188, s13, -v204
	v_fma_f32 v205, v189, s13, -v205
	v_fma_f32 v206, v190, s13, -v206
	v_fma_f32 v207, v191, s13, -v207
	v_fmac_f32_e32 v200, 0x3377d1cf, v184
	v_fmac_f32_e32 v201, 0x3377d1cf, v185
	v_fmac_f32_e32 v202, 0x3377d1cf, v186
	v_fmac_f32_e32 v203, 0x3377d1cf, v187
	v_fmac_f32_e32 v204, 0x3377d1cf, v188
	v_fmac_f32_e32 v205, 0x3377d1cf, v189
	v_fmac_f32_e32 v206, 0x3377d1cf, v190
	v_fmac_f32_e32 v207, 0x3377d1cf, v191
	v_fmac_f32_e32 v200, 0x3f317217, v184
	v_fmac_f32_e32 v201, 0x3f317217, v185
	v_fmac_f32_e32 v202, 0x3f317217, v186
	v_fmac_f32_e32 v203, 0x3f317217, v187
	v_fmac_f32_e32 v204, 0x3f317217, v188
	v_fmac_f32_e32 v205, 0x3f317217, v189
	v_fmac_f32_e32 v206, 0x3f317217, v190
	v_fmac_f32_e32 v207, 0x3f317217, v191
	v_cmp_lt_f32_e64 vcc, |v184|, s36
	v_cmp_lt_f32_e64 s[38:39], |v185|, s36
	v_cmp_lt_f32_e64 s[48:49], |v186|, s36
	v_cmp_lt_f32_e64 s[50:51], |v187|, s36
	v_cndmask_b32_e64 v184, v184, v200, vcc
	v_cndmask_b32_e64 v185, v185, v201, s[38:39]
	v_cndmask_b32_e64 v186, v186, v202, s[48:49]
	v_cndmask_b32_e64 v187, v187, v203, s[50:51]
	v_cmp_lt_f32_e64 vcc, |v188|, s36
	v_cmp_lt_f32_e64 s[38:39], |v189|, s36
	v_cmp_lt_f32_e64 s[48:49], |v190|, s36
	v_cmp_lt_f32_e64 s[50:51], |v191|, s36
	v_cndmask_b32_e64 v188, v188, v204, vcc
	v_cndmask_b32_e64 v189, v189, v205, s[38:39]
	v_cndmask_b32_e64 v190, v190, v206, s[48:49]
	v_cndmask_b32_e64 v191, v191, v207, s[50:51]
	v_sub_f32_e32 v116, v184, v192
	v_sub_f32_e32 v117, v185, v193
	v_sub_f32_e32 v118, v186, v194
	v_sub_f32_e32 v119, v187, v195
	v_sub_f32_e32 v112, v188, v196
	v_sub_f32_e32 v113, v189, v197
	v_sub_f32_e32 v114, v190, v198
	v_sub_f32_e32 v115, v191, v199
	v_cvt_pk_bf16_f32 v116, v116, v117
	v_cvt_pk_bf16_f32 v117, v118, v119
	v_cvt_pk_bf16_f32 v118, v112, v113
	v_cvt_pk_bf16_f32 v119, v114, v115
	global_store_dwordx4 v[162:163], v[116:119], off offset:256
	s_cmp_eq_u64 s[68:69], 0
	s_cbranch_scc1 .Lal1lo_skip
	s_barrier
.Lal1lo_skip:
	v_lshl_add_u64 v[176:177], v[162:163], 0, s[46:47]
	v_pk_mul_f32 v[108:109], v[108:109], v[130:131] op_sel_hi:[1,0]
	v_pk_mul_f32 v[110:111], v[110:111], v[130:131] op_sel_hi:[1,0]
	v_pk_mul_f32 v[104:105], v[104:105], v[130:131] op_sel_hi:[1,0]
	v_pk_mul_f32 v[106:107], v[106:107], v[130:131] op_sel_hi:[1,0]
	v_mul_f32_e32 v184, 0xbfb8aa3b, v108
	v_mul_f32_e32 v185, 0xbfb8aa3b, v109
	v_mul_f32_e32 v186, 0xbfb8aa3b, v110
	v_mul_f32_e32 v187, 0xbfb8aa3b, v111
	v_mul_f32_e32 v188, 0xbfb8aa3b, v104
	v_mul_f32_e32 v189, 0xbfb8aa3b, v105
	v_mul_f32_e32 v190, 0xbfb8aa3b, v106
	v_mul_f32_e32 v191, 0xbfb8aa3b, v107
	v_exp_f32_e32 v184, v184
	v_exp_f32_e32 v185, v185
	v_exp_f32_e32 v186, v186
	v_exp_f32_e32 v187, v187
	v_exp_f32_e32 v188, v188
	v_exp_f32_e32 v189, v189
	v_exp_f32_e32 v190, v190
	v_exp_f32_e32 v191, v191
	v_sub_f32_e32 v192, 1.0, v152
	v_sub_f32_e32 v193, 1.0, v153
	v_sub_f32_e32 v194, 1.0, v154
	v_sub_f32_e32 v195, 1.0, v155
	v_sub_f32_e32 v196, 1.0, v180
	v_sub_f32_e32 v197, 1.0, v181
	v_sub_f32_e32 v198, 1.0, v182
	v_sub_f32_e32 v199, 1.0, v183
	v_add_f32_e32 v184, 1.0, v184
	v_add_f32_e32 v185, 1.0, v185
	v_add_f32_e32 v186, 1.0, v186
	v_add_f32_e32 v187, 1.0, v187
	v_add_f32_e32 v188, 1.0, v188
	v_add_f32_e32 v189, 1.0, v189
	v_add_f32_e32 v190, 1.0, v190
	v_add_f32_e32 v191, 1.0, v191
	v_rcp_f32_e32 v184, v184
	v_rcp_f32_e32 v185, v185
	v_rcp_f32_e32 v186, v186
	v_rcp_f32_e32 v187, v187
	v_rcp_f32_e32 v188, v188
	v_rcp_f32_e32 v189, v189
	v_rcp_f32_e32 v190, v190
	v_rcp_f32_e32 v191, v191
	v_fma_f32 v200, v184, v192, v152
	v_fma_f32 v201, v185, v193, v153
	v_fma_f32 v202, v186, v194, v154
	v_fma_f32 v203, v187, v195, v155
	v_fma_f32 v204, v188, v196, v180
	v_fma_f32 v205, v189, v197, v181
	v_fma_f32 v206, v190, v198, v182
	v_fma_f32 v207, v191, v199, v183
	v_cmp_gt_f32_e64 vcc, s35, v200
	v_cmp_gt_f32_e64 s[38:39], s35, v201
	v_cmp_gt_f32_e64 s[48:49], s35, v202
	v_cmp_gt_f32_e64 s[50:51], s35, v203
	v_cndmask_b32_e64 v184, 0, 32, vcc
	v_cndmask_b32_e64 v185, 0, 32, s[38:39]
	v_cndmask_b32_e64 v186, 0, 32, s[48:49]
	v_cndmask_b32_e64 v187, 0, 32, s[50:51]
	v_cndmask_b32_e64 v192, 0, v214, vcc
	v_cndmask_b32_e64 v193, 0, v214, s[38:39]
	v_cndmask_b32_e64 v194, 0, v214, s[48:49]
	v_cndmask_b32_e64 v195, 0, v214, s[50:51]
	v_cmp_gt_f32_e64 vcc, s35, v204
	v_cmp_gt_f32_e64 s[38:39], s35, v205
; __device__ __forceinline__ unsigned cvt_pk_bf16(float lo, float hi) { unsigned r; asm volatile("v_cvt_pk_bf16_f32 %0, %1, %2" : "=v"(r) : "v"(lo), "v"(hi)); return r; }
; __device__ __forceinline__ float silu_f(float v) { return v * __builtin_amdgcn_rcpf(1.f + __expf(-v)); }
;     __device__ __forceinline__ void operator()(const f32x4 (&acc)[2][2][4][2], const Unit& u, int wr, int wc, int fr, int fq, int ui, PG8_LAS unsigned char* lds) const {
;     ...
;                     f32x4 v[2] = {acc[ai][bj][m][0] * rs, acc[ai][bj][m][1] * rs};
;                     if (ksum) { csum[bj][0] += v[0]; csum[bj][1] += v[1]; }
; #pragma unroll
;                     for (int n = 0; n < 2; ++n) {
;                         f32x4 lbv = (f32x4){0.f, 0.f, 0.f, 0.f};
;                         if (act == 2) lbv = *(const f32x4*)(lb + (col0 - 1024) + bj * HALF + 4 * n);
; #pragma unroll
;                         for (int e = 0; e < 4; ++e) {
;                             float x = v[n][e];
;                             if (act == 1) x = silu_f(x);
;                             else if (act == 2) { const float l = lbv[e]; x = __logf(l + (1.f - l) * __builtin_amdgcn_rcpf(1.f + __expf(-x))); }
;                             else if (act == 3) { x = fmaxf(x, 0.f); x = x * x; }
;                             v[n][e] = x;
;                         }
;                     }
;                     u32x4 w; w.x = cvt_pk_bf16(v[0][0], v[0][1]); w.y = cvt_pk_bf16(v[0][2], v[0][3]); w.z = cvt_pk_bf16(v[1][0], v[1][1]); w.w = cvt_pk_bf16(v[1][2], v[1][3]);
;                     *(u32x4*)(rowp + bj * HALF) = w;
	v_cmp_gt_f32_e64 s[48:49], s35, v206
	v_cmp_gt_f32_e64 s[50:51], s35, v207
	v_cndmask_b32_e64 v188, 0, 32, vcc
	v_cndmask_b32_e64 v189, 0, 32, s[38:39]
	v_cndmask_b32_e64 v190, 0, 32, s[48:49]
	v_cndmask_b32_e64 v191, 0, 32, s[50:51]
	v_cndmask_b32_e64 v196, 0, v214, vcc
	v_cndmask_b32_e64 v197, 0, v214, s[38:39]
	v_cndmask_b32_e64 v198, 0, v214, s[48:49]
	v_cndmask_b32_e64 v199, 0, v214, s[50:51]
	v_ldexp_f32 v184, v200, v184
	v_ldexp_f32 v185, v201, v185
	v_ldexp_f32 v186, v202, v186
	v_ldexp_f32 v187, v203, v187
	v_ldexp_f32 v188, v204, v188
	v_ldexp_f32 v189, v205, v189
	v_ldexp_f32 v190, v206, v190
	v_ldexp_f32 v191, v207, v191
	v_log_f32_e32 v184, v184
	v_log_f32_e32 v185, v185
	v_log_f32_e32 v186, v186
	v_log_f32_e32 v187, v187
	v_log_f32_e32 v188, v188
	v_log_f32_e32 v189, v189
	v_log_f32_e32 v190, v190
	v_log_f32_e32 v191, v191
	v_mul_f32_e32 v200, 0x3f317217, v184
	v_mul_f32_e32 v201, 0x3f317217, v185
	v_mul_f32_e32 v202, 0x3f317217, v186
	v_mul_f32_e32 v203, 0x3f317217, v187
	v_mul_f32_e32 v204, 0x3f317217, v188
	v_mul_f32_e32 v205, 0x3f317217, v189
	v_mul_f32_e32 v206, 0x3f317217, v190
	v_mul_f32_e32 v207, 0x3f317217, v191
	v_fma_f32 v200, v184, s13, -v200
	v_fma_f32 v201, v185, s13, -v201
	v_fma_f32 v202, v186, s13, -v202
	v_fma_f32 v203, v187, s13, -v203
	v_fma_f32 v204, v188, s13, -v204
	v_fma_f32 v205, v189, s13, -v205
	v_fma_f32 v206, v190, s13, -v206
	v_fma_f32 v207, v191, s13, -v207
	v_fmac_f32_e32 v200, 0x3377d1cf, v184
	v_fmac_f32_e32 v201, 0x3377d1cf, v185
	v_fmac_f32_e32 v202, 0x3377d1cf, v186
	v_fmac_f32_e32 v203, 0x3377d1cf, v187
	v_fmac_f32_e32 v204, 0x3377d1cf, v188
	v_fmac_f32_e32 v205, 0x3377d1cf, v189
	v_fmac_f32_e32 v206, 0x3377d1cf, v190
	v_fmac_f32_e32 v207, 0x3377d1cf, v191
	v_fmac_f32_e32 v200, 0x3f317217, v184
	v_fmac_f32_e32 v201, 0x3f317217, v185
	v_fmac_f32_e32 v202, 0x3f317217, v186
	v_fmac_f32_e32 v203, 0x3f317217, v187
	v_fmac_f32_e32 v204, 0x3f317217, v188
	v_fmac_f32_e32 v205, 0x3f317217, v189
	v_fmac_f32_e32 v206, 0x3f317217, v190
	v_fmac_f32_e32 v207, 0x3f317217, v191
	v_cmp_lt_f32_e64 vcc, |v184|, s36
	v_cmp_lt_f32_e64 s[38:39], |v185|, s36
	v_cmp_lt_f32_e64 s[48:49], |v186|, s36
	v_cmp_lt_f32_e64 s[50:51], |v187|, s36
	v_cndmask_b32_e64 v184, v184, v200, vcc
	v_cndmask_b32_e64 v185, v185, v201, s[38:39]
	v_cndmask_b32_e64 v186, v186, v202, s[48:49]
	v_cndmask_b32_e64 v187, v187, v203, s[50:51]
	v_cmp_lt_f32_e64 vcc, |v188|, s36
	v_cmp_lt_f32_e64 s[38:39], |v189|, s36
	v_cmp_lt_f32_e64 s[48:49], |v190|, s36
	v_cmp_lt_f32_e64 s[50:51], |v191|, s36
	v_cndmask_b32_e64 v188, v188, v204, vcc
	v_cndmask_b32_e64 v189, v189, v205, s[38:39]
	v_cndmask_b32_e64 v190, v190, v206, s[48:49]
	v_cndmask_b32_e64 v191, v191, v207, s[50:51]
	v_sub_f32_e32 v108, v184, v192
	v_sub_f32_e32 v109, v185, v193
	v_sub_f32_e32 v110, v186, v194
	v_sub_f32_e32 v111, v187, v195
	v_sub_f32_e32 v104, v188, v196
	v_sub_f32_e32 v105, v189, v197
	v_sub_f32_e32 v106, v190, v198
	v_sub_f32_e32 v107, v191, v199
	v_cvt_pk_bf16_f32 v108, v108, v109
	v_cvt_pk_bf16_f32 v109, v110, v111
	v_cvt_pk_bf16_f32 v110, v104, v105
	v_cvt_pk_bf16_f32 v111, v106, v107
	global_store_dwordx4 v[176:177], v[108:111], off
	v_pk_mul_f32 v[100:101], v[100:101], v[130:131] op_sel_hi:[1,0]
	v_pk_mul_f32 v[102:103], v[102:103], v[130:131] op_sel_hi:[1,0]
	v_pk_mul_f32 v[96:97], v[96:97], v[130:131] op_sel_hi:[1,0]
	v_pk_mul_f32 v[98:99], v[98:99], v[130:131] op_sel_hi:[1,0]
	v_mul_f32_e32 v184, 0xbfb8aa3b, v100
	v_mul_f32_e32 v185, 0xbfb8aa3b, v101
	v_mul_f32_e32 v186, 0xbfb8aa3b, v102
	v_mul_f32_e32 v187, 0xbfb8aa3b, v103
	v_mul_f32_e32 v188, 0xbfb8aa3b, v96
	v_mul_f32_e32 v189, 0xbfb8aa3b, v97
	v_mul_f32_e32 v190, 0xbfb8aa3b, v98
	v_mul_f32_e32 v191, 0xbfb8aa3b, v99
	v_exp_f32_e32 v184, v184
	v_exp_f32_e32 v185, v185
	v_exp_f32_e32 v186, v186
	v_exp_f32_e32 v187, v187
	v_exp_f32_e32 v188, v188
	v_exp_f32_e32 v189, v189
	v_exp_f32_e32 v190, v190
	v_exp_f32_e32 v191, v191
	v_sub_f32_e32 v192, 1.0, v218
	v_sub_f32_e32 v193, 1.0, v219
	v_sub_f32_e32 v194, 1.0, v220
	v_sub_f32_e32 v195, 1.0, v221
	v_sub_f32_e32 v196, 1.0, v222
	v_sub_f32_e32 v197, 1.0, v223
	v_sub_f32_e32 v198, 1.0, v224
	v_sub_f32_e32 v199, 1.0, v225
	v_add_f32_e32 v184, 1.0, v184
	v_add_f32_e32 v185, 1.0, v185
	v_add_f32_e32 v186, 1.0, v186
	v_add_f32_e32 v187, 1.0, v187
	v_add_f32_e32 v188, 1.0, v188
	v_add_f32_e32 v189, 1.0, v189
	v_add_f32_e32 v190, 1.0, v190
	v_add_f32_e32 v191, 1.0, v191
	v_rcp_f32_e32 v184, v184
	v_rcp_f32_e32 v185, v185
	v_rcp_f32_e32 v186, v186
	v_rcp_f32_e32 v187, v187
	v_rcp_f32_e32 v188, v188
	v_rcp_f32_e32 v189, v189
	v_rcp_f32_e32 v190, v190
	v_rcp_f32_e32 v191, v191
	v_fma_f32 v200, v184, v192, v218
	v_fma_f32 v201, v185, v193, v219
	v_fma_f32 v202, v186, v194, v220
	v_fma_f32 v203, v187, v195, v221
	v_fma_f32 v204, v188, v196, v222
	v_fma_f32 v205, v189, v197, v223
	v_fma_f32 v206, v190, v198, v224
	v_fma_f32 v207, v191, v199, v225
	v_cmp_gt_f32_e64 vcc, s35, v200
	v_cmp_gt_f32_e64 s[38:39], s35, v201
	v_cmp_gt_f32_e64 s[48:49], s35, v202
	v_cmp_gt_f32_e64 s[50:51], s35, v203
	v_cndmask_b32_e64 v184, 0, 32, vcc
	v_cndmask_b32_e64 v185, 0, 32, s[38:39]
	v_cndmask_b32_e64 v186, 0, 32, s[48:49]
	v_cndmask_b32_e64 v187, 0, 32, s[50:51]
	v_cndmask_b32_e64 v192, 0, v214, vcc
	v_cndmask_b32_e64 v193, 0, v214, s[38:39]
	v_cndmask_b32_e64 v194, 0, v214, s[48:49]
	v_cndmask_b32_e64 v195, 0, v214, s[50:51]
	v_cmp_gt_f32_e64 vcc, s35, v204
	v_cmp_gt_f32_e64 s[38:39], s35, v205
	v_cmp_gt_f32_e64 s[48:49], s35, v206
	v_cmp_gt_f32_e64 s[50:51], s35, v207
	v_cndmask_b32_e64 v188, 0, 32, vcc
	v_cndmask_b32_e64 v189, 0, 32, s[38:39]
	v_cndmask_b32_e64 v190, 0, 32, s[48:49]
; __device__ __forceinline__ unsigned cvt_pk_bf16(float lo, float hi) { unsigned r; asm volatile("v_cvt_pk_bf16_f32 %0, %1, %2" : "=v"(r) : "v"(lo), "v"(hi)); return r; }
; __device__ __forceinline__ float silu_f(float v) { return v * __builtin_amdgcn_rcpf(1.f + __expf(-v)); }
;     __device__ __forceinline__ void operator()(const f32x4 (&acc)[2][2][4][2], const Unit& u, int wr, int wc, int fr, int fq, int ui, PG8_LAS unsigned char* lds) const {
;     ...
;                     f32x4 v[2] = {acc[ai][bj][m][0] * rs, acc[ai][bj][m][1] * rs};
;                     if (ksum) { csum[bj][0] += v[0]; csum[bj][1] += v[1]; }
; #pragma unroll
;                     for (int n = 0; n < 2; ++n) {
;                         f32x4 lbv = (f32x4){0.f, 0.f, 0.f, 0.f};
;                         if (act == 2) lbv = *(const f32x4*)(lb + (col0 - 1024) + bj * HALF + 4 * n);
; #pragma unroll
;                         for (int e = 0; e < 4; ++e) {
;                             float x = v[n][e];
;                             if (act == 1) x = silu_f(x);
;                             else if (act == 2) { const float l = lbv[e]; x = __logf(l + (1.f - l) * __builtin_amdgcn_rcpf(1.f + __expf(-x))); }
;                             else if (act == 3) { x = fmaxf(x, 0.f); x = x * x; }
;                             v[n][e] = x;
;                         }
;                     }
;                     u32x4 w; w.x = cvt_pk_bf16(v[0][0], v[0][1]); w.y = cvt_pk_bf16(v[0][2], v[0][3]); w.z = cvt_pk_bf16(v[1][0], v[1][1]); w.w = cvt_pk_bf16(v[1][2], v[1][3]);
;                     *(u32x4*)(rowp + bj * HALF) = w;
	v_cndmask_b32_e64 v191, 0, 32, s[50:51]
	v_cndmask_b32_e64 v196, 0, v214, vcc
	v_cndmask_b32_e64 v197, 0, v214, s[38:39]
	v_cndmask_b32_e64 v198, 0, v214, s[48:49]
	v_cndmask_b32_e64 v199, 0, v214, s[50:51]
	v_ldexp_f32 v184, v200, v184
	v_ldexp_f32 v185, v201, v185
	v_ldexp_f32 v186, v202, v186
	v_ldexp_f32 v187, v203, v187
	v_ldexp_f32 v188, v204, v188
	v_ldexp_f32 v189, v205, v189
	v_ldexp_f32 v190, v206, v190
	v_ldexp_f32 v191, v207, v191
	v_log_f32_e32 v184, v184
	v_log_f32_e32 v185, v185
	v_log_f32_e32 v186, v186
	v_log_f32_e32 v187, v187
	v_log_f32_e32 v188, v188
	v_log_f32_e32 v189, v189
	v_log_f32_e32 v190, v190
	v_log_f32_e32 v191, v191
	v_mul_f32_e32 v200, 0x3f317217, v184
	v_mul_f32_e32 v201, 0x3f317217, v185
	v_mul_f32_e32 v202, 0x3f317217, v186
	v_mul_f32_e32 v203, 0x3f317217, v187
	v_mul_f32_e32 v204, 0x3f317217, v188
	v_mul_f32_e32 v205, 0x3f317217, v189
	v_mul_f32_e32 v206, 0x3f317217, v190
	v_mul_f32_e32 v207, 0x3f317217, v191
	v_fma_f32 v200, v184, s13, -v200
	v_fma_f32 v201, v185, s13, -v201
	v_fma_f32 v202, v186, s13, -v202
	v_fma_f32 v203, v187, s13, -v203
	v_fma_f32 v204, v188, s13, -v204
	v_fma_f32 v205, v189, s13, -v205
	v_fma_f32 v206, v190, s13, -v206
	v_fma_f32 v207, v191, s13, -v207
	v_fmac_f32_e32 v200, 0x3377d1cf, v184
	v_fmac_f32_e32 v201, 0x3377d1cf, v185
	v_fmac_f32_e32 v202, 0x3377d1cf, v186
	v_fmac_f32_e32 v203, 0x3377d1cf, v187
	v_fmac_f32_e32 v204, 0x3377d1cf, v188
	v_fmac_f32_e32 v205, 0x3377d1cf, v189
	v_fmac_f32_e32 v206, 0x3377d1cf, v190
	v_fmac_f32_e32 v207, 0x3377d1cf, v191
	v_fmac_f32_e32 v200, 0x3f317217, v184
	v_fmac_f32_e32 v201, 0x3f317217, v185
	v_fmac_f32_e32 v202, 0x3f317217, v186
	v_fmac_f32_e32 v203, 0x3f317217, v187
	v_fmac_f32_e32 v204, 0x3f317217, v188
	v_fmac_f32_e32 v205, 0x3f317217, v189
	v_fmac_f32_e32 v206, 0x3f317217, v190
	v_fmac_f32_e32 v207, 0x3f317217, v191
	v_cmp_lt_f32_e64 vcc, |v184|, s36
	v_cmp_lt_f32_e64 s[38:39], |v185|, s36
	v_cmp_lt_f32_e64 s[48:49], |v186|, s36
	v_cmp_lt_f32_e64 s[50:51], |v187|, s36
	v_cndmask_b32_e64 v184, v184, v200, vcc
	v_cndmask_b32_e64 v185, v185, v201, s[38:39]
	v_cndmask_b32_e64 v186, v186, v202, s[48:49]
	v_cndmask_b32_e64 v187, v187, v203, s[50:51]
	v_cmp_lt_f32_e64 vcc, |v188|, s36
	v_cmp_lt_f32_e64 s[38:39], |v189|, s36
	v_cmp_lt_f32_e64 s[48:49], |v190|, s36
	v_cmp_lt_f32_e64 s[50:51], |v191|, s36
	v_cndmask_b32_e64 v188, v188, v204, vcc
	v_cndmask_b32_e64 v189, v189, v205, s[38:39]
	v_cndmask_b32_e64 v190, v190, v206, s[48:49]
	v_cndmask_b32_e64 v191, v191, v207, s[50:51]
	v_sub_f32_e32 v100, v184, v192
	v_sub_f32_e32 v101, v185, v193
	v_sub_f32_e32 v102, v186, v194
	v_sub_f32_e32 v103, v187, v195
	v_sub_f32_e32 v96, v188, v196
	v_sub_f32_e32 v97, v189, v197
	v_sub_f32_e32 v98, v190, v198
	v_sub_f32_e32 v99, v191, v199
	v_cvt_pk_bf16_f32 v100, v100, v101
	v_cvt_pk_bf16_f32 v101, v102, v103
	v_cvt_pk_bf16_f32 v102, v96, v97
	v_cvt_pk_bf16_f32 v103, v98, v99
	global_store_dwordx4 v[176:177], v[100:103], off offset:256
	v_lshl_add_u64 v[162:163], v[176:177], 0, s[46:47]
	v_pk_mul_f32 v[92:93], v[92:93], v[144:145] op_sel_hi:[1,0]
	v_pk_mul_f32 v[94:95], v[94:95], v[144:145] op_sel_hi:[1,0]
	v_pk_mul_f32 v[88:89], v[88:89], v[144:145] op_sel_hi:[1,0]
	v_pk_mul_f32 v[90:91], v[90:91], v[144:145] op_sel_hi:[1,0]
	v_mul_f32_e32 v184, 0xbfb8aa3b, v92
	v_mul_f32_e32 v185, 0xbfb8aa3b, v93
	v_mul_f32_e32 v186, 0xbfb8aa3b, v94
	v_mul_f32_e32 v187, 0xbfb8aa3b, v95
	v_mul_f32_e32 v188, 0xbfb8aa3b, v88
	v_mul_f32_e32 v189, 0xbfb8aa3b, v89
	v_mul_f32_e32 v190, 0xbfb8aa3b, v90
	v_mul_f32_e32 v191, 0xbfb8aa3b, v91
	v_exp_f32_e32 v184, v184
	v_exp_f32_e32 v185, v185
	v_exp_f32_e32 v186, v186
	v_exp_f32_e32 v187, v187
	v_exp_f32_e32 v188, v188
	v_exp_f32_e32 v189, v189
	v_exp_f32_e32 v190, v190
	v_exp_f32_e32 v191, v191
	v_sub_f32_e32 v192, 1.0, v152
	v_sub_f32_e32 v193, 1.0, v153
	v_sub_f32_e32 v194, 1.0, v154
	v_sub_f32_e32 v195, 1.0, v155
	v_sub_f32_e32 v196, 1.0, v180
	v_sub_f32_e32 v197, 1.0, v181
	v_sub_f32_e32 v198, 1.0, v182
	v_sub_f32_e32 v199, 1.0, v183
	v_add_f32_e32 v184, 1.0, v184
	v_add_f32_e32 v185, 1.0, v185
	v_add_f32_e32 v186, 1.0, v186
	v_add_f32_e32 v187, 1.0, v187
	v_add_f32_e32 v188, 1.0, v188
	v_add_f32_e32 v189, 1.0, v189
	v_add_f32_e32 v190, 1.0, v190
	v_add_f32_e32 v191, 1.0, v191
	v_rcp_f32_e32 v184, v184
	v_rcp_f32_e32 v185, v185
	v_rcp_f32_e32 v186, v186
	v_rcp_f32_e32 v187, v187
	v_rcp_f32_e32 v188, v188
	v_rcp_f32_e32 v189, v189
	v_rcp_f32_e32 v190, v190
	v_rcp_f32_e32 v191, v191
	v_fma_f32 v200, v184, v192, v152
	v_fma_f32 v201, v185, v193, v153
	v_fma_f32 v202, v186, v194, v154
	v_fma_f32 v203, v187, v195, v155
	v_fma_f32 v204, v188, v196, v180
	v_fma_f32 v205, v189, v197, v181
	v_fma_f32 v206, v190, v198, v182
	v_fma_f32 v207, v191, v199, v183
	v_cmp_gt_f32_e64 vcc, s35, v200
	v_cmp_gt_f32_e64 s[38:39], s35, v201
	v_cmp_gt_f32_e64 s[48:49], s35, v202
	v_cmp_gt_f32_e64 s[50:51], s35, v203
	v_cndmask_b32_e64 v184, 0, 32, vcc
	v_cndmask_b32_e64 v185, 0, 32, s[38:39]
	v_cndmask_b32_e64 v186, 0, 32, s[48:49]
	v_cndmask_b32_e64 v187, 0, 32, s[50:51]
	v_cndmask_b32_e64 v192, 0, v214, vcc
	v_cndmask_b32_e64 v193, 0, v214, s[38:39]
	v_cndmask_b32_e64 v194, 0, v214, s[48:49]
	v_cndmask_b32_e64 v195, 0, v214, s[50:51]
	v_cmp_gt_f32_e64 vcc, s35, v204
	v_cmp_gt_f32_e64 s[38:39], s35, v205
	v_cmp_gt_f32_e64 s[48:49], s35, v206
	v_cmp_gt_f32_e64 s[50:51], s35, v207
	v_cndmask_b32_e64 v188, 0, 32, vcc
	v_cndmask_b32_e64 v189, 0, 32, s[38:39]
	v_cndmask_b32_e64 v190, 0, 32, s[48:49]
	v_cndmask_b32_e64 v191, 0, 32, s[50:51]
	v_cndmask_b32_e64 v196, 0, v214, vcc
	v_cndmask_b32_e64 v197, 0, v214, s[38:39]
	v_cndmask_b32_e64 v198, 0, v214, s[48:49]
; __device__ __forceinline__ unsigned cvt_pk_bf16(float lo, float hi) { unsigned r; asm volatile("v_cvt_pk_bf16_f32 %0, %1, %2" : "=v"(r) : "v"(lo), "v"(hi)); return r; }
; __device__ __forceinline__ float silu_f(float v) { return v * __builtin_amdgcn_rcpf(1.f + __expf(-v)); }
;     __device__ __forceinline__ void operator()(const f32x4 (&acc)[2][2][4][2], const Unit& u, int wr, int wc, int fr, int fq, int ui, PG8_LAS unsigned char* lds) const {
;     ...
;                     f32x4 v[2] = {acc[ai][bj][m][0] * rs, acc[ai][bj][m][1] * rs};
;                     if (ksum) { csum[bj][0] += v[0]; csum[bj][1] += v[1]; }
; #pragma unroll
;                     for (int n = 0; n < 2; ++n) {
;                         f32x4 lbv = (f32x4){0.f, 0.f, 0.f, 0.f};
;                         if (act == 2) lbv = *(const f32x4*)(lb + (col0 - 1024) + bj * HALF + 4 * n);
; #pragma unroll
;                         for (int e = 0; e < 4; ++e) {
;                             float x = v[n][e];
;                             if (act == 1) x = silu_f(x);
;                             else if (act == 2) { const float l = lbv[e]; x = __logf(l + (1.f - l) * __builtin_amdgcn_rcpf(1.f + __expf(-x))); }
;                             else if (act == 3) { x = fmaxf(x, 0.f); x = x * x; }
;                             v[n][e] = x;
;                         }
;                     }
;                     u32x4 w; w.x = cvt_pk_bf16(v[0][0], v[0][1]); w.y = cvt_pk_bf16(v[0][2], v[0][3]); w.z = cvt_pk_bf16(v[1][0], v[1][1]); w.w = cvt_pk_bf16(v[1][2], v[1][3]);
;                     *(u32x4*)(rowp + bj * HALF) = w;
	v_cndmask_b32_e64 v199, 0, v214, s[50:51]
	v_ldexp_f32 v184, v200, v184
	v_ldexp_f32 v185, v201, v185
	v_ldexp_f32 v186, v202, v186
	v_ldexp_f32 v187, v203, v187
	v_ldexp_f32 v188, v204, v188
	v_ldexp_f32 v189, v205, v189
	v_ldexp_f32 v190, v206, v190
	v_ldexp_f32 v191, v207, v191
	v_log_f32_e32 v184, v184
	v_log_f32_e32 v185, v185
	v_log_f32_e32 v186, v186
	v_log_f32_e32 v187, v187
	v_log_f32_e32 v188, v188
	v_log_f32_e32 v189, v189
	v_log_f32_e32 v190, v190
	v_log_f32_e32 v191, v191
	v_mul_f32_e32 v200, 0x3f317217, v184
	v_mul_f32_e32 v201, 0x3f317217, v185
	v_mul_f32_e32 v202, 0x3f317217, v186
	v_mul_f32_e32 v203, 0x3f317217, v187
	v_mul_f32_e32 v204, 0x3f317217, v188
	v_mul_f32_e32 v205, 0x3f317217, v189
	v_mul_f32_e32 v206, 0x3f317217, v190
	v_mul_f32_e32 v207, 0x3f317217, v191
	v_fma_f32 v200, v184, s13, -v200
	v_fma_f32 v201, v185, s13, -v201
	v_fma_f32 v202, v186, s13, -v202
	v_fma_f32 v203, v187, s13, -v203
	v_fma_f32 v204, v188, s13, -v204
	v_fma_f32 v205, v189, s13, -v205
	v_fma_f32 v206, v190, s13, -v206
	v_fma_f32 v207, v191, s13, -v207
	v_fmac_f32_e32 v200, 0x3377d1cf, v184
	v_fmac_f32_e32 v201, 0x3377d1cf, v185
	v_fmac_f32_e32 v202, 0x3377d1cf, v186
	v_fmac_f32_e32 v203, 0x3377d1cf, v187
	v_fmac_f32_e32 v204, 0x3377d1cf, v188
	v_fmac_f32_e32 v205, 0x3377d1cf, v189
	v_fmac_f32_e32 v206, 0x3377d1cf, v190
	v_fmac_f32_e32 v207, 0x3377d1cf, v191
	v_fmac_f32_e32 v200, 0x3f317217, v184
	v_fmac_f32_e32 v201, 0x3f317217, v185
	v_fmac_f32_e32 v202, 0x3f317217, v186
	v_fmac_f32_e32 v203, 0x3f317217, v187
	v_fmac_f32_e32 v204, 0x3f317217, v188
	v_fmac_f32_e32 v205, 0x3f317217, v189
	v_fmac_f32_e32 v206, 0x3f317217, v190
	v_fmac_f32_e32 v207, 0x3f317217, v191
	v_cmp_lt_f32_e64 vcc, |v184|, s36
	v_cmp_lt_f32_e64 s[38:39], |v185|, s36
	v_cmp_lt_f32_e64 s[48:49], |v186|, s36
	v_cmp_lt_f32_e64 s[50:51], |v187|, s36
	v_cndmask_b32_e64 v184, v184, v200, vcc
	v_cndmask_b32_e64 v185, v185, v201, s[38:39]
	v_cndmask_b32_e64 v186, v186, v202, s[48:49]
	v_cndmask_b32_e64 v187, v187, v203, s[50:51]
	v_cmp_lt_f32_e64 vcc, |v188|, s36
	v_cmp_lt_f32_e64 s[38:39], |v189|, s36
	v_cmp_lt_f32_e64 s[48:49], |v190|, s36
	v_cmp_lt_f32_e64 s[50:51], |v191|, s36
	v_cndmask_b32_e64 v188, v188, v204, vcc
	v_cndmask_b32_e64 v189, v189, v205, s[38:39]
	v_cndmask_b32_e64 v190, v190, v206, s[48:49]
	v_cndmask_b32_e64 v191, v191, v207, s[50:51]
	v_sub_f32_e32 v92, v184, v192
	v_sub_f32_e32 v93, v185, v193
	v_sub_f32_e32 v94, v186, v194
	v_sub_f32_e32 v95, v187, v195
	v_sub_f32_e32 v88, v188, v196
	v_sub_f32_e32 v89, v189, v197
	v_sub_f32_e32 v90, v190, v198
	v_sub_f32_e32 v91, v191, v199
	v_cvt_pk_bf16_f32 v92, v92, v93
	v_cvt_pk_bf16_f32 v93, v94, v95
	v_cvt_pk_bf16_f32 v94, v88, v89
	v_cvt_pk_bf16_f32 v95, v90, v91
	global_store_dwordx4 v[162:163], v[92:95], off
	v_pk_mul_f32 v[84:85], v[84:85], v[144:145] op_sel_hi:[1,0]
	v_pk_mul_f32 v[86:87], v[86:87], v[144:145] op_sel_hi:[1,0]
	v_pk_mul_f32 v[80:81], v[80:81], v[144:145] op_sel_hi:[1,0]
	v_pk_mul_f32 v[82:83], v[82:83], v[144:145] op_sel_hi:[1,0]
	v_mul_f32_e32 v184, 0xbfb8aa3b, v84
	v_mul_f32_e32 v185, 0xbfb8aa3b, v85
	v_mul_f32_e32 v186, 0xbfb8aa3b, v86
	v_mul_f32_e32 v187, 0xbfb8aa3b, v87
	v_mul_f32_e32 v188, 0xbfb8aa3b, v80
	v_mul_f32_e32 v189, 0xbfb8aa3b, v81
	v_mul_f32_e32 v190, 0xbfb8aa3b, v82
	v_mul_f32_e32 v191, 0xbfb8aa3b, v83
	v_exp_f32_e32 v184, v184
	v_exp_f32_e32 v185, v185
	v_exp_f32_e32 v186, v186
	v_exp_f32_e32 v187, v187
	v_exp_f32_e32 v188, v188
	v_exp_f32_e32 v189, v189
	v_exp_f32_e32 v190, v190
	v_exp_f32_e32 v191, v191
	v_sub_f32_e32 v192, 1.0, v218
	v_sub_f32_e32 v193, 1.0, v219
	v_sub_f32_e32 v194, 1.0, v220
	v_sub_f32_e32 v195, 1.0, v221
	v_sub_f32_e32 v196, 1.0, v222
	v_sub_f32_e32 v197, 1.0, v223
	v_sub_f32_e32 v198, 1.0, v224
	v_sub_f32_e32 v199, 1.0, v225
	v_add_f32_e32 v184, 1.0, v184
	v_add_f32_e32 v185, 1.0, v185
	v_add_f32_e32 v186, 1.0, v186
	v_add_f32_e32 v187, 1.0, v187
	v_add_f32_e32 v188, 1.0, v188
	v_add_f32_e32 v189, 1.0, v189
	v_add_f32_e32 v190, 1.0, v190
	v_add_f32_e32 v191, 1.0, v191
	v_rcp_f32_e32 v184, v184
	v_rcp_f32_e32 v185, v185
	v_rcp_f32_e32 v186, v186
	v_rcp_f32_e32 v187, v187
	v_rcp_f32_e32 v188, v188
	v_rcp_f32_e32 v189, v189
	v_rcp_f32_e32 v190, v190
	v_rcp_f32_e32 v191, v191
	v_fma_f32 v200, v184, v192, v218
	v_fma_f32 v201, v185, v193, v219
	v_fma_f32 v202, v186, v194, v220
	v_fma_f32 v203, v187, v195, v221
	v_fma_f32 v204, v188, v196, v222
	v_fma_f32 v205, v189, v197, v223
	v_fma_f32 v206, v190, v198, v224
	v_fma_f32 v207, v191, v199, v225
	v_cmp_gt_f32_e64 vcc, s35, v200
	v_cmp_gt_f32_e64 s[38:39], s35, v201
	v_cmp_gt_f32_e64 s[48:49], s35, v202
	v_cmp_gt_f32_e64 s[50:51], s35, v203
	v_cndmask_b32_e64 v184, 0, 32, vcc
	v_cndmask_b32_e64 v185, 0, 32, s[38:39]
	v_cndmask_b32_e64 v186, 0, 32, s[48:49]
	v_cndmask_b32_e64 v187, 0, 32, s[50:51]
	v_cndmask_b32_e64 v192, 0, v214, vcc
	v_cndmask_b32_e64 v193, 0, v214, s[38:39]
	v_cndmask_b32_e64 v194, 0, v214, s[48:49]
	v_cndmask_b32_e64 v195, 0, v214, s[50:51]
	v_cmp_gt_f32_e64 vcc, s35, v204
	v_cmp_gt_f32_e64 s[38:39], s35, v205
	v_cmp_gt_f32_e64 s[48:49], s35, v206
	v_cmp_gt_f32_e64 s[50:51], s35, v207
	v_cndmask_b32_e64 v188, 0, 32, vcc
	v_cndmask_b32_e64 v189, 0, 32, s[38:39]
	v_cndmask_b32_e64 v190, 0, 32, s[48:49]
	v_cndmask_b32_e64 v191, 0, 32, s[50:51]
	v_cndmask_b32_e64 v196, 0, v214, vcc
	v_cndmask_b32_e64 v197, 0, v214, s[38:39]
	v_cndmask_b32_e64 v198, 0, v214, s[48:49]
	v_cndmask_b32_e64 v199, 0, v214, s[50:51]
	v_ldexp_f32 v184, v200, v184
	v_ldexp_f32 v185, v201, v185
	v_ldexp_f32 v186, v202, v186
	v_ldexp_f32 v187, v203, v187
	v_ldexp_f32 v188, v204, v188
	v_ldexp_f32 v189, v205, v189
; __device__ __forceinline__ unsigned cvt_pk_bf16(float lo, float hi) { unsigned r; asm volatile("v_cvt_pk_bf16_f32 %0, %1, %2" : "=v"(r) : "v"(lo), "v"(hi)); return r; }
; __device__ __forceinline__ float silu_f(float v) { return v * __builtin_amdgcn_rcpf(1.f + __expf(-v)); }
;     __device__ __forceinline__ void operator()(const f32x4 (&acc)[2][2][4][2], const Unit& u, int wr, int wc, int fr, int fq, int ui, PG8_LAS unsigned char* lds) const {
;     ...
;                     f32x4 v[2] = {acc[ai][bj][m][0] * rs, acc[ai][bj][m][1] * rs};
;                     if (ksum) { csum[bj][0] += v[0]; csum[bj][1] += v[1]; }
; #pragma unroll
;                     for (int n = 0; n < 2; ++n) {
;                         f32x4 lbv = (f32x4){0.f, 0.f, 0.f, 0.f};
;                         if (act == 2) lbv = *(const f32x4*)(lb + (col0 - 1024) + bj * HALF + 4 * n);
; #pragma unroll
;                         for (int e = 0; e < 4; ++e) {
;                             float x = v[n][e];
;                             if (act == 1) x = silu_f(x);
;                             else if (act == 2) { const float l = lbv[e]; x = __logf(l + (1.f - l) * __builtin_amdgcn_rcpf(1.f + __expf(-x))); }
;                             else if (act == 3) { x = fmaxf(x, 0.f); x = x * x; }
;                             v[n][e] = x;
;                         }
;                     }
;                     u32x4 w; w.x = cvt_pk_bf16(v[0][0], v[0][1]); w.y = cvt_pk_bf16(v[0][2], v[0][3]); w.z = cvt_pk_bf16(v[1][0], v[1][1]); w.w = cvt_pk_bf16(v[1][2], v[1][3]);
;                     *(u32x4*)(rowp + bj * HALF) = w;
	v_ldexp_f32 v190, v206, v190
	v_ldexp_f32 v191, v207, v191
	v_log_f32_e32 v184, v184
	v_log_f32_e32 v185, v185
	v_log_f32_e32 v186, v186
	v_log_f32_e32 v187, v187
	v_log_f32_e32 v188, v188
	v_log_f32_e32 v189, v189
	v_log_f32_e32 v190, v190
	v_log_f32_e32 v191, v191
	v_mul_f32_e32 v200, 0x3f317217, v184
	v_mul_f32_e32 v201, 0x3f317217, v185
	v_mul_f32_e32 v202, 0x3f317217, v186
	v_mul_f32_e32 v203, 0x3f317217, v187
	v_mul_f32_e32 v204, 0x3f317217, v188
	v_mul_f32_e32 v205, 0x3f317217, v189
	v_mul_f32_e32 v206, 0x3f317217, v190
	v_mul_f32_e32 v207, 0x3f317217, v191
	v_fma_f32 v200, v184, s13, -v200
	v_fma_f32 v201, v185, s13, -v201
	v_fma_f32 v202, v186, s13, -v202
	v_fma_f32 v203, v187, s13, -v203
	v_fma_f32 v204, v188, s13, -v204
	v_fma_f32 v205, v189, s13, -v205
	v_fma_f32 v206, v190, s13, -v206
	v_fma_f32 v207, v191, s13, -v207
	v_fmac_f32_e32 v200, 0x3377d1cf, v184
	v_fmac_f32_e32 v201, 0x3377d1cf, v185
	v_fmac_f32_e32 v202, 0x3377d1cf, v186
	v_fmac_f32_e32 v203, 0x3377d1cf, v187
	v_fmac_f32_e32 v204, 0x3377d1cf, v188
	v_fmac_f32_e32 v205, 0x3377d1cf, v189
	v_fmac_f32_e32 v206, 0x3377d1cf, v190
	v_fmac_f32_e32 v207, 0x3377d1cf, v191
	v_fmac_f32_e32 v200, 0x3f317217, v184
	v_fmac_f32_e32 v201, 0x3f317217, v185
	v_fmac_f32_e32 v202, 0x3f317217, v186
	v_fmac_f32_e32 v203, 0x3f317217, v187
	v_fmac_f32_e32 v204, 0x3f317217, v188
	v_fmac_f32_e32 v205, 0x3f317217, v189
	v_fmac_f32_e32 v206, 0x3f317217, v190
	v_fmac_f32_e32 v207, 0x3f317217, v191
	v_cmp_lt_f32_e64 vcc, |v184|, s36
	v_cmp_lt_f32_e64 s[38:39], |v185|, s36
	v_cmp_lt_f32_e64 s[48:49], |v186|, s36
	v_cmp_lt_f32_e64 s[50:51], |v187|, s36
	v_cndmask_b32_e64 v184, v184, v200, vcc
	v_cndmask_b32_e64 v185, v185, v201, s[38:39]
	v_cndmask_b32_e64 v186, v186, v202, s[48:49]
	v_cndmask_b32_e64 v187, v187, v203, s[50:51]
	v_cmp_lt_f32_e64 vcc, |v188|, s36
	v_cmp_lt_f32_e64 s[38:39], |v189|, s36
	v_cmp_lt_f32_e64 s[48:49], |v190|, s36
	v_cmp_lt_f32_e64 s[50:51], |v191|, s36
	v_cndmask_b32_e64 v188, v188, v204, vcc
	v_cndmask_b32_e64 v189, v189, v205, s[38:39]
	v_cndmask_b32_e64 v190, v190, v206, s[48:49]
	v_cndmask_b32_e64 v191, v191, v207, s[50:51]
	v_sub_f32_e32 v84, v184, v192
	v_sub_f32_e32 v85, v185, v193
	v_sub_f32_e32 v86, v186, v194
	v_sub_f32_e32 v87, v187, v195
	v_sub_f32_e32 v80, v188, v196
	v_sub_f32_e32 v81, v189, v197
	v_sub_f32_e32 v82, v190, v198
	v_sub_f32_e32 v83, v191, v199
	v_cvt_pk_bf16_f32 v84, v84, v85
	v_cvt_pk_bf16_f32 v85, v86, v87
	v_cvt_pk_bf16_f32 v86, v80, v81
	v_cvt_pk_bf16_f32 v87, v82, v83
	global_store_dwordx4 v[162:163], v[84:87], off offset:256
	v_lshl_add_u64 v[176:177], v[162:163], 0, s[46:47]
	v_pk_mul_f32 v[76:77], v[76:77], v[146:147] op_sel_hi:[1,0]
	v_pk_mul_f32 v[78:79], v[78:79], v[146:147] op_sel_hi:[1,0]
	v_pk_mul_f32 v[72:73], v[72:73], v[146:147] op_sel_hi:[1,0]
	v_pk_mul_f32 v[74:75], v[74:75], v[146:147] op_sel_hi:[1,0]
	v_mul_f32_e32 v184, 0xbfb8aa3b, v76
	v_mul_f32_e32 v185, 0xbfb8aa3b, v77
	v_mul_f32_e32 v186, 0xbfb8aa3b, v78
	v_mul_f32_e32 v187, 0xbfb8aa3b, v79
	v_mul_f32_e32 v188, 0xbfb8aa3b, v72
	v_mul_f32_e32 v189, 0xbfb8aa3b, v73
	v_mul_f32_e32 v190, 0xbfb8aa3b, v74
	v_mul_f32_e32 v191, 0xbfb8aa3b, v75
	v_exp_f32_e32 v184, v184
	v_exp_f32_e32 v185, v185
	v_exp_f32_e32 v186, v186
	v_exp_f32_e32 v187, v187
	v_exp_f32_e32 v188, v188
	v_exp_f32_e32 v189, v189
	v_exp_f32_e32 v190, v190
	v_exp_f32_e32 v191, v191
	v_sub_f32_e32 v192, 1.0, v152
	v_sub_f32_e32 v193, 1.0, v153
	v_sub_f32_e32 v194, 1.0, v154
	v_sub_f32_e32 v195, 1.0, v155
	v_sub_f32_e32 v196, 1.0, v180
	v_sub_f32_e32 v197, 1.0, v181
	v_sub_f32_e32 v198, 1.0, v182
	v_sub_f32_e32 v199, 1.0, v183
	v_add_f32_e32 v184, 1.0, v184
	v_add_f32_e32 v185, 1.0, v185
	v_add_f32_e32 v186, 1.0, v186
	v_add_f32_e32 v187, 1.0, v187
	v_add_f32_e32 v188, 1.0, v188
	v_add_f32_e32 v189, 1.0, v189
	v_add_f32_e32 v190, 1.0, v190
	v_add_f32_e32 v191, 1.0, v191
	v_rcp_f32_e32 v184, v184
	v_rcp_f32_e32 v185, v185
	v_rcp_f32_e32 v186, v186
	v_rcp_f32_e32 v187, v187
	v_rcp_f32_e32 v188, v188
	v_rcp_f32_e32 v189, v189
	v_rcp_f32_e32 v190, v190
	v_rcp_f32_e32 v191, v191
	v_fma_f32 v200, v184, v192, v152
	v_fma_f32 v201, v185, v193, v153
	v_fma_f32 v202, v186, v194, v154
	v_fma_f32 v203, v187, v195, v155
	v_fma_f32 v204, v188, v196, v180
	v_fma_f32 v205, v189, v197, v181
	v_fma_f32 v206, v190, v198, v182
	v_fma_f32 v207, v191, v199, v183
	v_cmp_gt_f32_e64 vcc, s35, v200
	v_cmp_gt_f32_e64 s[38:39], s35, v201
	v_cmp_gt_f32_e64 s[48:49], s35, v202
	v_cmp_gt_f32_e64 s[50:51], s35, v203
	v_cndmask_b32_e64 v184, 0, 32, vcc
	v_cndmask_b32_e64 v185, 0, 32, s[38:39]
	v_cndmask_b32_e64 v186, 0, 32, s[48:49]
	v_cndmask_b32_e64 v187, 0, 32, s[50:51]
	v_cndmask_b32_e64 v192, 0, v214, vcc
	v_cndmask_b32_e64 v193, 0, v214, s[38:39]
	v_cndmask_b32_e64 v194, 0, v214, s[48:49]
	v_cndmask_b32_e64 v195, 0, v214, s[50:51]
	v_cmp_gt_f32_e64 vcc, s35, v204
	v_cmp_gt_f32_e64 s[38:39], s35, v205
	v_cmp_gt_f32_e64 s[48:49], s35, v206
	v_cmp_gt_f32_e64 s[50:51], s35, v207
	v_cndmask_b32_e64 v188, 0, 32, vcc
	v_cndmask_b32_e64 v189, 0, 32, s[38:39]
	v_cndmask_b32_e64 v190, 0, 32, s[48:49]
	v_cndmask_b32_e64 v191, 0, 32, s[50:51]
	v_cndmask_b32_e64 v196, 0, v214, vcc
	v_cndmask_b32_e64 v197, 0, v214, s[38:39]
	v_cndmask_b32_e64 v198, 0, v214, s[48:49]
	v_cndmask_b32_e64 v199, 0, v214, s[50:51]
	v_ldexp_f32 v184, v200, v184
	v_ldexp_f32 v185, v201, v185
	v_ldexp_f32 v186, v202, v186
	v_ldexp_f32 v187, v203, v187
	v_ldexp_f32 v188, v204, v188
	v_ldexp_f32 v189, v205, v189
	v_ldexp_f32 v190, v206, v190
	v_ldexp_f32 v191, v207, v191
	v_log_f32_e32 v184, v184
	v_log_f32_e32 v185, v185
	v_log_f32_e32 v186, v186
	v_log_f32_e32 v187, v187
; __device__ __forceinline__ unsigned cvt_pk_bf16(float lo, float hi) { unsigned r; asm volatile("v_cvt_pk_bf16_f32 %0, %1, %2" : "=v"(r) : "v"(lo), "v"(hi)); return r; }
; __device__ __forceinline__ float silu_f(float v) { return v * __builtin_amdgcn_rcpf(1.f + __expf(-v)); }
;     __device__ __forceinline__ void operator()(const f32x4 (&acc)[2][2][4][2], const Unit& u, int wr, int wc, int fr, int fq, int ui, PG8_LAS unsigned char* lds) const {
;     ...
;                     f32x4 v[2] = {acc[ai][bj][m][0] * rs, acc[ai][bj][m][1] * rs};
;                     if (ksum) { csum[bj][0] += v[0]; csum[bj][1] += v[1]; }
; #pragma unroll
;                     for (int n = 0; n < 2; ++n) {
;                         f32x4 lbv = (f32x4){0.f, 0.f, 0.f, 0.f};
;                         if (act == 2) lbv = *(const f32x4*)(lb + (col0 - 1024) + bj * HALF + 4 * n);
; #pragma unroll
;                         for (int e = 0; e < 4; ++e) {
;                             float x = v[n][e];
;                             if (act == 1) x = silu_f(x);
;                             else if (act == 2) { const float l = lbv[e]; x = __logf(l + (1.f - l) * __builtin_amdgcn_rcpf(1.f + __expf(-x))); }
;                             else if (act == 3) { x = fmaxf(x, 0.f); x = x * x; }
;                             v[n][e] = x;
;                         }
;                     }
;                     u32x4 w; w.x = cvt_pk_bf16(v[0][0], v[0][1]); w.y = cvt_pk_bf16(v[0][2], v[0][3]); w.z = cvt_pk_bf16(v[1][0], v[1][1]); w.w = cvt_pk_bf16(v[1][2], v[1][3]);
;                     *(u32x4*)(rowp + bj * HALF) = w;
	v_log_f32_e32 v188, v188
	v_log_f32_e32 v189, v189
	v_log_f32_e32 v190, v190
	v_log_f32_e32 v191, v191
	v_mul_f32_e32 v200, 0x3f317217, v184
	v_mul_f32_e32 v201, 0x3f317217, v185
	v_mul_f32_e32 v202, 0x3f317217, v186
	v_mul_f32_e32 v203, 0x3f317217, v187
	v_mul_f32_e32 v204, 0x3f317217, v188
	v_mul_f32_e32 v205, 0x3f317217, v189
	v_mul_f32_e32 v206, 0x3f317217, v190
	v_mul_f32_e32 v207, 0x3f317217, v191
	v_fma_f32 v200, v184, s13, -v200
	v_fma_f32 v201, v185, s13, -v201
	v_fma_f32 v202, v186, s13, -v202
	v_fma_f32 v203, v187, s13, -v203
	v_fma_f32 v204, v188, s13, -v204
	v_fma_f32 v205, v189, s13, -v205
	v_fma_f32 v206, v190, s13, -v206
	v_fma_f32 v207, v191, s13, -v207
	v_fmac_f32_e32 v200, 0x3377d1cf, v184
	v_fmac_f32_e32 v201, 0x3377d1cf, v185
	v_fmac_f32_e32 v202, 0x3377d1cf, v186
	v_fmac_f32_e32 v203, 0x3377d1cf, v187
	v_fmac_f32_e32 v204, 0x3377d1cf, v188
	v_fmac_f32_e32 v205, 0x3377d1cf, v189
	v_fmac_f32_e32 v206, 0x3377d1cf, v190
	v_fmac_f32_e32 v207, 0x3377d1cf, v191
	v_fmac_f32_e32 v200, 0x3f317217, v184
	v_fmac_f32_e32 v201, 0x3f317217, v185
	v_fmac_f32_e32 v202, 0x3f317217, v186
	v_fmac_f32_e32 v203, 0x3f317217, v187
	v_fmac_f32_e32 v204, 0x3f317217, v188
	v_fmac_f32_e32 v205, 0x3f317217, v189
	v_fmac_f32_e32 v206, 0x3f317217, v190
	v_fmac_f32_e32 v207, 0x3f317217, v191
	v_cmp_lt_f32_e64 vcc, |v184|, s36
	v_cmp_lt_f32_e64 s[38:39], |v185|, s36
	v_cmp_lt_f32_e64 s[48:49], |v186|, s36
	v_cmp_lt_f32_e64 s[50:51], |v187|, s36
	v_cndmask_b32_e64 v184, v184, v200, vcc
	v_cndmask_b32_e64 v185, v185, v201, s[38:39]
	v_cndmask_b32_e64 v186, v186, v202, s[48:49]
	v_cndmask_b32_e64 v187, v187, v203, s[50:51]
	v_cmp_lt_f32_e64 vcc, |v188|, s36
	v_cmp_lt_f32_e64 s[38:39], |v189|, s36
	v_cmp_lt_f32_e64 s[48:49], |v190|, s36
	v_cmp_lt_f32_e64 s[50:51], |v191|, s36
	v_cndmask_b32_e64 v188, v188, v204, vcc
	v_cndmask_b32_e64 v189, v189, v205, s[38:39]
	v_cndmask_b32_e64 v190, v190, v206, s[48:49]
	v_cndmask_b32_e64 v191, v191, v207, s[50:51]
	v_sub_f32_e32 v76, v184, v192
	v_sub_f32_e32 v77, v185, v193
	v_sub_f32_e32 v78, v186, v194
	v_sub_f32_e32 v79, v187, v195
	v_sub_f32_e32 v72, v188, v196
	v_sub_f32_e32 v73, v189, v197
	v_sub_f32_e32 v74, v190, v198
	v_sub_f32_e32 v75, v191, v199
	v_cvt_pk_bf16_f32 v76, v76, v77
	v_cvt_pk_bf16_f32 v77, v78, v79
	v_cvt_pk_bf16_f32 v78, v72, v73
	v_cvt_pk_bf16_f32 v79, v74, v75
	global_store_dwordx4 v[176:177], v[76:79], off
	v_pk_mul_f32 v[68:69], v[68:69], v[146:147] op_sel_hi:[1,0]
	v_pk_mul_f32 v[70:71], v[70:71], v[146:147] op_sel_hi:[1,0]
	v_pk_mul_f32 v[64:65], v[64:65], v[146:147] op_sel_hi:[1,0]
	v_pk_mul_f32 v[66:67], v[66:67], v[146:147] op_sel_hi:[1,0]
	v_mul_f32_e32 v184, 0xbfb8aa3b, v68
	v_mul_f32_e32 v185, 0xbfb8aa3b, v69
	v_mul_f32_e32 v186, 0xbfb8aa3b, v70
	v_mul_f32_e32 v187, 0xbfb8aa3b, v71
	v_mul_f32_e32 v188, 0xbfb8aa3b, v64
	v_mul_f32_e32 v189, 0xbfb8aa3b, v65
	v_mul_f32_e32 v190, 0xbfb8aa3b, v66
	v_mul_f32_e32 v191, 0xbfb8aa3b, v67
	v_exp_f32_e32 v184, v184
	v_exp_f32_e32 v185, v185
	v_exp_f32_e32 v186, v186
	v_exp_f32_e32 v187, v187
	v_exp_f32_e32 v188, v188
	v_exp_f32_e32 v189, v189
	v_exp_f32_e32 v190, v190
	v_exp_f32_e32 v191, v191
	v_sub_f32_e32 v192, 1.0, v218
	v_sub_f32_e32 v193, 1.0, v219
	v_sub_f32_e32 v194, 1.0, v220
	v_sub_f32_e32 v195, 1.0, v221
	v_sub_f32_e32 v196, 1.0, v222
	v_sub_f32_e32 v197, 1.0, v223
	v_sub_f32_e32 v198, 1.0, v224
	v_sub_f32_e32 v199, 1.0, v225
	v_add_f32_e32 v184, 1.0, v184
	v_add_f32_e32 v185, 1.0, v185
	v_add_f32_e32 v186, 1.0, v186
	v_add_f32_e32 v187, 1.0, v187
	v_add_f32_e32 v188, 1.0, v188
	v_add_f32_e32 v189, 1.0, v189
	v_add_f32_e32 v190, 1.0, v190
	v_add_f32_e32 v191, 1.0, v191
	v_rcp_f32_e32 v184, v184
	v_rcp_f32_e32 v185, v185
	v_rcp_f32_e32 v186, v186
	v_rcp_f32_e32 v187, v187
	v_rcp_f32_e32 v188, v188
	v_rcp_f32_e32 v189, v189
	v_rcp_f32_e32 v190, v190
	v_rcp_f32_e32 v191, v191
	v_fma_f32 v200, v184, v192, v218
	v_fma_f32 v201, v185, v193, v219
	v_fma_f32 v202, v186, v194, v220
	v_fma_f32 v203, v187, v195, v221
	v_fma_f32 v204, v188, v196, v222
	v_fma_f32 v205, v189, v197, v223
	v_fma_f32 v206, v190, v198, v224
	v_fma_f32 v207, v191, v199, v225
	v_cmp_gt_f32_e64 vcc, s35, v200
	v_cmp_gt_f32_e64 s[38:39], s35, v201
	v_cmp_gt_f32_e64 s[48:49], s35, v202
	v_cmp_gt_f32_e64 s[50:51], s35, v203
	v_cndmask_b32_e64 v184, 0, 32, vcc
	v_cndmask_b32_e64 v185, 0, 32, s[38:39]
	v_cndmask_b32_e64 v186, 0, 32, s[48:49]
	v_cndmask_b32_e64 v187, 0, 32, s[50:51]
	v_cndmask_b32_e64 v192, 0, v214, vcc
	v_cndmask_b32_e64 v193, 0, v214, s[38:39]
	v_cndmask_b32_e64 v194, 0, v214, s[48:49]
	v_cndmask_b32_e64 v195, 0, v214, s[50:51]
	v_cmp_gt_f32_e64 vcc, s35, v204
	v_cmp_gt_f32_e64 s[38:39], s35, v205
	v_cmp_gt_f32_e64 s[48:49], s35, v206
	v_cmp_gt_f32_e64 s[50:51], s35, v207
	v_cndmask_b32_e64 v188, 0, 32, vcc
	v_cndmask_b32_e64 v189, 0, 32, s[38:39]
	v_cndmask_b32_e64 v190, 0, 32, s[48:49]
	v_cndmask_b32_e64 v191, 0, 32, s[50:51]
	v_cndmask_b32_e64 v196, 0, v214, vcc
	v_cndmask_b32_e64 v197, 0, v214, s[38:39]
	v_cndmask_b32_e64 v198, 0, v214, s[48:49]
	v_cndmask_b32_e64 v199, 0, v214, s[50:51]
	v_ldexp_f32 v184, v200, v184
	v_ldexp_f32 v185, v201, v185
	v_ldexp_f32 v186, v202, v186
	v_ldexp_f32 v187, v203, v187
	v_ldexp_f32 v188, v204, v188
	v_ldexp_f32 v189, v205, v189
	v_ldexp_f32 v190, v206, v190
	v_ldexp_f32 v191, v207, v191
	v_log_f32_e32 v184, v184
	v_log_f32_e32 v185, v185
	v_log_f32_e32 v186, v186
	v_log_f32_e32 v187, v187
	v_log_f32_e32 v188, v188
	v_log_f32_e32 v189, v189
	v_log_f32_e32 v190, v190
	v_log_f32_e32 v191, v191
	v_mul_f32_e32 v200, 0x3f317217, v184
	v_mul_f32_e32 v201, 0x3f317217, v185
	v_mul_f32_e32 v202, 0x3f317217, v186
; __device__ __forceinline__ unsigned cvt_pk_bf16(float lo, float hi) { unsigned r; asm volatile("v_cvt_pk_bf16_f32 %0, %1, %2" : "=v"(r) : "v"(lo), "v"(hi)); return r; }
; __device__ __forceinline__ float silu_f(float v) { return v * __builtin_amdgcn_rcpf(1.f + __expf(-v)); }
;     __device__ __forceinline__ void operator()(const f32x4 (&acc)[2][2][4][2], const Unit& u, int wr, int wc, int fr, int fq, int ui, PG8_LAS unsigned char* lds) const {
;     ...
;                     f32x4 v[2] = {acc[ai][bj][m][0] * rs, acc[ai][bj][m][1] * rs};
;                     if (ksum) { csum[bj][0] += v[0]; csum[bj][1] += v[1]; }
; #pragma unroll
;                     for (int n = 0; n < 2; ++n) {
;                         f32x4 lbv = (f32x4){0.f, 0.f, 0.f, 0.f};
;                         if (act == 2) lbv = *(const f32x4*)(lb + (col0 - 1024) + bj * HALF + 4 * n);
; #pragma unroll
;                         for (int e = 0; e < 4; ++e) {
;                             float x = v[n][e];
;                             if (act == 1) x = silu_f(x);
;                             else if (act == 2) { const float l = lbv[e]; x = __logf(l + (1.f - l) * __builtin_amdgcn_rcpf(1.f + __expf(-x))); }
;                             else if (act == 3) { x = fmaxf(x, 0.f); x = x * x; }
;                             v[n][e] = x;
;                         }
;                     }
;                     u32x4 w; w.x = cvt_pk_bf16(v[0][0], v[0][1]); w.y = cvt_pk_bf16(v[0][2], v[0][3]); w.z = cvt_pk_bf16(v[1][0], v[1][1]); w.w = cvt_pk_bf16(v[1][2], v[1][3]);
;                     *(u32x4*)(rowp + bj * HALF) = w;
	v_mul_f32_e32 v203, 0x3f317217, v187
	v_mul_f32_e32 v204, 0x3f317217, v188
	v_mul_f32_e32 v205, 0x3f317217, v189
	v_mul_f32_e32 v206, 0x3f317217, v190
	v_mul_f32_e32 v207, 0x3f317217, v191
	v_fma_f32 v200, v184, s13, -v200
	v_fma_f32 v201, v185, s13, -v201
	v_fma_f32 v202, v186, s13, -v202
	v_fma_f32 v203, v187, s13, -v203
	v_fma_f32 v204, v188, s13, -v204
	v_fma_f32 v205, v189, s13, -v205
	v_fma_f32 v206, v190, s13, -v206
	v_fma_f32 v207, v191, s13, -v207
	v_fmac_f32_e32 v200, 0x3377d1cf, v184
	v_fmac_f32_e32 v201, 0x3377d1cf, v185
	v_fmac_f32_e32 v202, 0x3377d1cf, v186
	v_fmac_f32_e32 v203, 0x3377d1cf, v187
	v_fmac_f32_e32 v204, 0x3377d1cf, v188
	v_fmac_f32_e32 v205, 0x3377d1cf, v189
	v_fmac_f32_e32 v206, 0x3377d1cf, v190
	v_fmac_f32_e32 v207, 0x3377d1cf, v191
	v_fmac_f32_e32 v200, 0x3f317217, v184
	v_fmac_f32_e32 v201, 0x3f317217, v185
	v_fmac_f32_e32 v202, 0x3f317217, v186
	v_fmac_f32_e32 v203, 0x3f317217, v187
	v_fmac_f32_e32 v204, 0x3f317217, v188
	v_fmac_f32_e32 v205, 0x3f317217, v189
	v_fmac_f32_e32 v206, 0x3f317217, v190
	v_fmac_f32_e32 v207, 0x3f317217, v191
	v_cmp_lt_f32_e64 vcc, |v184|, s36
	v_cmp_lt_f32_e64 s[38:39], |v185|, s36
	v_cmp_lt_f32_e64 s[48:49], |v186|, s36
	v_cmp_lt_f32_e64 s[50:51], |v187|, s36
	v_cndmask_b32_e64 v184, v184, v200, vcc
	v_cndmask_b32_e64 v185, v185, v201, s[38:39]
	v_cndmask_b32_e64 v186, v186, v202, s[48:49]
	v_cndmask_b32_e64 v187, v187, v203, s[50:51]
	v_cmp_lt_f32_e64 vcc, |v188|, s36
	v_cmp_lt_f32_e64 s[38:39], |v189|, s36
	v_cmp_lt_f32_e64 s[48:49], |v190|, s36
	v_cmp_lt_f32_e64 s[50:51], |v191|, s36
	v_cndmask_b32_e64 v188, v188, v204, vcc
	v_cndmask_b32_e64 v189, v189, v205, s[38:39]
	v_cndmask_b32_e64 v190, v190, v206, s[48:49]
	v_cndmask_b32_e64 v191, v191, v207, s[50:51]
	v_sub_f32_e32 v68, v184, v192
	v_sub_f32_e32 v69, v185, v193
	v_sub_f32_e32 v70, v186, v194
	v_sub_f32_e32 v71, v187, v195
	v_sub_f32_e32 v64, v188, v196
	v_sub_f32_e32 v65, v189, v197
	v_sub_f32_e32 v66, v190, v198
	v_sub_f32_e32 v67, v191, v199
	v_cvt_pk_bf16_f32 v68, v68, v69
	v_cvt_pk_bf16_f32 v69, v70, v71
	v_cvt_pk_bf16_f32 v70, v64, v65
	v_cvt_pk_bf16_f32 v71, v66, v67
	global_store_dwordx4 v[176:177], v[68:71], off offset:256
	v_lshl_add_u64 v[162:163], v[178:179], 0, 0
	v_pk_mul_f32 v[60:61], v[60:61], v[148:149] op_sel_hi:[1,0]
	v_pk_mul_f32 v[62:63], v[62:63], v[148:149] op_sel_hi:[1,0]
	v_pk_mul_f32 v[56:57], v[56:57], v[148:149] op_sel_hi:[1,0]
	v_pk_mul_f32 v[58:59], v[58:59], v[148:149] op_sel_hi:[1,0]
	v_mul_f32_e32 v184, 0xbfb8aa3b, v60
	v_mul_f32_e32 v185, 0xbfb8aa3b, v61
	v_mul_f32_e32 v186, 0xbfb8aa3b, v62
	v_mul_f32_e32 v187, 0xbfb8aa3b, v63
	v_mul_f32_e32 v188, 0xbfb8aa3b, v56
	v_mul_f32_e32 v189, 0xbfb8aa3b, v57
	v_mul_f32_e32 v190, 0xbfb8aa3b, v58
	v_mul_f32_e32 v191, 0xbfb8aa3b, v59
	v_exp_f32_e32 v184, v184
	v_exp_f32_e32 v185, v185
	v_exp_f32_e32 v186, v186
	v_exp_f32_e32 v187, v187
	v_exp_f32_e32 v188, v188
	v_exp_f32_e32 v189, v189
	v_exp_f32_e32 v190, v190
	v_exp_f32_e32 v191, v191
	v_sub_f32_e32 v192, 1.0, v152
	v_sub_f32_e32 v193, 1.0, v153
	v_sub_f32_e32 v194, 1.0, v154
	v_sub_f32_e32 v195, 1.0, v155
	v_sub_f32_e32 v196, 1.0, v180
	v_sub_f32_e32 v197, 1.0, v181
	v_sub_f32_e32 v198, 1.0, v182
	v_sub_f32_e32 v199, 1.0, v183
	v_add_f32_e32 v184, 1.0, v184
	v_add_f32_e32 v185, 1.0, v185
	v_add_f32_e32 v186, 1.0, v186
	v_add_f32_e32 v187, 1.0, v187
	v_add_f32_e32 v188, 1.0, v188
	v_add_f32_e32 v189, 1.0, v189
	v_add_f32_e32 v190, 1.0, v190
	v_add_f32_e32 v191, 1.0, v191
	v_rcp_f32_e32 v184, v184
	v_rcp_f32_e32 v185, v185
	v_rcp_f32_e32 v186, v186
	v_rcp_f32_e32 v187, v187
	v_rcp_f32_e32 v188, v188
	v_rcp_f32_e32 v189, v189
	v_rcp_f32_e32 v190, v190
	v_rcp_f32_e32 v191, v191
	v_fma_f32 v200, v184, v192, v152
	v_fma_f32 v201, v185, v193, v153
	v_fma_f32 v202, v186, v194, v154
	v_fma_f32 v203, v187, v195, v155
	v_fma_f32 v204, v188, v196, v180
	v_fma_f32 v205, v189, v197, v181
	v_fma_f32 v206, v190, v198, v182
	v_fma_f32 v207, v191, v199, v183
	v_cmp_gt_f32_e64 vcc, s35, v200
	v_cmp_gt_f32_e64 s[38:39], s35, v201
	v_cmp_gt_f32_e64 s[48:49], s35, v202
	v_cmp_gt_f32_e64 s[50:51], s35, v203
	v_cndmask_b32_e64 v184, 0, 32, vcc
	v_cndmask_b32_e64 v185, 0, 32, s[38:39]
	v_cndmask_b32_e64 v186, 0, 32, s[48:49]
	v_cndmask_b32_e64 v187, 0, 32, s[50:51]
	v_cndmask_b32_e64 v192, 0, v214, vcc
	v_cndmask_b32_e64 v193, 0, v214, s[38:39]
	v_cndmask_b32_e64 v194, 0, v214, s[48:49]
	v_cndmask_b32_e64 v195, 0, v214, s[50:51]
	v_cmp_gt_f32_e64 vcc, s35, v204
	v_cmp_gt_f32_e64 s[38:39], s35, v205
	v_cmp_gt_f32_e64 s[48:49], s35, v206
	v_cmp_gt_f32_e64 s[50:51], s35, v207
	v_cndmask_b32_e64 v188, 0, 32, vcc
	v_cndmask_b32_e64 v189, 0, 32, s[38:39]
	v_cndmask_b32_e64 v190, 0, 32, s[48:49]
	v_cndmask_b32_e64 v191, 0, 32, s[50:51]
	v_cndmask_b32_e64 v196, 0, v214, vcc
	v_cndmask_b32_e64 v197, 0, v214, s[38:39]
	v_cndmask_b32_e64 v198, 0, v214, s[48:49]
	v_cndmask_b32_e64 v199, 0, v214, s[50:51]
	v_ldexp_f32 v184, v200, v184
	v_ldexp_f32 v185, v201, v185
	v_ldexp_f32 v186, v202, v186
	v_ldexp_f32 v187, v203, v187
	v_ldexp_f32 v188, v204, v188
	v_ldexp_f32 v189, v205, v189
	v_ldexp_f32 v190, v206, v190
	v_ldexp_f32 v191, v207, v191
	v_log_f32_e32 v184, v184
	v_log_f32_e32 v185, v185
	v_log_f32_e32 v186, v186
	v_log_f32_e32 v187, v187
	v_log_f32_e32 v188, v188
	v_log_f32_e32 v189, v189
	v_log_f32_e32 v190, v190
	v_log_f32_e32 v191, v191
	v_mul_f32_e32 v200, 0x3f317217, v184
	v_mul_f32_e32 v201, 0x3f317217, v185
	v_mul_f32_e32 v202, 0x3f317217, v186
	v_mul_f32_e32 v203, 0x3f317217, v187
	v_mul_f32_e32 v204, 0x3f317217, v188
	v_mul_f32_e32 v205, 0x3f317217, v189
	v_mul_f32_e32 v206, 0x3f317217, v190
; __device__ __forceinline__ unsigned cvt_pk_bf16(float lo, float hi) { unsigned r; asm volatile("v_cvt_pk_bf16_f32 %0, %1, %2" : "=v"(r) : "v"(lo), "v"(hi)); return r; }
; __device__ __forceinline__ float silu_f(float v) { return v * __builtin_amdgcn_rcpf(1.f + __expf(-v)); }
;     __device__ __forceinline__ void operator()(const f32x4 (&acc)[2][2][4][2], const Unit& u, int wr, int wc, int fr, int fq, int ui, PG8_LAS unsigned char* lds) const {
;     ...
;                     f32x4 v[2] = {acc[ai][bj][m][0] * rs, acc[ai][bj][m][1] * rs};
;                     if (ksum) { csum[bj][0] += v[0]; csum[bj][1] += v[1]; }
; #pragma unroll
;                     for (int n = 0; n < 2; ++n) {
;                         f32x4 lbv = (f32x4){0.f, 0.f, 0.f, 0.f};
;                         if (act == 2) lbv = *(const f32x4*)(lb + (col0 - 1024) + bj * HALF + 4 * n);
; #pragma unroll
;                         for (int e = 0; e < 4; ++e) {
;                             float x = v[n][e];
;                             if (act == 1) x = silu_f(x);
;                             else if (act == 2) { const float l = lbv[e]; x = __logf(l + (1.f - l) * __builtin_amdgcn_rcpf(1.f + __expf(-x))); }
;                             else if (act == 3) { x = fmaxf(x, 0.f); x = x * x; }
;                             v[n][e] = x;
;                         }
;                     }
;                     u32x4 w; w.x = cvt_pk_bf16(v[0][0], v[0][1]); w.y = cvt_pk_bf16(v[0][2], v[0][3]); w.z = cvt_pk_bf16(v[1][0], v[1][1]); w.w = cvt_pk_bf16(v[1][2], v[1][3]);
;                     *(u32x4*)(rowp + bj * HALF) = w;
	v_mul_f32_e32 v207, 0x3f317217, v191
	v_fma_f32 v200, v184, s13, -v200
	v_fma_f32 v201, v185, s13, -v201
	v_fma_f32 v202, v186, s13, -v202
	v_fma_f32 v203, v187, s13, -v203
	v_fma_f32 v204, v188, s13, -v204
	v_fma_f32 v205, v189, s13, -v205
	v_fma_f32 v206, v190, s13, -v206
	v_fma_f32 v207, v191, s13, -v207
	v_fmac_f32_e32 v200, 0x3377d1cf, v184
	v_fmac_f32_e32 v201, 0x3377d1cf, v185
	v_fmac_f32_e32 v202, 0x3377d1cf, v186
	v_fmac_f32_e32 v203, 0x3377d1cf, v187
	v_fmac_f32_e32 v204, 0x3377d1cf, v188
	v_fmac_f32_e32 v205, 0x3377d1cf, v189
	v_fmac_f32_e32 v206, 0x3377d1cf, v190
	v_fmac_f32_e32 v207, 0x3377d1cf, v191
	v_fmac_f32_e32 v200, 0x3f317217, v184
	v_fmac_f32_e32 v201, 0x3f317217, v185
	v_fmac_f32_e32 v202, 0x3f317217, v186
	v_fmac_f32_e32 v203, 0x3f317217, v187
	v_fmac_f32_e32 v204, 0x3f317217, v188
	v_fmac_f32_e32 v205, 0x3f317217, v189
	v_fmac_f32_e32 v206, 0x3f317217, v190
	v_fmac_f32_e32 v207, 0x3f317217, v191
	v_cmp_lt_f32_e64 vcc, |v184|, s36
	v_cmp_lt_f32_e64 s[38:39], |v185|, s36
	v_cmp_lt_f32_e64 s[48:49], |v186|, s36
	v_cmp_lt_f32_e64 s[50:51], |v187|, s36
	v_cndmask_b32_e64 v184, v184, v200, vcc
	v_cndmask_b32_e64 v185, v185, v201, s[38:39]
	v_cndmask_b32_e64 v186, v186, v202, s[48:49]
	v_cndmask_b32_e64 v187, v187, v203, s[50:51]
	v_cmp_lt_f32_e64 vcc, |v188|, s36
	v_cmp_lt_f32_e64 s[38:39], |v189|, s36
	v_cmp_lt_f32_e64 s[48:49], |v190|, s36
	v_cmp_lt_f32_e64 s[50:51], |v191|, s36
	v_cndmask_b32_e64 v188, v188, v204, vcc
	v_cndmask_b32_e64 v189, v189, v205, s[38:39]
	v_cndmask_b32_e64 v190, v190, v206, s[48:49]
	v_cndmask_b32_e64 v191, v191, v207, s[50:51]
	v_sub_f32_e32 v60, v184, v192
	v_sub_f32_e32 v61, v185, v193
	v_sub_f32_e32 v62, v186, v194
	v_sub_f32_e32 v63, v187, v195
	v_sub_f32_e32 v56, v188, v196
	v_sub_f32_e32 v57, v189, v197
	v_sub_f32_e32 v58, v190, v198
	v_sub_f32_e32 v59, v191, v199
	v_cvt_pk_bf16_f32 v60, v60, v61
	v_cvt_pk_bf16_f32 v61, v62, v63
	v_cvt_pk_bf16_f32 v62, v56, v57
	v_cvt_pk_bf16_f32 v63, v58, v59
	global_store_dwordx4 v[162:163], v[60:63], off
	v_pk_mul_f32 v[52:53], v[52:53], v[148:149] op_sel_hi:[1,0]
	v_pk_mul_f32 v[54:55], v[54:55], v[148:149] op_sel_hi:[1,0]
	v_pk_mul_f32 v[48:49], v[48:49], v[148:149] op_sel_hi:[1,0]
	v_pk_mul_f32 v[50:51], v[50:51], v[148:149] op_sel_hi:[1,0]
	v_mul_f32_e32 v184, 0xbfb8aa3b, v52
	v_mul_f32_e32 v185, 0xbfb8aa3b, v53
	v_mul_f32_e32 v186, 0xbfb8aa3b, v54
	v_mul_f32_e32 v187, 0xbfb8aa3b, v55
	v_mul_f32_e32 v188, 0xbfb8aa3b, v48
	v_mul_f32_e32 v189, 0xbfb8aa3b, v49
	v_mul_f32_e32 v190, 0xbfb8aa3b, v50
	v_mul_f32_e32 v191, 0xbfb8aa3b, v51
	v_exp_f32_e32 v184, v184
	v_exp_f32_e32 v185, v185
	v_exp_f32_e32 v186, v186
	v_exp_f32_e32 v187, v187
	v_exp_f32_e32 v188, v188
	v_exp_f32_e32 v189, v189
	v_exp_f32_e32 v190, v190
	v_exp_f32_e32 v191, v191
	v_sub_f32_e32 v192, 1.0, v218
	v_sub_f32_e32 v193, 1.0, v219
	v_sub_f32_e32 v194, 1.0, v220
	v_sub_f32_e32 v195, 1.0, v221
	v_sub_f32_e32 v196, 1.0, v222
	v_sub_f32_e32 v197, 1.0, v223
	v_sub_f32_e32 v198, 1.0, v224
	v_sub_f32_e32 v199, 1.0, v225
	v_add_f32_e32 v184, 1.0, v184
	v_add_f32_e32 v185, 1.0, v185
	v_add_f32_e32 v186, 1.0, v186
	v_add_f32_e32 v187, 1.0, v187
	v_add_f32_e32 v188, 1.0, v188
	v_add_f32_e32 v189, 1.0, v189
	v_add_f32_e32 v190, 1.0, v190
	v_add_f32_e32 v191, 1.0, v191
	v_rcp_f32_e32 v184, v184
	v_rcp_f32_e32 v185, v185
	v_rcp_f32_e32 v186, v186
	v_rcp_f32_e32 v187, v187
	v_rcp_f32_e32 v188, v188
	v_rcp_f32_e32 v189, v189
	v_rcp_f32_e32 v190, v190
	v_rcp_f32_e32 v191, v191
	v_fma_f32 v200, v184, v192, v218
	v_fma_f32 v201, v185, v193, v219
	v_fma_f32 v202, v186, v194, v220
	v_fma_f32 v203, v187, v195, v221
	v_fma_f32 v204, v188, v196, v222
	v_fma_f32 v205, v189, v197, v223
	v_fma_f32 v206, v190, v198, v224
	v_fma_f32 v207, v191, v199, v225
	v_cmp_gt_f32_e64 vcc, s35, v200
	v_cmp_gt_f32_e64 s[38:39], s35, v201
	v_cmp_gt_f32_e64 s[48:49], s35, v202
	v_cmp_gt_f32_e64 s[50:51], s35, v203
	v_cndmask_b32_e64 v184, 0, 32, vcc
	v_cndmask_b32_e64 v185, 0, 32, s[38:39]
	v_cndmask_b32_e64 v186, 0, 32, s[48:49]
	v_cndmask_b32_e64 v187, 0, 32, s[50:51]
	v_cndmask_b32_e64 v192, 0, v214, vcc
	v_cndmask_b32_e64 v193, 0, v214, s[38:39]
	v_cndmask_b32_e64 v194, 0, v214, s[48:49]
	v_cndmask_b32_e64 v195, 0, v214, s[50:51]
	v_cmp_gt_f32_e64 vcc, s35, v204
	v_cmp_gt_f32_e64 s[38:39], s35, v205
	v_cmp_gt_f32_e64 s[48:49], s35, v206
	v_cmp_gt_f32_e64 s[50:51], s35, v207
	v_cndmask_b32_e64 v188, 0, 32, vcc
	v_cndmask_b32_e64 v189, 0, 32, s[38:39]
	v_cndmask_b32_e64 v190, 0, 32, s[48:49]
	v_cndmask_b32_e64 v191, 0, 32, s[50:51]
	v_cndmask_b32_e64 v196, 0, v214, vcc
	v_cndmask_b32_e64 v197, 0, v214, s[38:39]
	v_cndmask_b32_e64 v198, 0, v214, s[48:49]
	v_cndmask_b32_e64 v199, 0, v214, s[50:51]
	v_ldexp_f32 v184, v200, v184
	v_ldexp_f32 v185, v201, v185
	v_ldexp_f32 v186, v202, v186
	v_ldexp_f32 v187, v203, v187
	v_ldexp_f32 v188, v204, v188
	v_ldexp_f32 v189, v205, v189
	v_ldexp_f32 v190, v206, v190
	v_ldexp_f32 v191, v207, v191
	v_log_f32_e32 v184, v184
	v_log_f32_e32 v185, v185
	v_log_f32_e32 v186, v186
	v_log_f32_e32 v187, v187
	v_log_f32_e32 v188, v188
	v_log_f32_e32 v189, v189
	v_log_f32_e32 v190, v190
	v_log_f32_e32 v191, v191
	v_mul_f32_e32 v200, 0x3f317217, v184
	v_mul_f32_e32 v201, 0x3f317217, v185
	v_mul_f32_e32 v202, 0x3f317217, v186
	v_mul_f32_e32 v203, 0x3f317217, v187
	v_mul_f32_e32 v204, 0x3f317217, v188
	v_mul_f32_e32 v205, 0x3f317217, v189
	v_mul_f32_e32 v206, 0x3f317217, v190
	v_mul_f32_e32 v207, 0x3f317217, v191
	v_fma_f32 v200, v184, s13, -v200
	v_fma_f32 v201, v185, s13, -v201
	v_fma_f32 v202, v186, s13, -v202
	v_fma_f32 v203, v187, s13, -v203
	v_fma_f32 v204, v188, s13, -v204
	v_fma_f32 v205, v189, s13, -v205
; __device__ __forceinline__ unsigned cvt_pk_bf16(float lo, float hi) { unsigned r; asm volatile("v_cvt_pk_bf16_f32 %0, %1, %2" : "=v"(r) : "v"(lo), "v"(hi)); return r; }
; __device__ __forceinline__ float silu_f(float v) { return v * __builtin_amdgcn_rcpf(1.f + __expf(-v)); }
;     __device__ __forceinline__ void operator()(const f32x4 (&acc)[2][2][4][2], const Unit& u, int wr, int wc, int fr, int fq, int ui, PG8_LAS unsigned char* lds) const {
;     ...
;                     f32x4 v[2] = {acc[ai][bj][m][0] * rs, acc[ai][bj][m][1] * rs};
;                     if (ksum) { csum[bj][0] += v[0]; csum[bj][1] += v[1]; }
; #pragma unroll
;                     for (int n = 0; n < 2; ++n) {
;                         f32x4 lbv = (f32x4){0.f, 0.f, 0.f, 0.f};
;                         if (act == 2) lbv = *(const f32x4*)(lb + (col0 - 1024) + bj * HALF + 4 * n);
; #pragma unroll
;                         for (int e = 0; e < 4; ++e) {
;                             float x = v[n][e];
;                             if (act == 1) x = silu_f(x);
;                             else if (act == 2) { const float l = lbv[e]; x = __logf(l + (1.f - l) * __builtin_amdgcn_rcpf(1.f + __expf(-x))); }
;                             else if (act == 3) { x = fmaxf(x, 0.f); x = x * x; }
;                             v[n][e] = x;
;                         }
;                     }
;                     u32x4 w; w.x = cvt_pk_bf16(v[0][0], v[0][1]); w.y = cvt_pk_bf16(v[0][2], v[0][3]); w.z = cvt_pk_bf16(v[1][0], v[1][1]); w.w = cvt_pk_bf16(v[1][2], v[1][3]);
;                     *(u32x4*)(rowp + bj * HALF) = w;
	v_fma_f32 v206, v190, s13, -v206
	v_fma_f32 v207, v191, s13, -v207
	v_fmac_f32_e32 v200, 0x3377d1cf, v184
	v_fmac_f32_e32 v201, 0x3377d1cf, v185
	v_fmac_f32_e32 v202, 0x3377d1cf, v186
	v_fmac_f32_e32 v203, 0x3377d1cf, v187
	v_fmac_f32_e32 v204, 0x3377d1cf, v188
	v_fmac_f32_e32 v205, 0x3377d1cf, v189
	v_fmac_f32_e32 v206, 0x3377d1cf, v190
	v_fmac_f32_e32 v207, 0x3377d1cf, v191
	v_fmac_f32_e32 v200, 0x3f317217, v184
	v_fmac_f32_e32 v201, 0x3f317217, v185
	v_fmac_f32_e32 v202, 0x3f317217, v186
	v_fmac_f32_e32 v203, 0x3f317217, v187
	v_fmac_f32_e32 v204, 0x3f317217, v188
	v_fmac_f32_e32 v205, 0x3f317217, v189
	v_fmac_f32_e32 v206, 0x3f317217, v190
	v_fmac_f32_e32 v207, 0x3f317217, v191
	v_cmp_lt_f32_e64 vcc, |v184|, s36
	v_cmp_lt_f32_e64 s[38:39], |v185|, s36
	v_cmp_lt_f32_e64 s[48:49], |v186|, s36
	v_cmp_lt_f32_e64 s[50:51], |v187|, s36
	v_cndmask_b32_e64 v184, v184, v200, vcc
	v_cndmask_b32_e64 v185, v185, v201, s[38:39]
	v_cndmask_b32_e64 v186, v186, v202, s[48:49]
	v_cndmask_b32_e64 v187, v187, v203, s[50:51]
	v_cmp_lt_f32_e64 vcc, |v188|, s36
	v_cmp_lt_f32_e64 s[38:39], |v189|, s36
	v_cmp_lt_f32_e64 s[48:49], |v190|, s36
	v_cmp_lt_f32_e64 s[50:51], |v191|, s36
	v_cndmask_b32_e64 v188, v188, v204, vcc
	v_cndmask_b32_e64 v189, v189, v205, s[38:39]
	v_cndmask_b32_e64 v190, v190, v206, s[48:49]
	v_cndmask_b32_e64 v191, v191, v207, s[50:51]
	v_sub_f32_e32 v52, v184, v192
	v_sub_f32_e32 v53, v185, v193
	v_sub_f32_e32 v54, v186, v194
	v_sub_f32_e32 v55, v187, v195
	v_sub_f32_e32 v48, v188, v196
	v_sub_f32_e32 v49, v189, v197
	v_sub_f32_e32 v50, v190, v198
	v_sub_f32_e32 v51, v191, v199
	v_cvt_pk_bf16_f32 v52, v52, v53
	v_cvt_pk_bf16_f32 v53, v54, v55
	v_cvt_pk_bf16_f32 v54, v48, v49
	v_cvt_pk_bf16_f32 v55, v50, v51
	global_store_dwordx4 v[162:163], v[52:55], off offset:256
	v_lshl_add_u64 v[176:177], v[162:163], 0, s[46:47]
	v_pk_mul_f32 v[44:45], v[44:45], v[156:157] op_sel_hi:[1,0]
	v_pk_mul_f32 v[46:47], v[46:47], v[156:157] op_sel_hi:[1,0]
	v_pk_mul_f32 v[40:41], v[40:41], v[156:157] op_sel_hi:[1,0]
	v_pk_mul_f32 v[42:43], v[42:43], v[156:157] op_sel_hi:[1,0]
	v_mul_f32_e32 v184, 0xbfb8aa3b, v44
	v_mul_f32_e32 v185, 0xbfb8aa3b, v45
	v_mul_f32_e32 v186, 0xbfb8aa3b, v46
	v_mul_f32_e32 v187, 0xbfb8aa3b, v47
	v_mul_f32_e32 v188, 0xbfb8aa3b, v40
	v_mul_f32_e32 v189, 0xbfb8aa3b, v41
	v_mul_f32_e32 v190, 0xbfb8aa3b, v42
	v_mul_f32_e32 v191, 0xbfb8aa3b, v43
	v_exp_f32_e32 v184, v184
	v_exp_f32_e32 v185, v185
	v_exp_f32_e32 v186, v186
	v_exp_f32_e32 v187, v187
	v_exp_f32_e32 v188, v188
	v_exp_f32_e32 v189, v189
	v_exp_f32_e32 v190, v190
	v_exp_f32_e32 v191, v191
	v_sub_f32_e32 v192, 1.0, v152
	v_sub_f32_e32 v193, 1.0, v153
	v_sub_f32_e32 v194, 1.0, v154
	v_sub_f32_e32 v195, 1.0, v155
	v_sub_f32_e32 v196, 1.0, v180
	v_sub_f32_e32 v197, 1.0, v181
	v_sub_f32_e32 v198, 1.0, v182
	v_sub_f32_e32 v199, 1.0, v183
	v_add_f32_e32 v184, 1.0, v184
	v_add_f32_e32 v185, 1.0, v185
	v_add_f32_e32 v186, 1.0, v186
	v_add_f32_e32 v187, 1.0, v187
	v_add_f32_e32 v188, 1.0, v188
	v_add_f32_e32 v189, 1.0, v189
	v_add_f32_e32 v190, 1.0, v190
	v_add_f32_e32 v191, 1.0, v191
	v_rcp_f32_e32 v184, v184
	v_rcp_f32_e32 v185, v185
	v_rcp_f32_e32 v186, v186
	v_rcp_f32_e32 v187, v187
	v_rcp_f32_e32 v188, v188
	v_rcp_f32_e32 v189, v189
	v_rcp_f32_e32 v190, v190
	v_rcp_f32_e32 v191, v191
	v_fma_f32 v200, v184, v192, v152
	v_fma_f32 v201, v185, v193, v153
	v_fma_f32 v202, v186, v194, v154
	v_fma_f32 v203, v187, v195, v155
	v_fma_f32 v204, v188, v196, v180
	v_fma_f32 v205, v189, v197, v181
	v_fma_f32 v206, v190, v198, v182
	v_fma_f32 v207, v191, v199, v183
	v_cmp_gt_f32_e64 vcc, s35, v200
	v_cmp_gt_f32_e64 s[38:39], s35, v201
	v_cmp_gt_f32_e64 s[48:49], s35, v202
	v_cmp_gt_f32_e64 s[50:51], s35, v203
	v_cndmask_b32_e64 v184, 0, 32, vcc
	v_cndmask_b32_e64 v185, 0, 32, s[38:39]
	v_cndmask_b32_e64 v186, 0, 32, s[48:49]
	v_cndmask_b32_e64 v187, 0, 32, s[50:51]
	v_cndmask_b32_e64 v192, 0, v214, vcc
	v_cndmask_b32_e64 v193, 0, v214, s[38:39]
	v_cndmask_b32_e64 v194, 0, v214, s[48:49]
	v_cndmask_b32_e64 v195, 0, v214, s[50:51]
	v_cmp_gt_f32_e64 vcc, s35, v204
	v_cmp_gt_f32_e64 s[38:39], s35, v205
	v_cmp_gt_f32_e64 s[48:49], s35, v206
	v_cmp_gt_f32_e64 s[50:51], s35, v207
	v_cndmask_b32_e64 v188, 0, 32, vcc
	v_cndmask_b32_e64 v189, 0, 32, s[38:39]
	v_cndmask_b32_e64 v190, 0, 32, s[48:49]
	v_cndmask_b32_e64 v191, 0, 32, s[50:51]
	v_cndmask_b32_e64 v196, 0, v214, vcc
	v_cndmask_b32_e64 v197, 0, v214, s[38:39]
	v_cndmask_b32_e64 v198, 0, v214, s[48:49]
	v_cndmask_b32_e64 v199, 0, v214, s[50:51]
	v_ldexp_f32 v184, v200, v184
	v_ldexp_f32 v185, v201, v185
	v_ldexp_f32 v186, v202, v186
	v_ldexp_f32 v187, v203, v187
	v_ldexp_f32 v188, v204, v188
	v_ldexp_f32 v189, v205, v189
	v_ldexp_f32 v190, v206, v190
	v_ldexp_f32 v191, v207, v191
	v_log_f32_e32 v184, v184
	v_log_f32_e32 v185, v185
	v_log_f32_e32 v186, v186
	v_log_f32_e32 v187, v187
	v_log_f32_e32 v188, v188
	v_log_f32_e32 v189, v189
	v_log_f32_e32 v190, v190
	v_log_f32_e32 v191, v191
	v_mul_f32_e32 v200, 0x3f317217, v184
	v_mul_f32_e32 v201, 0x3f317217, v185
	v_mul_f32_e32 v202, 0x3f317217, v186
	v_mul_f32_e32 v203, 0x3f317217, v187
	v_mul_f32_e32 v204, 0x3f317217, v188
	v_mul_f32_e32 v205, 0x3f317217, v189
	v_mul_f32_e32 v206, 0x3f317217, v190
	v_mul_f32_e32 v207, 0x3f317217, v191
	v_fma_f32 v200, v184, s13, -v200
	v_fma_f32 v201, v185, s13, -v201
	v_fma_f32 v202, v186, s13, -v202
	v_fma_f32 v203, v187, s13, -v203
	v_fma_f32 v204, v188, s13, -v204
	v_fma_f32 v205, v189, s13, -v205
	v_fma_f32 v206, v190, s13, -v206
	v_fma_f32 v207, v191, s13, -v207
	v_fmac_f32_e32 v200, 0x3377d1cf, v184
	v_fmac_f32_e32 v201, 0x3377d1cf, v185
; __device__ __forceinline__ unsigned cvt_pk_bf16(float lo, float hi) { unsigned r; asm volatile("v_cvt_pk_bf16_f32 %0, %1, %2" : "=v"(r) : "v"(lo), "v"(hi)); return r; }
; __device__ __forceinline__ float silu_f(float v) { return v * __builtin_amdgcn_rcpf(1.f + __expf(-v)); }
;     __device__ __forceinline__ void operator()(const f32x4 (&acc)[2][2][4][2], const Unit& u, int wr, int wc, int fr, int fq, int ui, PG8_LAS unsigned char* lds) const {
;     ...
;                     f32x4 v[2] = {acc[ai][bj][m][0] * rs, acc[ai][bj][m][1] * rs};
;                     if (ksum) { csum[bj][0] += v[0]; csum[bj][1] += v[1]; }
; #pragma unroll
;                     for (int n = 0; n < 2; ++n) {
;                         f32x4 lbv = (f32x4){0.f, 0.f, 0.f, 0.f};
;                         if (act == 2) lbv = *(const f32x4*)(lb + (col0 - 1024) + bj * HALF + 4 * n);
; #pragma unroll
;                         for (int e = 0; e < 4; ++e) {
;                             float x = v[n][e];
;                             if (act == 1) x = silu_f(x);
;                             else if (act == 2) { const float l = lbv[e]; x = __logf(l + (1.f - l) * __builtin_amdgcn_rcpf(1.f + __expf(-x))); }
;                             else if (act == 3) { x = fmaxf(x, 0.f); x = x * x; }
;                             v[n][e] = x;
;                         }
;                     }
;                     u32x4 w; w.x = cvt_pk_bf16(v[0][0], v[0][1]); w.y = cvt_pk_bf16(v[0][2], v[0][3]); w.z = cvt_pk_bf16(v[1][0], v[1][1]); w.w = cvt_pk_bf16(v[1][2], v[1][3]);
;                     *(u32x4*)(rowp + bj * HALF) = w;
	v_fmac_f32_e32 v202, 0x3377d1cf, v186
	v_fmac_f32_e32 v203, 0x3377d1cf, v187
	v_fmac_f32_e32 v204, 0x3377d1cf, v188
	v_fmac_f32_e32 v205, 0x3377d1cf, v189
	v_fmac_f32_e32 v206, 0x3377d1cf, v190
	v_fmac_f32_e32 v207, 0x3377d1cf, v191
	v_fmac_f32_e32 v200, 0x3f317217, v184
	v_fmac_f32_e32 v201, 0x3f317217, v185
	v_fmac_f32_e32 v202, 0x3f317217, v186
	v_fmac_f32_e32 v203, 0x3f317217, v187
	v_fmac_f32_e32 v204, 0x3f317217, v188
	v_fmac_f32_e32 v205, 0x3f317217, v189
	v_fmac_f32_e32 v206, 0x3f317217, v190
	v_fmac_f32_e32 v207, 0x3f317217, v191
	v_cmp_lt_f32_e64 vcc, |v184|, s36
	v_cmp_lt_f32_e64 s[38:39], |v185|, s36
	v_cmp_lt_f32_e64 s[48:49], |v186|, s36
	v_cmp_lt_f32_e64 s[50:51], |v187|, s36
	v_cndmask_b32_e64 v184, v184, v200, vcc
	v_cndmask_b32_e64 v185, v185, v201, s[38:39]
	v_cndmask_b32_e64 v186, v186, v202, s[48:49]
	v_cndmask_b32_e64 v187, v187, v203, s[50:51]
	v_cmp_lt_f32_e64 vcc, |v188|, s36
	v_cmp_lt_f32_e64 s[38:39], |v189|, s36
	v_cmp_lt_f32_e64 s[48:49], |v190|, s36
	v_cmp_lt_f32_e64 s[50:51], |v191|, s36
	v_cndmask_b32_e64 v188, v188, v204, vcc
	v_cndmask_b32_e64 v189, v189, v205, s[38:39]
	v_cndmask_b32_e64 v190, v190, v206, s[48:49]
	v_cndmask_b32_e64 v191, v191, v207, s[50:51]
	v_sub_f32_e32 v44, v184, v192
	v_sub_f32_e32 v45, v185, v193
	v_sub_f32_e32 v46, v186, v194
	v_sub_f32_e32 v47, v187, v195
	v_sub_f32_e32 v40, v188, v196
	v_sub_f32_e32 v41, v189, v197
	v_sub_f32_e32 v42, v190, v198
	v_sub_f32_e32 v43, v191, v199
	v_cvt_pk_bf16_f32 v44, v44, v45
	v_cvt_pk_bf16_f32 v45, v46, v47
	v_cvt_pk_bf16_f32 v46, v40, v41
	v_cvt_pk_bf16_f32 v47, v42, v43
	global_store_dwordx4 v[176:177], v[44:47], off
	v_pk_mul_f32 v[36:37], v[36:37], v[156:157] op_sel_hi:[1,0]
	v_pk_mul_f32 v[38:39], v[38:39], v[156:157] op_sel_hi:[1,0]
	v_pk_mul_f32 v[32:33], v[32:33], v[156:157] op_sel_hi:[1,0]
	v_pk_mul_f32 v[34:35], v[34:35], v[156:157] op_sel_hi:[1,0]
	v_mul_f32_e32 v184, 0xbfb8aa3b, v36
	v_mul_f32_e32 v185, 0xbfb8aa3b, v37
	v_mul_f32_e32 v186, 0xbfb8aa3b, v38
	v_mul_f32_e32 v187, 0xbfb8aa3b, v39
	v_mul_f32_e32 v188, 0xbfb8aa3b, v32
	v_mul_f32_e32 v189, 0xbfb8aa3b, v33
	v_mul_f32_e32 v190, 0xbfb8aa3b, v34
	v_mul_f32_e32 v191, 0xbfb8aa3b, v35
	v_exp_f32_e32 v184, v184
	v_exp_f32_e32 v185, v185
	v_exp_f32_e32 v186, v186
	v_exp_f32_e32 v187, v187
	v_exp_f32_e32 v188, v188
	v_exp_f32_e32 v189, v189
	v_exp_f32_e32 v190, v190
	v_exp_f32_e32 v191, v191
	v_sub_f32_e32 v192, 1.0, v218
	v_sub_f32_e32 v193, 1.0, v219
	v_sub_f32_e32 v194, 1.0, v220
	v_sub_f32_e32 v195, 1.0, v221
	v_sub_f32_e32 v196, 1.0, v222
	v_sub_f32_e32 v197, 1.0, v223
	v_sub_f32_e32 v198, 1.0, v224
	v_sub_f32_e32 v199, 1.0, v225
	v_add_f32_e32 v184, 1.0, v184
	v_add_f32_e32 v185, 1.0, v185
	v_add_f32_e32 v186, 1.0, v186
	v_add_f32_e32 v187, 1.0, v187
	v_add_f32_e32 v188, 1.0, v188
	v_add_f32_e32 v189, 1.0, v189
	v_add_f32_e32 v190, 1.0, v190
	v_add_f32_e32 v191, 1.0, v191
	v_rcp_f32_e32 v184, v184
	v_rcp_f32_e32 v185, v185
	v_rcp_f32_e32 v186, v186
	v_rcp_f32_e32 v187, v187
	v_rcp_f32_e32 v188, v188
	v_rcp_f32_e32 v189, v189
	v_rcp_f32_e32 v190, v190
	v_rcp_f32_e32 v191, v191
	v_fma_f32 v200, v184, v192, v218
	v_fma_f32 v201, v185, v193, v219
	v_fma_f32 v202, v186, v194, v220
	v_fma_f32 v203, v187, v195, v221
	v_fma_f32 v204, v188, v196, v222
	v_fma_f32 v205, v189, v197, v223
	v_fma_f32 v206, v190, v198, v224
	v_fma_f32 v207, v191, v199, v225
	v_cmp_gt_f32_e64 vcc, s35, v200
	v_cmp_gt_f32_e64 s[38:39], s35, v201
	v_cmp_gt_f32_e64 s[48:49], s35, v202
	v_cmp_gt_f32_e64 s[50:51], s35, v203
	v_cndmask_b32_e64 v184, 0, 32, vcc
	v_cndmask_b32_e64 v185, 0, 32, s[38:39]
	v_cndmask_b32_e64 v186, 0, 32, s[48:49]
	v_cndmask_b32_e64 v187, 0, 32, s[50:51]
	v_cndmask_b32_e64 v192, 0, v214, vcc
	v_cndmask_b32_e64 v193, 0, v214, s[38:39]
	v_cndmask_b32_e64 v194, 0, v214, s[48:49]
	v_cndmask_b32_e64 v195, 0, v214, s[50:51]
	v_cmp_gt_f32_e64 vcc, s35, v204
	v_cmp_gt_f32_e64 s[38:39], s35, v205
	v_cmp_gt_f32_e64 s[48:49], s35, v206
	v_cmp_gt_f32_e64 s[50:51], s35, v207
	v_cndmask_b32_e64 v188, 0, 32, vcc
	v_cndmask_b32_e64 v189, 0, 32, s[38:39]
	v_cndmask_b32_e64 v190, 0, 32, s[48:49]
	v_cndmask_b32_e64 v191, 0, 32, s[50:51]
	v_cndmask_b32_e64 v196, 0, v214, vcc
	v_cndmask_b32_e64 v197, 0, v214, s[38:39]
	v_cndmask_b32_e64 v198, 0, v214, s[48:49]
	v_cndmask_b32_e64 v199, 0, v214, s[50:51]
	v_ldexp_f32 v184, v200, v184
	v_ldexp_f32 v185, v201, v185
	v_ldexp_f32 v186, v202, v186
	v_ldexp_f32 v187, v203, v187
	v_ldexp_f32 v188, v204, v188
	v_ldexp_f32 v189, v205, v189
	v_ldexp_f32 v190, v206, v190
	v_ldexp_f32 v191, v207, v191
	v_log_f32_e32 v184, v184
	v_log_f32_e32 v185, v185
	v_log_f32_e32 v186, v186
	v_log_f32_e32 v187, v187
	v_log_f32_e32 v188, v188
	v_log_f32_e32 v189, v189
	v_log_f32_e32 v190, v190
	v_log_f32_e32 v191, v191
	v_mul_f32_e32 v200, 0x3f317217, v184
	v_mul_f32_e32 v201, 0x3f317217, v185
	v_mul_f32_e32 v202, 0x3f317217, v186
	v_mul_f32_e32 v203, 0x3f317217, v187
	v_mul_f32_e32 v204, 0x3f317217, v188
	v_mul_f32_e32 v205, 0x3f317217, v189
	v_mul_f32_e32 v206, 0x3f317217, v190
	v_mul_f32_e32 v207, 0x3f317217, v191
	v_fma_f32 v200, v184, s13, -v200
	v_fma_f32 v201, v185, s13, -v201
	v_fma_f32 v202, v186, s13, -v202
	v_fma_f32 v203, v187, s13, -v203
	v_fma_f32 v204, v188, s13, -v204
	v_fma_f32 v205, v189, s13, -v205
	v_fma_f32 v206, v190, s13, -v206
	v_fma_f32 v207, v191, s13, -v207
	v_fmac_f32_e32 v200, 0x3377d1cf, v184
	v_fmac_f32_e32 v201, 0x3377d1cf, v185
	v_fmac_f32_e32 v202, 0x3377d1cf, v186
	v_fmac_f32_e32 v203, 0x3377d1cf, v187
	v_fmac_f32_e32 v204, 0x3377d1cf, v188
	v_fmac_f32_e32 v205, 0x3377d1cf, v189
	v_fmac_f32_e32 v206, 0x3377d1cf, v190
	v_fmac_f32_e32 v207, 0x3377d1cf, v191
; __device__ __forceinline__ unsigned cvt_pk_bf16(float lo, float hi) { unsigned r; asm volatile("v_cvt_pk_bf16_f32 %0, %1, %2" : "=v"(r) : "v"(lo), "v"(hi)); return r; }
; __device__ __forceinline__ float silu_f(float v) { return v * __builtin_amdgcn_rcpf(1.f + __expf(-v)); }
;     __device__ __forceinline__ void operator()(const f32x4 (&acc)[2][2][4][2], const Unit& u, int wr, int wc, int fr, int fq, int ui, PG8_LAS unsigned char* lds) const {
;     ...
;                     f32x4 v[2] = {acc[ai][bj][m][0] * rs, acc[ai][bj][m][1] * rs};
;                     if (ksum) { csum[bj][0] += v[0]; csum[bj][1] += v[1]; }
; #pragma unroll
;                     for (int n = 0; n < 2; ++n) {
;                         f32x4 lbv = (f32x4){0.f, 0.f, 0.f, 0.f};
;                         if (act == 2) lbv = *(const f32x4*)(lb + (col0 - 1024) + bj * HALF + 4 * n);
; #pragma unroll
;                         for (int e = 0; e < 4; ++e) {
;                             float x = v[n][e];
;                             if (act == 1) x = silu_f(x);
;                             else if (act == 2) { const float l = lbv[e]; x = __logf(l + (1.f - l) * __builtin_amdgcn_rcpf(1.f + __expf(-x))); }
;                             else if (act == 3) { x = fmaxf(x, 0.f); x = x * x; }
;                             v[n][e] = x;
;                         }
;                     }
;                     u32x4 w; w.x = cvt_pk_bf16(v[0][0], v[0][1]); w.y = cvt_pk_bf16(v[0][2], v[0][3]); w.z = cvt_pk_bf16(v[1][0], v[1][1]); w.w = cvt_pk_bf16(v[1][2], v[1][3]);
;                     *(u32x4*)(rowp + bj * HALF) = w;
	v_fmac_f32_e32 v200, 0x3f317217, v184
	v_fmac_f32_e32 v201, 0x3f317217, v185
	v_fmac_f32_e32 v202, 0x3f317217, v186
	v_fmac_f32_e32 v203, 0x3f317217, v187
	v_fmac_f32_e32 v204, 0x3f317217, v188
	v_fmac_f32_e32 v205, 0x3f317217, v189
	v_fmac_f32_e32 v206, 0x3f317217, v190
	v_fmac_f32_e32 v207, 0x3f317217, v191
	v_cmp_lt_f32_e64 vcc, |v184|, s36
	v_cmp_lt_f32_e64 s[38:39], |v185|, s36
	v_cmp_lt_f32_e64 s[48:49], |v186|, s36
	v_cmp_lt_f32_e64 s[50:51], |v187|, s36
	v_cndmask_b32_e64 v184, v184, v200, vcc
	v_cndmask_b32_e64 v185, v185, v201, s[38:39]
	v_cndmask_b32_e64 v186, v186, v202, s[48:49]
	v_cndmask_b32_e64 v187, v187, v203, s[50:51]
	v_cmp_lt_f32_e64 vcc, |v188|, s36
	v_cmp_lt_f32_e64 s[38:39], |v189|, s36
	v_cmp_lt_f32_e64 s[48:49], |v190|, s36
	v_cmp_lt_f32_e64 s[50:51], |v191|, s36
	v_cndmask_b32_e64 v188, v188, v204, vcc
	v_cndmask_b32_e64 v189, v189, v205, s[38:39]
	v_cndmask_b32_e64 v190, v190, v206, s[48:49]
	v_cndmask_b32_e64 v191, v191, v207, s[50:51]
	v_sub_f32_e32 v36, v184, v192
	v_sub_f32_e32 v37, v185, v193
	v_sub_f32_e32 v38, v186, v194
	v_sub_f32_e32 v39, v187, v195
	v_sub_f32_e32 v32, v188, v196
	v_sub_f32_e32 v33, v189, v197
	v_sub_f32_e32 v34, v190, v198
	v_sub_f32_e32 v35, v191, v199
	v_cvt_pk_bf16_f32 v36, v36, v37
	v_cvt_pk_bf16_f32 v37, v38, v39
	v_cvt_pk_bf16_f32 v38, v32, v33
	v_cvt_pk_bf16_f32 v39, v34, v35
	global_store_dwordx4 v[176:177], v[36:39], off offset:256
	v_lshl_add_u64 v[162:163], v[176:177], 0, s[46:47]
	v_pk_mul_f32 v[28:29], v[28:29], v[158:159] op_sel_hi:[1,0]
	v_pk_mul_f32 v[30:31], v[30:31], v[158:159] op_sel_hi:[1,0]
	v_pk_mul_f32 v[24:25], v[24:25], v[158:159] op_sel_hi:[1,0]
	v_pk_mul_f32 v[26:27], v[26:27], v[158:159] op_sel_hi:[1,0]
	v_mul_f32_e32 v184, 0xbfb8aa3b, v28
	v_mul_f32_e32 v185, 0xbfb8aa3b, v29
	v_mul_f32_e32 v186, 0xbfb8aa3b, v30
	v_mul_f32_e32 v187, 0xbfb8aa3b, v31
	v_mul_f32_e32 v188, 0xbfb8aa3b, v24
	v_mul_f32_e32 v189, 0xbfb8aa3b, v25
	v_mul_f32_e32 v190, 0xbfb8aa3b, v26
	v_mul_f32_e32 v191, 0xbfb8aa3b, v27
	v_exp_f32_e32 v184, v184
	v_exp_f32_e32 v185, v185
	v_exp_f32_e32 v186, v186
	v_exp_f32_e32 v187, v187
	v_exp_f32_e32 v188, v188
	v_exp_f32_e32 v189, v189
	v_exp_f32_e32 v190, v190
	v_exp_f32_e32 v191, v191
	v_sub_f32_e32 v192, 1.0, v152
	v_sub_f32_e32 v193, 1.0, v153
	v_sub_f32_e32 v194, 1.0, v154
	v_sub_f32_e32 v195, 1.0, v155
	v_sub_f32_e32 v196, 1.0, v180
	v_sub_f32_e32 v197, 1.0, v181
	v_sub_f32_e32 v198, 1.0, v182
	v_sub_f32_e32 v199, 1.0, v183
	v_add_f32_e32 v184, 1.0, v184
	v_add_f32_e32 v185, 1.0, v185
	v_add_f32_e32 v186, 1.0, v186
	v_add_f32_e32 v187, 1.0, v187
	v_add_f32_e32 v188, 1.0, v188
	v_add_f32_e32 v189, 1.0, v189
	v_add_f32_e32 v190, 1.0, v190
	v_add_f32_e32 v191, 1.0, v191
	v_rcp_f32_e32 v184, v184
	v_rcp_f32_e32 v185, v185
	v_rcp_f32_e32 v186, v186
	v_rcp_f32_e32 v187, v187
	v_rcp_f32_e32 v188, v188
	v_rcp_f32_e32 v189, v189
	v_rcp_f32_e32 v190, v190
	v_rcp_f32_e32 v191, v191
	v_fma_f32 v200, v184, v192, v152
	v_fma_f32 v201, v185, v193, v153
	v_fma_f32 v202, v186, v194, v154
	v_fma_f32 v203, v187, v195, v155
	v_fma_f32 v204, v188, v196, v180
	v_fma_f32 v205, v189, v197, v181
	v_fma_f32 v206, v190, v198, v182
	v_fma_f32 v207, v191, v199, v183
	v_cmp_gt_f32_e64 vcc, s35, v200
	v_cmp_gt_f32_e64 s[38:39], s35, v201
	v_cmp_gt_f32_e64 s[48:49], s35, v202
	v_cmp_gt_f32_e64 s[50:51], s35, v203
	v_cndmask_b32_e64 v184, 0, 32, vcc
	v_cndmask_b32_e64 v185, 0, 32, s[38:39]
	v_cndmask_b32_e64 v186, 0, 32, s[48:49]
	v_cndmask_b32_e64 v187, 0, 32, s[50:51]
	v_cndmask_b32_e64 v192, 0, v214, vcc
	v_cndmask_b32_e64 v193, 0, v214, s[38:39]
	v_cndmask_b32_e64 v194, 0, v214, s[48:49]
	v_cndmask_b32_e64 v195, 0, v214, s[50:51]
	v_cmp_gt_f32_e64 vcc, s35, v204
	v_cmp_gt_f32_e64 s[38:39], s35, v205
	v_cmp_gt_f32_e64 s[48:49], s35, v206
	v_cmp_gt_f32_e64 s[50:51], s35, v207
	v_cndmask_b32_e64 v188, 0, 32, vcc
	v_cndmask_b32_e64 v189, 0, 32, s[38:39]
	v_cndmask_b32_e64 v190, 0, 32, s[48:49]
	v_cndmask_b32_e64 v191, 0, 32, s[50:51]
	v_cndmask_b32_e64 v196, 0, v214, vcc
	v_cndmask_b32_e64 v197, 0, v214, s[38:39]
	v_cndmask_b32_e64 v198, 0, v214, s[48:49]
	v_cndmask_b32_e64 v199, 0, v214, s[50:51]
	v_ldexp_f32 v184, v200, v184
	v_ldexp_f32 v185, v201, v185
	v_ldexp_f32 v186, v202, v186
	v_ldexp_f32 v187, v203, v187
	v_ldexp_f32 v188, v204, v188
	v_ldexp_f32 v189, v205, v189
	v_ldexp_f32 v190, v206, v190
	v_ldexp_f32 v191, v207, v191
	v_log_f32_e32 v184, v184
	v_log_f32_e32 v185, v185
	v_log_f32_e32 v186, v186
	v_log_f32_e32 v187, v187
	v_log_f32_e32 v188, v188
	v_log_f32_e32 v189, v189
	v_log_f32_e32 v190, v190
	v_log_f32_e32 v191, v191
	v_mul_f32_e32 v200, 0x3f317217, v184
	v_mul_f32_e32 v201, 0x3f317217, v185
	v_mul_f32_e32 v202, 0x3f317217, v186
	v_mul_f32_e32 v203, 0x3f317217, v187
	v_mul_f32_e32 v204, 0x3f317217, v188
	v_mul_f32_e32 v205, 0x3f317217, v189
	v_mul_f32_e32 v206, 0x3f317217, v190
	v_mul_f32_e32 v207, 0x3f317217, v191
	v_fma_f32 v200, v184, s13, -v200
	v_fma_f32 v201, v185, s13, -v201
	v_fma_f32 v202, v186, s13, -v202
	v_fma_f32 v203, v187, s13, -v203
	v_fma_f32 v204, v188, s13, -v204
	v_fma_f32 v205, v189, s13, -v205
	v_fma_f32 v206, v190, s13, -v206
	v_fma_f32 v207, v191, s13, -v207
	v_fmac_f32_e32 v200, 0x3377d1cf, v184
	v_fmac_f32_e32 v201, 0x3377d1cf, v185
	v_fmac_f32_e32 v202, 0x3377d1cf, v186
	v_fmac_f32_e32 v203, 0x3377d1cf, v187
	v_fmac_f32_e32 v204, 0x3377d1cf, v188
	v_fmac_f32_e32 v205, 0x3377d1cf, v189
	v_fmac_f32_e32 v206, 0x3377d1cf, v190
	v_fmac_f32_e32 v207, 0x3377d1cf, v191
	v_fmac_f32_e32 v200, 0x3f317217, v184
	v_fmac_f32_e32 v201, 0x3f317217, v185
	v_fmac_f32_e32 v202, 0x3f317217, v186
	v_fmac_f32_e32 v203, 0x3f317217, v187
; __device__ __forceinline__ unsigned cvt_pk_bf16(float lo, float hi) { unsigned r; asm volatile("v_cvt_pk_bf16_f32 %0, %1, %2" : "=v"(r) : "v"(lo), "v"(hi)); return r; }
; __device__ __forceinline__ float silu_f(float v) { return v * __builtin_amdgcn_rcpf(1.f + __expf(-v)); }
;     __device__ __forceinline__ void operator()(const f32x4 (&acc)[2][2][4][2], const Unit& u, int wr, int wc, int fr, int fq, int ui, PG8_LAS unsigned char* lds) const {
;     ...
;                     f32x4 v[2] = {acc[ai][bj][m][0] * rs, acc[ai][bj][m][1] * rs};
;                     if (ksum) { csum[bj][0] += v[0]; csum[bj][1] += v[1]; }
; #pragma unroll
;                     for (int n = 0; n < 2; ++n) {
;                         f32x4 lbv = (f32x4){0.f, 0.f, 0.f, 0.f};
;                         if (act == 2) lbv = *(const f32x4*)(lb + (col0 - 1024) + bj * HALF + 4 * n);
; #pragma unroll
;                         for (int e = 0; e < 4; ++e) {
;                             float x = v[n][e];
;                             if (act == 1) x = silu_f(x);
;                             else if (act == 2) { const float l = lbv[e]; x = __logf(l + (1.f - l) * __builtin_amdgcn_rcpf(1.f + __expf(-x))); }
;                             else if (act == 3) { x = fmaxf(x, 0.f); x = x * x; }
;                             v[n][e] = x;
;                         }
;                     }
;                     u32x4 w; w.x = cvt_pk_bf16(v[0][0], v[0][1]); w.y = cvt_pk_bf16(v[0][2], v[0][3]); w.z = cvt_pk_bf16(v[1][0], v[1][1]); w.w = cvt_pk_bf16(v[1][2], v[1][3]);
;                     *(u32x4*)(rowp + bj * HALF) = w;
	v_fmac_f32_e32 v204, 0x3f317217, v188
	v_fmac_f32_e32 v205, 0x3f317217, v189
	v_fmac_f32_e32 v206, 0x3f317217, v190
	v_fmac_f32_e32 v207, 0x3f317217, v191
	v_cmp_lt_f32_e64 vcc, |v184|, s36
	v_cmp_lt_f32_e64 s[38:39], |v185|, s36
	v_cmp_lt_f32_e64 s[48:49], |v186|, s36
	v_cmp_lt_f32_e64 s[50:51], |v187|, s36
	v_cndmask_b32_e64 v184, v184, v200, vcc
	v_cndmask_b32_e64 v185, v185, v201, s[38:39]
	v_cndmask_b32_e64 v186, v186, v202, s[48:49]
	v_cndmask_b32_e64 v187, v187, v203, s[50:51]
	v_cmp_lt_f32_e64 vcc, |v188|, s36
	v_cmp_lt_f32_e64 s[38:39], |v189|, s36
	v_cmp_lt_f32_e64 s[48:49], |v190|, s36
	v_cmp_lt_f32_e64 s[50:51], |v191|, s36
	v_cndmask_b32_e64 v188, v188, v204, vcc
	v_cndmask_b32_e64 v189, v189, v205, s[38:39]
	v_cndmask_b32_e64 v190, v190, v206, s[48:49]
	v_cndmask_b32_e64 v191, v191, v207, s[50:51]
	v_sub_f32_e32 v28, v184, v192
	v_sub_f32_e32 v29, v185, v193
	v_sub_f32_e32 v30, v186, v194
	v_sub_f32_e32 v31, v187, v195
	v_sub_f32_e32 v24, v188, v196
	v_sub_f32_e32 v25, v189, v197
	v_sub_f32_e32 v26, v190, v198
	v_sub_f32_e32 v27, v191, v199
	v_cvt_pk_bf16_f32 v28, v28, v29
	v_cvt_pk_bf16_f32 v29, v30, v31
	v_cvt_pk_bf16_f32 v30, v24, v25
	v_cvt_pk_bf16_f32 v31, v26, v27
	global_store_dwordx4 v[162:163], v[28:31], off
	v_pk_mul_f32 v[20:21], v[20:21], v[158:159] op_sel_hi:[1,0]
	v_pk_mul_f32 v[22:23], v[22:23], v[158:159] op_sel_hi:[1,0]
	v_pk_mul_f32 v[16:17], v[16:17], v[158:159] op_sel_hi:[1,0]
	v_pk_mul_f32 v[18:19], v[18:19], v[158:159] op_sel_hi:[1,0]
	v_mul_f32_e32 v184, 0xbfb8aa3b, v20
	v_mul_f32_e32 v185, 0xbfb8aa3b, v21
	v_mul_f32_e32 v186, 0xbfb8aa3b, v22
	v_mul_f32_e32 v187, 0xbfb8aa3b, v23
	v_mul_f32_e32 v188, 0xbfb8aa3b, v16
	v_mul_f32_e32 v189, 0xbfb8aa3b, v17
	v_mul_f32_e32 v190, 0xbfb8aa3b, v18
	v_mul_f32_e32 v191, 0xbfb8aa3b, v19
	v_exp_f32_e32 v184, v184
	v_exp_f32_e32 v185, v185
	v_exp_f32_e32 v186, v186
	v_exp_f32_e32 v187, v187
	v_exp_f32_e32 v188, v188
	v_exp_f32_e32 v189, v189
	v_exp_f32_e32 v190, v190
	v_exp_f32_e32 v191, v191
	v_sub_f32_e32 v192, 1.0, v218
	v_sub_f32_e32 v193, 1.0, v219
	v_sub_f32_e32 v194, 1.0, v220
	v_sub_f32_e32 v195, 1.0, v221
	v_sub_f32_e32 v196, 1.0, v222
	v_sub_f32_e32 v197, 1.0, v223
	v_sub_f32_e32 v198, 1.0, v224
	v_sub_f32_e32 v199, 1.0, v225
	v_add_f32_e32 v184, 1.0, v184
	v_add_f32_e32 v185, 1.0, v185
	v_add_f32_e32 v186, 1.0, v186
	v_add_f32_e32 v187, 1.0, v187
	v_add_f32_e32 v188, 1.0, v188
	v_add_f32_e32 v189, 1.0, v189
	v_add_f32_e32 v190, 1.0, v190
	v_add_f32_e32 v191, 1.0, v191
	v_rcp_f32_e32 v184, v184
	v_rcp_f32_e32 v185, v185
	v_rcp_f32_e32 v186, v186
	v_rcp_f32_e32 v187, v187
	v_rcp_f32_e32 v188, v188
	v_rcp_f32_e32 v189, v189
	v_rcp_f32_e32 v190, v190
	v_rcp_f32_e32 v191, v191
	v_fma_f32 v200, v184, v192, v218
	v_fma_f32 v201, v185, v193, v219
	v_fma_f32 v202, v186, v194, v220
	v_fma_f32 v203, v187, v195, v221
	v_fma_f32 v204, v188, v196, v222
	v_fma_f32 v205, v189, v197, v223
	v_fma_f32 v206, v190, v198, v224
	v_fma_f32 v207, v191, v199, v225
	v_cmp_gt_f32_e64 vcc, s35, v200
	v_cmp_gt_f32_e64 s[38:39], s35, v201
	v_cmp_gt_f32_e64 s[48:49], s35, v202
	v_cmp_gt_f32_e64 s[50:51], s35, v203
	v_cndmask_b32_e64 v184, 0, 32, vcc
	v_cndmask_b32_e64 v185, 0, 32, s[38:39]
	v_cndmask_b32_e64 v186, 0, 32, s[48:49]
	v_cndmask_b32_e64 v187, 0, 32, s[50:51]
	v_cndmask_b32_e64 v192, 0, v214, vcc
	v_cndmask_b32_e64 v193, 0, v214, s[38:39]
	v_cndmask_b32_e64 v194, 0, v214, s[48:49]
	v_cndmask_b32_e64 v195, 0, v214, s[50:51]
	v_cmp_gt_f32_e64 vcc, s35, v204
	v_cmp_gt_f32_e64 s[38:39], s35, v205
	v_cmp_gt_f32_e64 s[48:49], s35, v206
	v_cmp_gt_f32_e64 s[50:51], s35, v207
	v_cndmask_b32_e64 v188, 0, 32, vcc
	v_cndmask_b32_e64 v189, 0, 32, s[38:39]
	v_cndmask_b32_e64 v190, 0, 32, s[48:49]
	v_cndmask_b32_e64 v191, 0, 32, s[50:51]
	v_cndmask_b32_e64 v196, 0, v214, vcc
	v_cndmask_b32_e64 v197, 0, v214, s[38:39]
	v_cndmask_b32_e64 v198, 0, v214, s[48:49]
	v_cndmask_b32_e64 v199, 0, v214, s[50:51]
	v_ldexp_f32 v184, v200, v184
	v_ldexp_f32 v185, v201, v185
	v_ldexp_f32 v186, v202, v186
	v_ldexp_f32 v187, v203, v187
	v_ldexp_f32 v188, v204, v188
	v_ldexp_f32 v189, v205, v189
	v_ldexp_f32 v190, v206, v190
	v_ldexp_f32 v191, v207, v191
	v_log_f32_e32 v184, v184
	v_log_f32_e32 v185, v185
	v_log_f32_e32 v186, v186
	v_log_f32_e32 v187, v187
	v_log_f32_e32 v188, v188
	v_log_f32_e32 v189, v189
	v_log_f32_e32 v190, v190
	v_log_f32_e32 v191, v191
	v_mul_f32_e32 v200, 0x3f317217, v184
	v_mul_f32_e32 v201, 0x3f317217, v185
	v_mul_f32_e32 v202, 0x3f317217, v186
	v_mul_f32_e32 v203, 0x3f317217, v187
	v_mul_f32_e32 v204, 0x3f317217, v188
	v_mul_f32_e32 v205, 0x3f317217, v189
	v_mul_f32_e32 v206, 0x3f317217, v190
	v_mul_f32_e32 v207, 0x3f317217, v191
	v_fma_f32 v200, v184, s13, -v200
	v_fma_f32 v201, v185, s13, -v201
	v_fma_f32 v202, v186, s13, -v202
	v_fma_f32 v203, v187, s13, -v203
	v_fma_f32 v204, v188, s13, -v204
	v_fma_f32 v205, v189, s13, -v205
	v_fma_f32 v206, v190, s13, -v206
	v_fma_f32 v207, v191, s13, -v207
	v_fmac_f32_e32 v200, 0x3377d1cf, v184
	v_fmac_f32_e32 v201, 0x3377d1cf, v185
	v_fmac_f32_e32 v202, 0x3377d1cf, v186
	v_fmac_f32_e32 v203, 0x3377d1cf, v187
	v_fmac_f32_e32 v204, 0x3377d1cf, v188
	v_fmac_f32_e32 v205, 0x3377d1cf, v189
	v_fmac_f32_e32 v206, 0x3377d1cf, v190
	v_fmac_f32_e32 v207, 0x3377d1cf, v191
	v_fmac_f32_e32 v200, 0x3f317217, v184
	v_fmac_f32_e32 v201, 0x3f317217, v185
	v_fmac_f32_e32 v202, 0x3f317217, v186
	v_fmac_f32_e32 v203, 0x3f317217, v187
	v_fmac_f32_e32 v204, 0x3f317217, v188
	v_fmac_f32_e32 v205, 0x3f317217, v189
	v_fmac_f32_e32 v206, 0x3f317217, v190
	v_fmac_f32_e32 v207, 0x3f317217, v191
	v_cmp_lt_f32_e64 vcc, |v184|, s36
	v_cmp_lt_f32_e64 s[38:39], |v185|, s36
; __device__ __forceinline__ unsigned cvt_pk_bf16(float lo, float hi) { unsigned r; asm volatile("v_cvt_pk_bf16_f32 %0, %1, %2" : "=v"(r) : "v"(lo), "v"(hi)); return r; }
; __device__ __forceinline__ float silu_f(float v) { return v * __builtin_amdgcn_rcpf(1.f + __expf(-v)); }
;     __device__ __forceinline__ void operator()(const f32x4 (&acc)[2][2][4][2], const Unit& u, int wr, int wc, int fr, int fq, int ui, PG8_LAS unsigned char* lds) const {
;     ...
;                     f32x4 v[2] = {acc[ai][bj][m][0] * rs, acc[ai][bj][m][1] * rs};
;                     if (ksum) { csum[bj][0] += v[0]; csum[bj][1] += v[1]; }
; #pragma unroll
;                     for (int n = 0; n < 2; ++n) {
;                         f32x4 lbv = (f32x4){0.f, 0.f, 0.f, 0.f};
;                         if (act == 2) lbv = *(const f32x4*)(lb + (col0 - 1024) + bj * HALF + 4 * n);
; #pragma unroll
;                         for (int e = 0; e < 4; ++e) {
;                             float x = v[n][e];
;                             if (act == 1) x = silu_f(x);
;                             else if (act == 2) { const float l = lbv[e]; x = __logf(l + (1.f - l) * __builtin_amdgcn_rcpf(1.f + __expf(-x))); }
;                             else if (act == 3) { x = fmaxf(x, 0.f); x = x * x; }
;                             v[n][e] = x;
;                         }
;                     }
;                     u32x4 w; w.x = cvt_pk_bf16(v[0][0], v[0][1]); w.y = cvt_pk_bf16(v[0][2], v[0][3]); w.z = cvt_pk_bf16(v[1][0], v[1][1]); w.w = cvt_pk_bf16(v[1][2], v[1][3]);
;                     *(u32x4*)(rowp + bj * HALF) = w;
	v_cmp_lt_f32_e64 s[48:49], |v186|, s36
	v_cmp_lt_f32_e64 s[50:51], |v187|, s36
	v_cndmask_b32_e64 v184, v184, v200, vcc
	v_cndmask_b32_e64 v185, v185, v201, s[38:39]
	v_cndmask_b32_e64 v186, v186, v202, s[48:49]
	v_cndmask_b32_e64 v187, v187, v203, s[50:51]
	v_cmp_lt_f32_e64 vcc, |v188|, s36
	v_cmp_lt_f32_e64 s[38:39], |v189|, s36
	v_cmp_lt_f32_e64 s[48:49], |v190|, s36
	v_cmp_lt_f32_e64 s[50:51], |v191|, s36
	v_cndmask_b32_e64 v188, v188, v204, vcc
	v_cndmask_b32_e64 v189, v189, v205, s[38:39]
	v_cndmask_b32_e64 v190, v190, v206, s[48:49]
	v_cndmask_b32_e64 v191, v191, v207, s[50:51]
	v_sub_f32_e32 v20, v184, v192
	v_sub_f32_e32 v21, v185, v193
	v_sub_f32_e32 v22, v186, v194
	v_sub_f32_e32 v23, v187, v195
	v_sub_f32_e32 v16, v188, v196
	v_sub_f32_e32 v17, v189, v197
	v_sub_f32_e32 v18, v190, v198
	v_sub_f32_e32 v19, v191, v199
	v_cvt_pk_bf16_f32 v20, v20, v21
	v_cvt_pk_bf16_f32 v21, v22, v23
	v_cvt_pk_bf16_f32 v22, v16, v17
	v_cvt_pk_bf16_f32 v23, v18, v19
	global_store_dwordx4 v[162:163], v[20:23], off offset:256
	v_lshl_add_u64 v[176:177], v[162:163], 0, s[46:47]
	v_pk_mul_f32 v[12:13], v[12:13], v[160:161] op_sel_hi:[1,0]
	v_pk_mul_f32 v[14:15], v[14:15], v[160:161] op_sel_hi:[1,0]
	v_pk_mul_f32 v[8:9], v[8:9], v[160:161] op_sel_hi:[1,0]
	v_pk_mul_f32 v[10:11], v[10:11], v[160:161] op_sel_hi:[1,0]
	v_mul_f32_e32 v184, 0xbfb8aa3b, v12
	v_mul_f32_e32 v185, 0xbfb8aa3b, v13
	v_mul_f32_e32 v186, 0xbfb8aa3b, v14
	v_mul_f32_e32 v187, 0xbfb8aa3b, v15
	v_mul_f32_e32 v188, 0xbfb8aa3b, v8
	v_mul_f32_e32 v189, 0xbfb8aa3b, v9
	v_mul_f32_e32 v190, 0xbfb8aa3b, v10
	v_mul_f32_e32 v191, 0xbfb8aa3b, v11
	v_exp_f32_e32 v184, v184
	v_exp_f32_e32 v185, v185
	v_exp_f32_e32 v186, v186
	v_exp_f32_e32 v187, v187
	v_exp_f32_e32 v188, v188
	v_exp_f32_e32 v189, v189
	v_exp_f32_e32 v190, v190
	v_exp_f32_e32 v191, v191
	v_sub_f32_e32 v192, 1.0, v152
	v_sub_f32_e32 v193, 1.0, v153
	v_sub_f32_e32 v194, 1.0, v154
	v_sub_f32_e32 v195, 1.0, v155
	v_sub_f32_e32 v196, 1.0, v180
	v_sub_f32_e32 v197, 1.0, v181
	v_sub_f32_e32 v198, 1.0, v182
	v_sub_f32_e32 v199, 1.0, v183
	v_add_f32_e32 v184, 1.0, v184
	v_add_f32_e32 v185, 1.0, v185
	v_add_f32_e32 v186, 1.0, v186
	v_add_f32_e32 v187, 1.0, v187
	v_add_f32_e32 v188, 1.0, v188
	v_add_f32_e32 v189, 1.0, v189
	v_add_f32_e32 v190, 1.0, v190
	v_add_f32_e32 v191, 1.0, v191
	v_rcp_f32_e32 v184, v184
	v_rcp_f32_e32 v185, v185
	v_rcp_f32_e32 v186, v186
	v_rcp_f32_e32 v187, v187
	v_rcp_f32_e32 v188, v188
	v_rcp_f32_e32 v189, v189
	v_rcp_f32_e32 v190, v190
	v_rcp_f32_e32 v191, v191
	v_fma_f32 v200, v184, v192, v152
	v_fma_f32 v201, v185, v193, v153
	v_fma_f32 v202, v186, v194, v154
	v_fma_f32 v203, v187, v195, v155
	v_fma_f32 v204, v188, v196, v180
	v_fma_f32 v205, v189, v197, v181
	v_fma_f32 v206, v190, v198, v182
	v_fma_f32 v207, v191, v199, v183
	v_cmp_gt_f32_e64 vcc, s35, v200
	v_cmp_gt_f32_e64 s[38:39], s35, v201
	v_cmp_gt_f32_e64 s[48:49], s35, v202
	v_cmp_gt_f32_e64 s[50:51], s35, v203
	v_cndmask_b32_e64 v184, 0, 32, vcc
	v_cndmask_b32_e64 v185, 0, 32, s[38:39]
	v_cndmask_b32_e64 v186, 0, 32, s[48:49]
	v_cndmask_b32_e64 v187, 0, 32, s[50:51]
	v_cndmask_b32_e64 v192, 0, v214, vcc
	v_cndmask_b32_e64 v193, 0, v214, s[38:39]
	v_cndmask_b32_e64 v194, 0, v214, s[48:49]
	v_cndmask_b32_e64 v195, 0, v214, s[50:51]
	v_cmp_gt_f32_e64 vcc, s35, v204
	v_cmp_gt_f32_e64 s[38:39], s35, v205
	v_cmp_gt_f32_e64 s[48:49], s35, v206
	v_cmp_gt_f32_e64 s[50:51], s35, v207
	v_cndmask_b32_e64 v188, 0, 32, vcc
	v_cndmask_b32_e64 v189, 0, 32, s[38:39]
	v_cndmask_b32_e64 v190, 0, 32, s[48:49]
	v_cndmask_b32_e64 v191, 0, 32, s[50:51]
	v_cndmask_b32_e64 v196, 0, v214, vcc
	v_cndmask_b32_e64 v197, 0, v214, s[38:39]
	v_cndmask_b32_e64 v198, 0, v214, s[48:49]
	v_cndmask_b32_e64 v199, 0, v214, s[50:51]
	v_ldexp_f32 v184, v200, v184
	v_ldexp_f32 v185, v201, v185
	v_ldexp_f32 v186, v202, v186
	v_ldexp_f32 v187, v203, v187
	v_ldexp_f32 v188, v204, v188
	v_ldexp_f32 v189, v205, v189
	v_ldexp_f32 v190, v206, v190
	v_ldexp_f32 v191, v207, v191
	v_log_f32_e32 v184, v184
	v_log_f32_e32 v185, v185
	v_log_f32_e32 v186, v186
	v_log_f32_e32 v187, v187
	v_log_f32_e32 v188, v188
	v_log_f32_e32 v189, v189
	v_log_f32_e32 v190, v190
	v_log_f32_e32 v191, v191
	v_mul_f32_e32 v200, 0x3f317217, v184
	v_mul_f32_e32 v201, 0x3f317217, v185
	v_mul_f32_e32 v202, 0x3f317217, v186
	v_mul_f32_e32 v203, 0x3f317217, v187
	v_mul_f32_e32 v204, 0x3f317217, v188
	v_mul_f32_e32 v205, 0x3f317217, v189
	v_mul_f32_e32 v206, 0x3f317217, v190
	v_mul_f32_e32 v207, 0x3f317217, v191
	v_fma_f32 v200, v184, s13, -v200
	v_fma_f32 v201, v185, s13, -v201
	v_fma_f32 v202, v186, s13, -v202
	v_fma_f32 v203, v187, s13, -v203
	v_fma_f32 v204, v188, s13, -v204
	v_fma_f32 v205, v189, s13, -v205
	v_fma_f32 v206, v190, s13, -v206
	v_fma_f32 v207, v191, s13, -v207
	v_fmac_f32_e32 v200, 0x3377d1cf, v184
	v_fmac_f32_e32 v201, 0x3377d1cf, v185
	v_fmac_f32_e32 v202, 0x3377d1cf, v186
	v_fmac_f32_e32 v203, 0x3377d1cf, v187
	v_fmac_f32_e32 v204, 0x3377d1cf, v188
	v_fmac_f32_e32 v205, 0x3377d1cf, v189
	v_fmac_f32_e32 v206, 0x3377d1cf, v190
	v_fmac_f32_e32 v207, 0x3377d1cf, v191
	v_fmac_f32_e32 v200, 0x3f317217, v184
	v_fmac_f32_e32 v201, 0x3f317217, v185
	v_fmac_f32_e32 v202, 0x3f317217, v186
	v_fmac_f32_e32 v203, 0x3f317217, v187
	v_fmac_f32_e32 v204, 0x3f317217, v188
	v_fmac_f32_e32 v205, 0x3f317217, v189
	v_fmac_f32_e32 v206, 0x3f317217, v190
	v_fmac_f32_e32 v207, 0x3f317217, v191
	v_cmp_lt_f32_e64 vcc, |v184|, s36
	v_cmp_lt_f32_e64 s[38:39], |v185|, s36
	v_cmp_lt_f32_e64 s[48:49], |v186|, s36
	v_cmp_lt_f32_e64 s[50:51], |v187|, s36
	v_cndmask_b32_e64 v184, v184, v200, vcc
	v_cndmask_b32_e64 v185, v185, v201, s[38:39]
; __device__ __forceinline__ unsigned cvt_pk_bf16(float lo, float hi) { unsigned r; asm volatile("v_cvt_pk_bf16_f32 %0, %1, %2" : "=v"(r) : "v"(lo), "v"(hi)); return r; }
; __device__ __forceinline__ float silu_f(float v) { return v * __builtin_amdgcn_rcpf(1.f + __expf(-v)); }
; #define PG8_BAR __builtin_amdgcn_s_barrier()
;     __device__ __forceinline__ void operator()(const f32x4 (&acc)[2][2][4][2], const Unit& u, int wr, int wc, int fr, int fq, int ui, PG8_LAS unsigned char* lds) const {
;     ...
;                     f32x4 v[2] = {acc[ai][bj][m][0] * rs, acc[ai][bj][m][1] * rs};
;                     if (ksum) { csum[bj][0] += v[0]; csum[bj][1] += v[1]; }
; #pragma unroll
;                     for (int n = 0; n < 2; ++n) {
;                         f32x4 lbv = (f32x4){0.f, 0.f, 0.f, 0.f};
;                         if (act == 2) lbv = *(const f32x4*)(lb + (col0 - 1024) + bj * HALF + 4 * n);
; #pragma unroll
;                         for (int e = 0; e < 4; ++e) {
;                             float x = v[n][e];
;                             if (act == 1) x = silu_f(x);
;                             else if (act == 2) { const float l = lbv[e]; x = __logf(l + (1.f - l) * __builtin_amdgcn_rcpf(1.f + __expf(-x))); }
;                             else if (act == 3) { x = fmaxf(x, 0.f); x = x * x; }
;                             v[n][e] = x;
;                         }
;                     }
;                     u32x4 w; w.x = cvt_pk_bf16(v[0][0], v[0][1]); w.y = cvt_pk_bf16(v[0][2], v[0][3]); w.z = cvt_pk_bf16(v[1][0], v[1][1]); w.w = cvt_pk_bf16(v[1][2], v[1][3]);
;                     *(u32x4*)(rowp + bj * HALF) = w;
; template <class Epi, class Sched, bool ALIGN_EPI = false, bool SP2 = false>
; __device__ __forceinline__ void gemm_phase(PG8_LAS unsigned char* lds, const Gemm g, const Sched& S, const Epi& E) {
;     ...
;         if constexpr (ALIGN_EPI) { if (wr == 0) PG8_BAR; }
	v_cndmask_b32_e64 v186, v186, v202, s[48:49]
	v_cndmask_b32_e64 v187, v187, v203, s[50:51]
	v_cmp_lt_f32_e64 vcc, |v188|, s36
	v_cmp_lt_f32_e64 s[38:39], |v189|, s36
	v_cmp_lt_f32_e64 s[48:49], |v190|, s36
	v_cmp_lt_f32_e64 s[50:51], |v191|, s36
	v_cndmask_b32_e64 v188, v188, v204, vcc
	v_cndmask_b32_e64 v189, v189, v205, s[38:39]
	v_cndmask_b32_e64 v190, v190, v206, s[48:49]
	v_cndmask_b32_e64 v191, v191, v207, s[50:51]
	v_sub_f32_e32 v12, v184, v192
	v_sub_f32_e32 v13, v185, v193
	v_sub_f32_e32 v14, v186, v194
	v_sub_f32_e32 v15, v187, v195
	v_sub_f32_e32 v8, v188, v196
	v_sub_f32_e32 v9, v189, v197
	v_sub_f32_e32 v10, v190, v198
	v_sub_f32_e32 v11, v191, v199
	v_cvt_pk_bf16_f32 v12, v12, v13
	v_cvt_pk_bf16_f32 v13, v14, v15
	v_cvt_pk_bf16_f32 v14, v8, v9
	v_cvt_pk_bf16_f32 v15, v10, v11
	global_store_dwordx4 v[176:177], v[12:15], off
	v_pk_mul_f32 v[4:5], v[4:5], v[160:161] op_sel_hi:[1,0]
	v_pk_mul_f32 v[6:7], v[6:7], v[160:161] op_sel_hi:[1,0]
	v_pk_mul_f32 v[0:1], v[0:1], v[160:161] op_sel_hi:[1,0]
	v_pk_mul_f32 v[2:3], v[2:3], v[160:161] op_sel_hi:[1,0]
	v_mul_f32_e32 v184, 0xbfb8aa3b, v4
	v_mul_f32_e32 v185, 0xbfb8aa3b, v5
	v_mul_f32_e32 v186, 0xbfb8aa3b, v6
	v_mul_f32_e32 v187, 0xbfb8aa3b, v7
	v_mul_f32_e32 v188, 0xbfb8aa3b, v0
	v_mul_f32_e32 v189, 0xbfb8aa3b, v1
	v_mul_f32_e32 v190, 0xbfb8aa3b, v2
	v_mul_f32_e32 v191, 0xbfb8aa3b, v3
	v_exp_f32_e32 v184, v184
	v_exp_f32_e32 v185, v185
	v_exp_f32_e32 v186, v186
	v_exp_f32_e32 v187, v187
	v_exp_f32_e32 v188, v188
	v_exp_f32_e32 v189, v189
	v_exp_f32_e32 v190, v190
	v_exp_f32_e32 v191, v191
	v_sub_f32_e32 v192, 1.0, v218
	v_sub_f32_e32 v193, 1.0, v219
	v_sub_f32_e32 v194, 1.0, v220
	v_sub_f32_e32 v195, 1.0, v221
	v_sub_f32_e32 v196, 1.0, v222
	v_sub_f32_e32 v197, 1.0, v223
	v_sub_f32_e32 v198, 1.0, v224
	v_sub_f32_e32 v199, 1.0, v225
	v_add_f32_e32 v184, 1.0, v184
	v_add_f32_e32 v185, 1.0, v185
	v_add_f32_e32 v186, 1.0, v186
	v_add_f32_e32 v187, 1.0, v187
	v_add_f32_e32 v188, 1.0, v188
	v_add_f32_e32 v189, 1.0, v189
	v_add_f32_e32 v190, 1.0, v190
	v_add_f32_e32 v191, 1.0, v191
	v_rcp_f32_e32 v184, v184
	v_rcp_f32_e32 v185, v185
	v_rcp_f32_e32 v186, v186
	v_rcp_f32_e32 v187, v187
	v_rcp_f32_e32 v188, v188
	v_rcp_f32_e32 v189, v189
	v_rcp_f32_e32 v190, v190
	v_rcp_f32_e32 v191, v191
	v_fma_f32 v200, v184, v192, v218
	v_fma_f32 v201, v185, v193, v219
	v_fma_f32 v202, v186, v194, v220
	v_fma_f32 v203, v187, v195, v221
	v_fma_f32 v204, v188, v196, v222
	v_fma_f32 v205, v189, v197, v223
	v_fma_f32 v206, v190, v198, v224
	v_fma_f32 v207, v191, v199, v225
	v_cmp_gt_f32_e64 vcc, s35, v200
	v_cmp_gt_f32_e64 s[38:39], s35, v201
	v_cmp_gt_f32_e64 s[48:49], s35, v202
	v_cmp_gt_f32_e64 s[50:51], s35, v203
	v_cndmask_b32_e64 v184, 0, 32, vcc
	v_cndmask_b32_e64 v185, 0, 32, s[38:39]
	v_cndmask_b32_e64 v186, 0, 32, s[48:49]
	v_cndmask_b32_e64 v187, 0, 32, s[50:51]
	v_cndmask_b32_e64 v192, 0, v214, vcc
	v_cndmask_b32_e64 v193, 0, v214, s[38:39]
	v_cndmask_b32_e64 v194, 0, v214, s[48:49]
	v_cndmask_b32_e64 v195, 0, v214, s[50:51]
	v_cmp_gt_f32_e64 vcc, s35, v204
	v_cmp_gt_f32_e64 s[38:39], s35, v205
	v_cmp_gt_f32_e64 s[48:49], s35, v206
	v_cmp_gt_f32_e64 s[50:51], s35, v207
	v_cndmask_b32_e64 v188, 0, 32, vcc
	v_cndmask_b32_e64 v189, 0, 32, s[38:39]
	v_cndmask_b32_e64 v190, 0, 32, s[48:49]
	v_cndmask_b32_e64 v191, 0, 32, s[50:51]
	v_cndmask_b32_e64 v196, 0, v214, vcc
	v_cndmask_b32_e64 v197, 0, v214, s[38:39]
	v_cndmask_b32_e64 v198, 0, v214, s[48:49]
	v_cndmask_b32_e64 v199, 0, v214, s[50:51]
	v_ldexp_f32 v184, v200, v184
	v_ldexp_f32 v185, v201, v185
	v_ldexp_f32 v186, v202, v186
	v_ldexp_f32 v187, v203, v187
	v_ldexp_f32 v188, v204, v188
	v_ldexp_f32 v189, v205, v189
	v_ldexp_f32 v190, v206, v190
	v_ldexp_f32 v191, v207, v191
	v_log_f32_e32 v184, v184
	v_log_f32_e32 v185, v185
	v_log_f32_e32 v186, v186
	v_log_f32_e32 v187, v187
	v_log_f32_e32 v188, v188
	v_log_f32_e32 v189, v189
	v_log_f32_e32 v190, v190
	v_log_f32_e32 v191, v191
	v_mul_f32_e32 v200, 0x3f317217, v184
	v_mul_f32_e32 v201, 0x3f317217, v185
	v_mul_f32_e32 v202, 0x3f317217, v186
	v_mul_f32_e32 v203, 0x3f317217, v187
	v_mul_f32_e32 v204, 0x3f317217, v188
	v_mul_f32_e32 v205, 0x3f317217, v189
	v_mul_f32_e32 v206, 0x3f317217, v190
	v_mul_f32_e32 v207, 0x3f317217, v191
	v_fma_f32 v200, v184, s13, -v200
	v_fma_f32 v201, v185, s13, -v201
	v_fma_f32 v202, v186, s13, -v202
	v_fma_f32 v203, v187, s13, -v203
	v_fma_f32 v204, v188, s13, -v204
	v_fma_f32 v205, v189, s13, -v205
	v_fma_f32 v206, v190, s13, -v206
	v_fma_f32 v207, v191, s13, -v207
	v_fmac_f32_e32 v200, 0x3377d1cf, v184
	v_fmac_f32_e32 v201, 0x3377d1cf, v185
	v_fmac_f32_e32 v202, 0x3377d1cf, v186
	v_fmac_f32_e32 v203, 0x3377d1cf, v187
	v_fmac_f32_e32 v204, 0x3377d1cf, v188
	v_fmac_f32_e32 v205, 0x3377d1cf, v189
	v_fmac_f32_e32 v206, 0x3377d1cf, v190
	v_fmac_f32_e32 v207, 0x3377d1cf, v191
	v_fmac_f32_e32 v200, 0x3f317217, v184
	v_fmac_f32_e32 v201, 0x3f317217, v185
	v_fmac_f32_e32 v202, 0x3f317217, v186
	v_fmac_f32_e32 v203, 0x3f317217, v187
	v_fmac_f32_e32 v204, 0x3f317217, v188
	v_fmac_f32_e32 v205, 0x3f317217, v189
	v_fmac_f32_e32 v206, 0x3f317217, v190
	v_fmac_f32_e32 v207, 0x3f317217, v191
	v_cmp_lt_f32_e64 vcc, |v184|, s36
	v_cmp_lt_f32_e64 s[38:39], |v185|, s36
	v_cmp_lt_f32_e64 s[48:49], |v186|, s36
	v_cmp_lt_f32_e64 s[50:51], |v187|, s36
	v_cndmask_b32_e64 v184, v184, v200, vcc
	v_cndmask_b32_e64 v185, v185, v201, s[38:39]
	v_cndmask_b32_e64 v186, v186, v202, s[48:49]
	v_cndmask_b32_e64 v187, v187, v203, s[50:51]
	v_cmp_lt_f32_e64 vcc, |v188|, s36
	v_cmp_lt_f32_e64 s[38:39], |v189|, s36
	v_cmp_lt_f32_e64 s[48:49], |v190|, s36
	v_cmp_lt_f32_e64 s[50:51], |v191|, s36
	v_cndmask_b32_e64 v188, v188, v204, vcc
	v_cndmask_b32_e64 v189, v189, v205, s[38:39]
	v_cndmask_b32_e64 v190, v190, v206, s[48:49]
	v_cndmask_b32_e64 v191, v191, v207, s[50:51]
	v_sub_f32_e32 v4, v184, v192
	v_sub_f32_e32 v5, v185, v193
	v_sub_f32_e32 v6, v186, v194
	v_sub_f32_e32 v7, v187, v195
	v_sub_f32_e32 v0, v188, v196
	v_sub_f32_e32 v1, v189, v197
	v_sub_f32_e32 v2, v190, v198
	v_sub_f32_e32 v3, v191, v199
	v_cvt_pk_bf16_f32 v4, v4, v5
	v_cvt_pk_bf16_f32 v5, v6, v7
	v_cvt_pk_bf16_f32 v6, v0, v1
	v_cvt_pk_bf16_f32 v7, v2, v3
	global_store_dwordx4 v[176:177], v[4:7], off offset:256
	s_branch .LBB0_1108
.Lepi_generic:
	s_cmp_eq_u64 s[68:69], 0
	s_cbranch_scc1 .Lal1ge_skip
	s_barrier

; #define PG8_STAGE(bufoff, gbase, voff) do { _Pragma("unroll") for (int _i = 0; _i < 2; ++_i) \
;         __builtin_amdgcn_global_load_lds((const unsigned*)((const char*)(gbase) + (voff)[_i]), (PG8_LAS unsigned*)(lds + (bufoff) + ldsw + _i * 8192), 16, 0, 0); } while (0)
; #define PG8_LDA(dst, b, h) do { _Pragma("unroll") for (int m = 0; m < 4; ++m) _Pragma("unroll") for (int k = 0; k < 2; ++k) dst[m][k] = *(const PG8_LAS bf16x8*)(lds + PG8_SA(b, h) + aoff + m * 2048 + k * 1024); } while (0)
; #define PG8_LDB(dst, b, h) do { _Pragma("unroll") for (int n = 0; n < 2; ++n) _Pragma("unroll") for (int k = 0; k < 2; ++k) dst[n][k] = *(const PG8_LAS bf16x8*)(lds + PG8_SB(b, h) + boff + n * 2048 + k * 1024); } while (0)
; template <class Epi, class Sched, bool ALIGN_EPI = false, bool SP2 = false>
; __device__ __forceinline__ void gemm_phase(PG8_LAS unsigned char* lds, const Gemm g, const Sched& S, const Epi& E) {
;     ...
;         for (int t = 0; t < nt; t += 2) {
;             const bool last = (t == nt - 2);
;             const char* a1 = cA + (size_t)(t + 1) * kstep;
;             const char* a2 = last ? nA : cA + (size_t)(t + 2) * kstep; const char* b2 = last ? nB : cB + (size_t)(t + 2) * kstep;
;             const char* a3 = a2 + kstep; const char* b3 = b2 + kstep;
;             if (last && has_next) S.a_ready(nxt);
;             if constexpr (SP2) {
;             PG8_LDB(B0, 0, 0); PG8_LDB(B1, 0, 1); PG8_SCHED; PG8_LDA(At, 0, 0); PG8_STAGE(PG8_SA(1, 1), a1 + hstep, voffA);
;             PG8_WAIT_V(8); PG8_WAIT_L(0); PG8_BAR; PG8_MMA(0, 0, At, B0); PG8_MMA(0, 1, At, B1); PG8_BAR; PG8_SCHED;
;             PG8_LDA(At, 0, 1); PG8_STAGE(PG8_SB(0, 0), b2, voffB); PG8_STAGE(PG8_SB(0, 1), b2 + hstep, voffB); PG8_STAGE(PG8_SA(0, 0), a2, voffA);
;             PG8_WAIT_V(8); PG8_WAIT_L(0); PG8_BAR; PG8_MMA(1, 0, At, B0); PG8_MMA(1, 1, At, B1); PG8_BAR; PG8_SCHED;
;             PG8_LDB(B0, 1, 0); PG8_LDB(B1, 1, 1); PG8_SCHED; PG8_LDA(At, 1, 0); PG8_STAGE(PG8_SA(0, 1), a2 + hstep, voffA);
;             PG8_WAIT_V(8); PG8_WAIT_L(0); PG8_BAR; PG8_MMA(0, 0, At, B0); PG8_MMA(0, 1, At, B1); PG8_BAR; PG8_SCHED;
;             PG8_LDA(At, 1, 1); PG8_STAGE(PG8_SB(1, 0), b3, voffB); PG8_STAGE(PG8_SB(1, 1), b3 + hstep, voffB); PG8_STAGE(PG8_SA(1, 0), a3, voffA);
;             PG8_WAIT_V(8); PG8_WAIT_L(0); PG8_BAR; PG8_MMA(1, 0, At, B0); PG8_MMA(1, 1, At, B1); PG8_BAR; PG8_SCHED;
.LBB0_1641:
	s_add_i32 s78, s38, 2
	s_add_u32 s79, s0, 0x80
	s_addc_u32 s39, s1, 0
	s_add_i32 s93, 0, 0x10000
	s_cmp_eq_u32 s75, s38
	s_cselect_b32 s39, s63, s39
	s_cselect_b32 s38, s62, s79
	s_cselect_b32 s95, s65, s45
	s_cselect_b32 s94, s64, s44
	s_add_i32 s79, 0, 0x14000
	v_add_u32_e32 v68, s93, v218
	v_add_u32_e32 v156, s79, v218
	ds_read_b128 v[56:59], v68
	ds_read_b128 v[60:63], v68 offset:1024
	ds_read_b128 v[64:67], v68 offset:2048
	ds_read_b128 v[68:71], v68 offset:3072
	ds_read_b128 v[144:147], v156
	ds_read_b128 v[148:151], v156 offset:1024
	ds_read_b128 v[152:155], v156 offset:2048
	ds_read_b128 v[156:159], v156 offset:3072
	v_lshl_add_u64 v[172:173], s[0:1], 0, v[186:187]
	s_add_i32 m0, s9, 0xc000
	ds_read_b128 v[160:163], v220
	ds_read_b128 v[164:167], v220 offset:1024
	ds_read_b128 v[168:171], v220 offset:2048
	ds_read_b128 v[176:179], v220 offset:3072
	ds_read_b128 v[190:193], v220 offset:4096
	ds_read_b128 v[194:197], v220 offset:5120
	ds_read_b128 v[198:201], v220 offset:6144
	ds_read_b128 v[202:205], v220 offset:7168
	global_load_lds_dwordx4 v[172:173], off
	v_lshl_add_u64 v[172:173], s[0:1], 0, v[188:189]
	s_add_i32 m0, s9, 0xe000
	s_nop 0
	global_load_lds_dwordx4 v[172:173], off
	s_waitcnt vmcnt(8)
	s_waitcnt lgkmcnt(0)
	s_setprio 1
	s_barrier
	v_mfma_f32_16x16x32_bf16 v[140:143], v[56:59], v[160:163], v[140:143]
	v_mfma_f32_16x16x32_bf16 v[136:139], v[64:67], v[160:163], v[136:139]
	v_mfma_f32_16x16x32_bf16 v[124:127], v[56:59], v[168:171], v[124:127]
	v_mfma_f32_16x16x32_bf16 v[120:123], v[64:67], v[168:171], v[120:123]
	v_mfma_f32_16x16x32_bf16 v[108:111], v[56:59], v[190:193], v[108:111]
	v_mfma_f32_16x16x32_bf16 v[104:107], v[64:67], v[190:193], v[104:107]
	v_mfma_f32_16x16x32_bf16 v[92:95], v[56:59], v[198:201], v[92:95]
	v_mfma_f32_16x16x32_bf16 v[88:91], v[64:67], v[198:201], v[88:91]
	v_mfma_f32_16x16x32_bf16 v[140:143], v[60:63], v[164:167], v[140:143]
	v_mfma_f32_16x16x32_bf16 v[136:139], v[68:71], v[164:167], v[136:139]
	v_mfma_f32_16x16x32_bf16 v[124:127], v[60:63], v[176:179], v[124:127]
	v_mfma_f32_16x16x32_bf16 v[120:123], v[68:71], v[176:179], v[120:123]
	v_mfma_f32_16x16x32_bf16 v[108:111], v[60:63], v[194:197], v[108:111]
	v_mfma_f32_16x16x32_bf16 v[104:107], v[68:71], v[194:197], v[104:107]
	v_mfma_f32_16x16x32_bf16 v[92:95], v[60:63], v[202:205], v[92:95]
	v_mfma_f32_16x16x32_bf16 v[88:91], v[68:71], v[202:205], v[88:91]
	v_mfma_f32_16x16x32_bf16 v[132:135], v[144:147], v[160:163], v[132:135]
	v_mfma_f32_16x16x32_bf16 v[128:131], v[152:155], v[160:163], v[128:131]
	v_mfma_f32_16x16x32_bf16 v[116:119], v[144:147], v[168:171], v[116:119]
	v_mfma_f32_16x16x32_bf16 v[112:115], v[152:155], v[168:171], v[112:115]
	v_mfma_f32_16x16x32_bf16 v[100:103], v[144:147], v[190:193], v[100:103]
	v_mfma_f32_16x16x32_bf16 v[96:99], v[152:155], v[190:193], v[96:99]
	v_mfma_f32_16x16x32_bf16 v[84:87], v[144:147], v[198:201], v[84:87]
	v_mfma_f32_16x16x32_bf16 v[80:83], v[152:155], v[198:201], v[80:83]
	v_mfma_f32_16x16x32_bf16 v[132:135], v[148:151], v[164:167], v[132:135]
	v_mfma_f32_16x16x32_bf16 v[128:131], v[156:159], v[164:167], v[128:131]
	v_mfma_f32_16x16x32_bf16 v[116:119], v[148:151], v[176:179], v[116:119]
	v_mfma_f32_16x16x32_bf16 v[112:115], v[156:159], v[176:179], v[112:115]
	v_mfma_f32_16x16x32_bf16 v[100:103], v[148:151], v[194:197], v[100:103]
	v_mfma_f32_16x16x32_bf16 v[96:99], v[156:159], v[194:197], v[96:99]
	v_mfma_f32_16x16x32_bf16 v[84:87], v[148:151], v[202:205], v[84:87]
	v_mfma_f32_16x16x32_bf16 v[80:83], v[156:159], v[202:205], v[80:83]
	s_barrier
	s_setprio 0
	s_add_i32 s93, s93, s8
	v_lshl_add_u64 v[172:173], s[94:95], 0, v[174:175]
	s_mov_b32 m0, s93
	ds_read_b128 v[160:163], v220 offset:16384
	ds_read_b128 v[164:167], v220 offset:17408
	ds_read_b128 v[168:171], v220 offset:18432
	ds_read_b128 v[176:179], v220 offset:19456
	ds_read_b128 v[190:193], v220 offset:20480
	ds_read_b128 v[194:197], v220 offset:21504
	ds_read_b128 v[198:201], v220 offset:22528
	ds_read_b128 v[202:205], v220 offset:23552
	global_load_lds_dwordx4 v[172:173], off
	s_add_i32 m0, s93, 0x2000
	v_lshl_add_u64 v[206:207], s[94:95], 0, v[180:181]
	s_add_u32 s94, s94, s50
	s_addc_u32 s95, s95, 0
	s_add_i32 s79, s79, s8
	global_load_lds_dwordx4 v[206:207], off
	v_lshl_add_u64 v[208:209], s[94:95], 0, v[174:175]
	s_mov_b32 m0, s79
	v_lshl_add_u64 v[222:223], s[94:95], 0, v[180:181]
	global_load_lds_dwordx4 v[208:209], off
	s_add_i32 m0, s79, 0x2000
	v_lshl_add_u64 v[224:225], s[38:39], 0, v[184:185]
	global_load_lds_dwordx4 v[222:223], off
	s_mov_b32 m0, s9
	v_lshl_add_u64 v[226:227], s[38:39], 0, v[182:183]
	global_load_lds_dwordx4 v[224:225], off
	s_mov_b32 m0, s67
	s_nop 0
	global_load_lds_dwordx4 v[226:227], off
	s_waitcnt vmcnt(8)
	s_waitcnt lgkmcnt(0)
	s_setprio 1
	s_barrier
; #define PG8_STAGE(bufoff, gbase, voff) do { _Pragma("unroll") for (int _i = 0; _i < 2; ++_i) \
;         __builtin_amdgcn_global_load_lds((const unsigned*)((const char*)(gbase) + (voff)[_i]), (PG8_LAS unsigned*)(lds + (bufoff) + ldsw + _i * 8192), 16, 0, 0); } while (0)
; #define PG8_LDA(dst, b, h) do { _Pragma("unroll") for (int m = 0; m < 4; ++m) _Pragma("unroll") for (int k = 0; k < 2; ++k) dst[m][k] = *(const PG8_LAS bf16x8*)(lds + PG8_SA(b, h) + aoff + m * 2048 + k * 1024); } while (0)
; #define PG8_LDB(dst, b, h) do { _Pragma("unroll") for (int n = 0; n < 2; ++n) _Pragma("unroll") for (int k = 0; k < 2; ++k) dst[n][k] = *(const PG8_LAS bf16x8*)(lds + PG8_SB(b, h) + boff + n * 2048 + k * 1024); } while (0)
; template <class Epi, class Sched, bool ALIGN_EPI = false, bool SP2 = false>
; __device__ __forceinline__ void gemm_phase(PG8_LAS unsigned char* lds, const Gemm g, const Sched& S, const Epi& E) {
;     ...
;         for (int t = 0; t < nt; t += 2) {
;             const bool last = (t == nt - 2);
;             const char* a1 = cA + (size_t)(t + 1) * kstep;
;             const char* a2 = last ? nA : cA + (size_t)(t + 2) * kstep; const char* b2 = last ? nB : cB + (size_t)(t + 2) * kstep;
;             const char* a3 = a2 + kstep; const char* b3 = b2 + kstep;
;             if (last && has_next) S.a_ready(nxt);
;             if constexpr (SP2) {
;             PG8_LDB(B0, 0, 0); PG8_LDB(B1, 0, 1); PG8_SCHED; PG8_LDA(At, 0, 0); PG8_STAGE(PG8_SA(1, 1), a1 + hstep, voffA);
;             PG8_WAIT_V(8); PG8_WAIT_L(0); PG8_BAR; PG8_MMA(0, 0, At, B0); PG8_MMA(0, 1, At, B1); PG8_BAR; PG8_SCHED;
;             PG8_LDA(At, 0, 1); PG8_STAGE(PG8_SB(0, 0), b2, voffB); PG8_STAGE(PG8_SB(0, 1), b2 + hstep, voffB); PG8_STAGE(PG8_SA(0, 0), a2, voffA);
;             PG8_WAIT_V(8); PG8_WAIT_L(0); PG8_BAR; PG8_MMA(1, 0, At, B0); PG8_MMA(1, 1, At, B1); PG8_BAR; PG8_SCHED;
;             PG8_LDB(B0, 1, 0); PG8_LDB(B1, 1, 1); PG8_SCHED; PG8_LDA(At, 1, 0); PG8_STAGE(PG8_SA(0, 1), a2 + hstep, voffA);
;             PG8_WAIT_V(8); PG8_WAIT_L(0); PG8_BAR; PG8_MMA(0, 0, At, B0); PG8_MMA(0, 1, At, B1); PG8_BAR; PG8_SCHED;
;             PG8_LDA(At, 1, 1); PG8_STAGE(PG8_SB(1, 0), b3, voffB); PG8_STAGE(PG8_SB(1, 1), b3 + hstep, voffB); PG8_STAGE(PG8_SA(1, 0), a3, voffA);
;             PG8_WAIT_V(8); PG8_WAIT_L(0); PG8_BAR; PG8_MMA(1, 0, At, B0); PG8_MMA(1, 1, At, B1); PG8_BAR; PG8_SCHED;
	v_mfma_f32_16x16x32_bf16 v[76:79], v[56:59], v[160:163], v[76:79]
	v_mfma_f32_16x16x32_bf16 v[72:75], v[64:67], v[160:163], v[72:75]
	v_mfma_f32_16x16x32_bf16 v[44:47], v[56:59], v[168:171], v[44:47]
	v_mfma_f32_16x16x32_bf16 v[40:43], v[64:67], v[168:171], v[40:43]
	v_mfma_f32_16x16x32_bf16 v[28:31], v[56:59], v[190:193], v[28:31]
	v_mfma_f32_16x16x32_bf16 v[24:27], v[64:67], v[190:193], v[24:27]
	v_mfma_f32_16x16x32_bf16 v[12:15], v[56:59], v[198:201], v[12:15]
	v_mfma_f32_16x16x32_bf16 v[8:11], v[64:67], v[198:201], v[8:11]
	v_mfma_f32_16x16x32_bf16 v[76:79], v[60:63], v[164:167], v[76:79]
	v_mfma_f32_16x16x32_bf16 v[72:75], v[68:71], v[164:167], v[72:75]
	v_mfma_f32_16x16x32_bf16 v[44:47], v[60:63], v[176:179], v[44:47]
	v_mfma_f32_16x16x32_bf16 v[40:43], v[68:71], v[176:179], v[40:43]
	v_mfma_f32_16x16x32_bf16 v[28:31], v[60:63], v[194:197], v[28:31]
	v_mfma_f32_16x16x32_bf16 v[24:27], v[68:71], v[194:197], v[24:27]
	v_mfma_f32_16x16x32_bf16 v[12:15], v[60:63], v[202:205], v[12:15]
	v_mfma_f32_16x16x32_bf16 v[8:11], v[68:71], v[202:205], v[8:11]
	v_mfma_f32_16x16x32_bf16 v[52:55], v[144:147], v[160:163], v[52:55]
	v_mfma_f32_16x16x32_bf16 v[48:51], v[152:155], v[160:163], v[48:51]
	v_mfma_f32_16x16x32_bf16 v[36:39], v[144:147], v[168:171], v[36:39]
	v_mfma_f32_16x16x32_bf16 v[32:35], v[152:155], v[168:171], v[32:35]
	v_mfma_f32_16x16x32_bf16 v[20:23], v[144:147], v[190:193], v[20:23]
	v_mfma_f32_16x16x32_bf16 v[16:19], v[152:155], v[190:193], v[16:19]
	v_mfma_f32_16x16x32_bf16 v[4:7], v[144:147], v[198:201], v[4:7]
	v_mfma_f32_16x16x32_bf16 v[0:3], v[152:155], v[198:201], v[0:3]
	v_mfma_f32_16x16x32_bf16 v[52:55], v[148:151], v[164:167], v[52:55]
	v_mfma_f32_16x16x32_bf16 v[48:51], v[156:159], v[164:167], v[48:51]
	v_mfma_f32_16x16x32_bf16 v[36:39], v[148:151], v[176:179], v[36:39]
	v_mfma_f32_16x16x32_bf16 v[32:35], v[156:159], v[176:179], v[32:35]
	v_mfma_f32_16x16x32_bf16 v[20:23], v[148:151], v[194:197], v[20:23]
	v_mfma_f32_16x16x32_bf16 v[16:19], v[156:159], v[194:197], v[16:19]
	v_mfma_f32_16x16x32_bf16 v[4:7], v[148:151], v[202:205], v[4:7]
	v_mfma_f32_16x16x32_bf16 v[0:3], v[156:159], v[202:205], v[0:3]
	s_barrier
	s_setprio 0
	s_add_i32 s79, 0, 0x18000
	s_add_i32 s93, 0, 0x1c000
	v_add_u32_e32 v68, s79, v218
	v_add_u32_e32 v156, s93, v218
	ds_read_b128 v[56:59], v68
	ds_read_b128 v[60:63], v68 offset:1024
	ds_read_b128 v[64:67], v68 offset:2048
	ds_read_b128 v[68:71], v68 offset:3072
	ds_read_b128 v[144:147], v156
	ds_read_b128 v[148:151], v156 offset:1024
	ds_read_b128 v[152:155], v156 offset:2048
	ds_read_b128 v[156:159], v156 offset:3072
	s_add_u32 s38, s38, s50
	s_addc_u32 s39, s39, 0
	s_mov_b32 m0, s68
	v_lshl_add_u64 v[228:229], s[38:39], 0, v[184:185]
	ds_read_b128 v[160:163], v220 offset:32768
	ds_read_b128 v[164:167], v220 offset:33792
	ds_read_b128 v[168:171], v220 offset:34816
	ds_read_b128 v[176:179], v220 offset:35840
	ds_read_b128 v[190:193], v220 offset:36864
	ds_read_b128 v[194:197], v220 offset:37888
	ds_read_b128 v[198:201], v220 offset:38912
	ds_read_b128 v[202:205], v220 offset:39936
	global_load_lds_dwordx4 v[228:229], off
	v_lshl_add_u64 v[228:229], s[38:39], 0, v[182:183]
	s_mov_b32 m0, s69
	s_nop 0
	global_load_lds_dwordx4 v[228:229], off
	s_waitcnt vmcnt(8)
	s_waitcnt lgkmcnt(0)
	s_setprio 1
	s_barrier
	v_mfma_f32_16x16x32_bf16 v[140:143], v[56:59], v[160:163], v[140:143]
	v_mfma_f32_16x16x32_bf16 v[136:139], v[64:67], v[160:163], v[136:139]
	v_mfma_f32_16x16x32_bf16 v[124:127], v[56:59], v[168:171], v[124:127]
	v_mfma_f32_16x16x32_bf16 v[120:123], v[64:67], v[168:171], v[120:123]
	v_mfma_f32_16x16x32_bf16 v[108:111], v[56:59], v[190:193], v[108:111]
	v_mfma_f32_16x16x32_bf16 v[104:107], v[64:67], v[190:193], v[104:107]
	v_mfma_f32_16x16x32_bf16 v[92:95], v[56:59], v[198:201], v[92:95]
	v_mfma_f32_16x16x32_bf16 v[88:91], v[64:67], v[198:201], v[88:91]
	v_mfma_f32_16x16x32_bf16 v[140:143], v[60:63], v[164:167], v[140:143]
	v_mfma_f32_16x16x32_bf16 v[136:139], v[68:71], v[164:167], v[136:139]
	v_mfma_f32_16x16x32_bf16 v[124:127], v[60:63], v[176:179], v[124:127]
	v_mfma_f32_16x16x32_bf16 v[120:123], v[68:71], v[176:179], v[120:123]
	v_mfma_f32_16x16x32_bf16 v[108:111], v[60:63], v[194:197], v[108:111]
	v_mfma_f32_16x16x32_bf16 v[104:107], v[68:71], v[194:197], v[104:107]
	v_mfma_f32_16x16x32_bf16 v[92:95], v[60:63], v[202:205], v[92:95]
	v_mfma_f32_16x16x32_bf16 v[88:91], v[68:71], v[202:205], v[88:91]
	v_mfma_f32_16x16x32_bf16 v[132:135], v[144:147], v[160:163], v[132:135]
	v_mfma_f32_16x16x32_bf16 v[128:131], v[152:155], v[160:163], v[128:131]
	v_mfma_f32_16x16x32_bf16 v[116:119], v[144:147], v[168:171], v[116:119]
	v_mfma_f32_16x16x32_bf16 v[112:115], v[152:155], v[168:171], v[112:115]
	v_mfma_f32_16x16x32_bf16 v[100:103], v[144:147], v[190:193], v[100:103]
	v_mfma_f32_16x16x32_bf16 v[96:99], v[152:155], v[190:193], v[96:99]
	v_mfma_f32_16x16x32_bf16 v[84:87], v[144:147], v[198:201], v[84:87]
	v_mfma_f32_16x16x32_bf16 v[80:83], v[152:155], v[198:201], v[80:83]
	v_mfma_f32_16x16x32_bf16 v[132:135], v[148:151], v[164:167], v[132:135]
	v_mfma_f32_16x16x32_bf16 v[128:131], v[156:159], v[164:167], v[128:131]
	v_mfma_f32_16x16x32_bf16 v[116:119], v[148:151], v[176:179], v[116:119]
	v_mfma_f32_16x16x32_bf16 v[112:115], v[156:159], v[176:179], v[112:115]
	v_mfma_f32_16x16x32_bf16 v[100:103], v[148:151], v[194:197], v[100:103]
	v_mfma_f32_16x16x32_bf16 v[96:99], v[156:159], v[194:197], v[96:99]
	v_mfma_f32_16x16x32_bf16 v[84:87], v[148:151], v[202:205], v[84:87]
	v_mfma_f32_16x16x32_bf16 v[80:83], v[156:159], v[202:205], v[80:83]
	s_barrier
; #define PG8_STAGE(bufoff, gbase, voff) do { _Pragma("unroll") for (int _i = 0; _i < 2; ++_i) \
;         __builtin_amdgcn_global_load_lds((const unsigned*)((const char*)(gbase) + (voff)[_i]), (PG8_LAS unsigned*)(lds + (bufoff) + ldsw + _i * 8192), 16, 0, 0); } while (0)
; #define PG8_LDA(dst, b, h) do { _Pragma("unroll") for (int m = 0; m < 4; ++m) _Pragma("unroll") for (int k = 0; k < 2; ++k) dst[m][k] = *(const PG8_LAS bf16x8*)(lds + PG8_SA(b, h) + aoff + m * 2048 + k * 1024); } while (0)
; #define PG8_LDB(dst, b, h) do { _Pragma("unroll") for (int n = 0; n < 2; ++n) _Pragma("unroll") for (int k = 0; k < 2; ++k) dst[n][k] = *(const PG8_LAS bf16x8*)(lds + PG8_SB(b, h) + boff + n * 2048 + k * 1024); } while (0)
;     __device__ __forceinline__ void operator()(const f32x4 (&acc)[2][2][4][2], const Unit& u, int wr, int wc, int fr, int fq, int, PG8_LAS unsigned char*) const {
;     ...
;         f32x4 csv[2][2];
; #pragma unroll
;         for (int bj = 0; bj < 2; ++bj)
; #pragma unroll
;             for (int n = 0; n < 2; ++n) { csv[bj][n] = (f32x4){1.f, 1.f, 1.f, 1.f}; if (cscale) csv[bj][n] = *(const f32x4*)(cscale + col0 + bj * HALF + 4 * n); }
; template <class Epi, class Sched, bool ALIGN_EPI = false, bool SP2 = false>
; __device__ __forceinline__ void gemm_phase(PG8_LAS unsigned char* lds, const Gemm g, const Sched& S, const Epi& E) {
;     ...
;             PG8_LDB(B0, 0, 0); PG8_LDB(B1, 0, 1); PG8_SCHED; PG8_LDA(At, 0, 0); PG8_STAGE(PG8_SA(1, 1), a1 + hstep, voffA);
;             PG8_WAIT_V(8); PG8_WAIT_L(0); PG8_BAR; PG8_MMA(0, 0, At, B0); PG8_MMA(0, 1, At, B1); PG8_BAR; PG8_SCHED;
;             PG8_LDA(At, 0, 1); PG8_STAGE(PG8_SB(0, 0), b2, voffB); PG8_STAGE(PG8_SB(0, 1), b2 + hstep, voffB); PG8_STAGE(PG8_SA(0, 0), a2, voffA);
;             PG8_WAIT_V(8); PG8_WAIT_L(0); PG8_BAR; PG8_MMA(1, 0, At, B0); PG8_MMA(1, 1, At, B1); PG8_BAR; PG8_SCHED;
;             PG8_LDB(B0, 1, 0); PG8_LDB(B1, 1, 1); PG8_SCHED; PG8_LDA(At, 1, 0); PG8_STAGE(PG8_SA(0, 1), a2 + hstep, voffA);
;             PG8_WAIT_V(8); PG8_WAIT_L(0); PG8_BAR; PG8_MMA(0, 0, At, B0); PG8_MMA(0, 1, At, B1); PG8_BAR; PG8_SCHED;
;             PG8_LDA(At, 1, 1); PG8_STAGE(PG8_SB(1, 0), b3, voffB); PG8_STAGE(PG8_SB(1, 1), b3 + hstep, voffB); PG8_STAGE(PG8_SA(1, 0), a3, voffA);
;             PG8_WAIT_V(8); PG8_WAIT_L(0); PG8_BAR; PG8_MMA(1, 0, At, B0); PG8_MMA(1, 1, At, B1); PG8_BAR; PG8_SCHED;
	s_setprio 0
	s_add_i32 s38, s79, s8
	v_lshl_add_u64 v[172:173], v[172:173], 0, s[4:5]
	s_mov_b32 m0, s38
	ds_read_b128 v[160:163], v220 offset:49152
	ds_read_b128 v[164:167], v220 offset:50176
	ds_read_b128 v[168:171], v220 offset:51200
	ds_read_b128 v[176:179], v220 offset:52224
	ds_read_b128 v[190:193], v220 offset:53248
	ds_read_b128 v[194:197], v220 offset:54272
	ds_read_b128 v[198:201], v220 offset:55296
	ds_read_b128 v[202:205], v220 offset:56320
	global_load_lds_dwordx4 v[172:173], off
	v_lshl_add_u64 v[172:173], v[206:207], 0, s[4:5]
	s_add_i32 m0, s38, 0x2000
	s_add_i32 s38, s93, s8
	global_load_lds_dwordx4 v[172:173], off
	v_lshl_add_u64 v[172:173], v[208:209], 0, s[4:5]
	s_mov_b32 m0, s38
	s_nop 0
	global_load_lds_dwordx4 v[172:173], off
	v_lshl_add_u64 v[172:173], v[222:223], 0, s[4:5]
	s_add_i32 m0, s38, 0x2000
	s_nop 0
	global_load_lds_dwordx4 v[172:173], off
	v_lshl_add_u64 v[172:173], v[224:225], 0, s[4:5]
	s_mov_b32 m0, s73
	s_nop 0
	global_load_lds_dwordx4 v[172:173], off
	v_lshl_add_u64 v[172:173], v[226:227], 0, s[4:5]
	s_mov_b32 m0, s74
	s_nop 0
	global_load_lds_dwordx4 v[172:173], off
	s_waitcnt vmcnt(8)
	s_waitcnt lgkmcnt(0)
	s_setprio 1
	s_barrier
	v_mfma_f32_16x16x32_bf16 v[76:79], v[56:59], v[160:163], v[76:79]
	v_mfma_f32_16x16x32_bf16 v[72:75], v[64:67], v[160:163], v[72:75]
	v_mfma_f32_16x16x32_bf16 v[44:47], v[56:59], v[168:171], v[44:47]
	v_mfma_f32_16x16x32_bf16 v[40:43], v[64:67], v[168:171], v[40:43]
	v_mfma_f32_16x16x32_bf16 v[28:31], v[56:59], v[190:193], v[28:31]
	v_mfma_f32_16x16x32_bf16 v[24:27], v[64:67], v[190:193], v[24:27]
	v_mfma_f32_16x16x32_bf16 v[12:15], v[56:59], v[198:201], v[12:15]
	v_mfma_f32_16x16x32_bf16 v[8:11], v[64:67], v[198:201], v[8:11]
	v_mfma_f32_16x16x32_bf16 v[76:79], v[60:63], v[164:167], v[76:79]
	v_mfma_f32_16x16x32_bf16 v[72:75], v[68:71], v[164:167], v[72:75]
	v_mfma_f32_16x16x32_bf16 v[44:47], v[60:63], v[176:179], v[44:47]
	v_mfma_f32_16x16x32_bf16 v[40:43], v[68:71], v[176:179], v[40:43]
	v_mfma_f32_16x16x32_bf16 v[28:31], v[60:63], v[194:197], v[28:31]
	v_mfma_f32_16x16x32_bf16 v[24:27], v[68:71], v[194:197], v[24:27]
	v_mfma_f32_16x16x32_bf16 v[12:15], v[60:63], v[202:205], v[12:15]
	v_mfma_f32_16x16x32_bf16 v[8:11], v[68:71], v[202:205], v[8:11]
	v_mfma_f32_16x16x32_bf16 v[52:55], v[144:147], v[160:163], v[52:55]
	v_mfma_f32_16x16x32_bf16 v[48:51], v[152:155], v[160:163], v[48:51]
	v_mfma_f32_16x16x32_bf16 v[36:39], v[144:147], v[168:171], v[36:39]
	v_mfma_f32_16x16x32_bf16 v[32:35], v[152:155], v[168:171], v[32:35]
	v_mfma_f32_16x16x32_bf16 v[20:23], v[144:147], v[190:193], v[20:23]
	v_mfma_f32_16x16x32_bf16 v[16:19], v[152:155], v[190:193], v[16:19]
	v_mfma_f32_16x16x32_bf16 v[4:7], v[144:147], v[198:201], v[4:7]
	v_mfma_f32_16x16x32_bf16 v[0:3], v[152:155], v[198:201], v[0:3]
	v_mfma_f32_16x16x32_bf16 v[52:55], v[148:151], v[164:167], v[52:55]
	v_mfma_f32_16x16x32_bf16 v[48:51], v[156:159], v[164:167], v[48:51]
	v_mfma_f32_16x16x32_bf16 v[36:39], v[148:151], v[176:179], v[36:39]
	v_mfma_f32_16x16x32_bf16 v[32:35], v[156:159], v[176:179], v[32:35]
	v_mfma_f32_16x16x32_bf16 v[20:23], v[148:151], v[194:197], v[20:23]
	v_mfma_f32_16x16x32_bf16 v[16:19], v[156:159], v[194:197], v[16:19]
	v_mfma_f32_16x16x32_bf16 v[4:7], v[148:151], v[202:205], v[4:7]
	v_mfma_f32_16x16x32_bf16 v[0:3], v[156:159], v[202:205], v[0:3]
	s_barrier
	s_setprio 0
	s_add_u32 s0, s0, 0x100
	s_addc_u32 s1, s1, 0
	s_add_u32 s44, s44, 0x100
	s_addc_u32 s45, s45, 0
	s_cmp_ge_u32 s78, s72
	s_mov_b32 s38, s78
	s_cbranch_scc0 .LBB0_1641
.LBB0_1644:
	v_lshl_or_b32 v190, s16, 8, v219
	v_ashrrev_i32_e32 v191, 31, v190
	v_cndmask_b32_e64 v56, 0, 1, s[60:61]
	v_lshl_add_u64 v[144:145], v[190:191], 2, s[56:57]
	v_mov_b32_e32 v64, 1.0
	v_cmp_ne_u32_e64 s[44:45], 1, v56
	s_andn2_b64 vcc, exec, s[60:61]
	v_mov_b32_e32 v68, 1.0
	v_mov_b32_e32 v69, 1.0
	v_mov_b32_e32 v70, 1.0
	v_mov_b32_e32 v71, 1.0
	s_cbranch_vccnz .LBB0_1646
	global_load_dwordx4 v[68:71], v[144:145], off

; __device__ __forceinline__ unsigned cvt_pk_bf16(float lo, float hi) { unsigned r; asm volatile("v_cvt_pk_bf16_f32 %0, %1, %2" : "=v"(r) : "v"(lo), "v"(hi)); return r; }
;     __device__ __forceinline__ void operator()(const f32x4 (&acc)[2][2][4][2], const Unit& u, int wr, int wc, int fr, int fq, int, PG8_LAS unsigned char*) const {
;     ...
;         for (int ai = 0; ai < 2; ++ai) {
;             u32x4 xw[4][2];
; #pragma unroll
;             for (int m = 0; m < 4; ++m)
; #pragma unroll
;                 for (int bj = 0; bj < 2; ++bj) xw[m][bj] = *(const u32x4*)(xb + (size_t)(row0 + ai * HALF + m * 16) * 1024 + col0 + bj * HALF);
; #pragma unroll
;             for (int m = 0; m < 4; ++m) {
;                 const int row = row0 + ai * HALF + m * 16; const size_t off = (size_t)row * 1024 + col0;
;                 float s = 0.f;
; #pragma unroll
;                 for (int bj = 0; bj < 2; ++bj) {
;                     const u32x4 xv = xw[m][bj];
;                     const f32x4 xo0 = {__builtin_bit_cast(float, xv.x << 16), __builtin_bit_cast(float, xv.x & 0xffff0000u), __builtin_bit_cast(float, xv.y << 16), __builtin_bit_cast(float, xv.y & 0xffff0000u)};
;                     const f32x4 xo1 = {__builtin_bit_cast(float, xv.z << 16), __builtin_bit_cast(float, xv.z & 0xffff0000u), __builtin_bit_cast(float, xv.w << 16), __builtin_bit_cast(float, xv.w & 0xffff0000u)};
;                     const f32x4 o0 = xo0 + acc[ai][bj][m][0] * csv[bj][0], o1 = xo1 + acc[ai][bj][m][1] * csv[bj][1];
;                     u32x4 w; w.x = cvt_pk_bf16(o0[0], o0[1]); w.y = cvt_pk_bf16(o0[2], o0[3]); w.z = cvt_pk_bf16(o1[0], o1[1]); w.w = cvt_pk_bf16(o1[2], o1[3]);
;                     if (!dry) *(u32x4*)(xb + off + bj * HALF) = w;
; #pragma unroll
;                     for (int q = 0; q < 4; ++q) { const unsigned ww = w[q]; const float ra = __builtin_bit_cast(float, ww << 16), rb = __builtin_bit_cast(float, ww & 0xffff0000u); s += ra * ra + rb * rb; }
;                 }
;                 s += __shfl_xor(s, 16); s += __shfl_xor(s, 32);
;                 if (fq == 0 && !dry) ssq_next[(size_t)row * 16 + u.pn * 4 + wc] = s;
; template <class Epi, class Sched, bool ALIGN_EPI = false, bool SP2 = false>
; __device__ __forceinline__ void gemm_phase(PG8_LAS unsigned char* lds, const Gemm g, const Sched& S, const Epi& E) {
;     ...
;         if constexpr (ALIGN_EPI) { if (wr == 0) PG8_BAR; }
.LBB0_1652:
	v_lshl_add_u32 v194, s77, 8, v217
	v_lshlrev_b64 v[144:145], 1, v[190:191]
	v_ashrrev_i32_e32 v195, 31, v194
	v_lshl_add_u64 v[192:193], s[10:11], 0, v[144:145]
	v_lshlrev_b64 v[146:147], 11, v[194:195]
	v_lshl_add_u64 v[148:149], v[192:193], 0, v[146:147]
	global_load_dwordx4 v[176:179], v[148:149], off
	global_load_dwordx4 v[168:171], v[148:149], off offset:256
	v_or_b32_e32 v202, 16, v194
	v_or_b32_e32 v200, 32, v194
	v_or_b32_e32 v196, 48, v194
	v_ashrrev_i32_e32 v203, 31, v202
	v_ashrrev_i32_e32 v201, 31, v200
	v_ashrrev_i32_e32 v197, 31, v196
	v_lshlrev_b64 v[206:207], 11, v[202:203]
	v_lshlrev_b64 v[204:205], 11, v[200:201]
	v_lshlrev_b64 v[198:199], 11, v[196:197]
	v_lshl_add_u64 v[146:147], s[10:11], 0, v[146:147]
	v_lshl_add_u64 v[148:149], v[192:193], 0, v[206:207]
	v_lshl_add_u64 v[150:151], v[192:193], 0, v[204:205]
	v_lshl_add_u64 v[172:173], v[192:193], 0, v[198:199]
	v_lshl_add_u64 v[208:209], v[146:147], 0, v[144:145]
	global_load_dwordx4 v[164:167], v[148:149], off
	global_load_dwordx4 v[160:163], v[148:149], off offset:256
	global_load_dwordx4 v[156:159], v[150:151], off
	global_load_dwordx4 v[152:155], v[150:151], off offset:256
	s_nop 0
	global_load_dwordx4 v[148:151], v[172:173], off
	global_load_dwordx4 v[144:147], v[172:173], off offset:256
	s_lshl_b32 s0, s16, 2
	s_ashr_i32 s1, s0, 31
	s_and_b64 vcc, exec, s[58:59]
	s_cbranch_vccz .Lal2_skip
	s_barrier
.Lal2_skip:
	s_waitcnt vmcnt(0)
	v_lshlrev_b32_e32 v172, 16, v176
	v_and_b32_e32 v173, 0xffff0000, v176
	v_lshlrev_b32_e32 v176, 16, v177
	v_and_b32_e32 v177, 0xffff0000, v177
	v_lshlrev_b32_e32 v222, 16, v178
	v_and_b32_e32 v223, 0xffff0000, v178
	v_lshlrev_b32_e32 v224, 16, v168
	v_and_b32_e32 v225, 0xffff0000, v168
	v_lshlrev_b32_e32 v168, 16, v169
	v_and_b32_e32 v169, 0xffff0000, v169
	v_lshlrev_b32_e32 v226, 16, v170
	v_and_b32_e32 v227, 0xffff0000, v170
	v_lshlrev_b32_e32 v170, 16, v171
	v_and_b32_e32 v171, 0xffff0000, v171
	v_lshlrev_b32_e32 v178, 16, v179
	v_and_b32_e32 v179, 0xffff0000, v179
	v_pk_fma_f32 v[142:143], v[142:143], v[70:71], v[176:177]
	v_pk_fma_f32 v[140:141], v[140:141], v[68:69], v[172:173]
	v_pk_fma_f32 v[136:137], v[136:137], v[64:65], v[222:223]
	v_pk_fma_f32 v[134:135], v[134:135], v[62:63], v[168:169]
	v_pk_fma_f32 v[168:169], v[130:131], v[58:59], v[170:171]
	v_pk_fma_f32 v[170:171], v[128:129], v[56:57], v[226:227]
	v_cvt_pk_bf16_f32 v128, v140, v141
	v_cvt_pk_bf16_f32 v129, v142, v143
	v_pk_fma_f32 v[138:139], v[138:139], v[66:67], v[178:179]
	v_cvt_pk_bf16_f32 v130, v136, v137
	v_lshlrev_b32_e32 v136, 16, v128
	v_cvt_pk_bf16_f32 v131, v138, v139
	global_store_dwordx4 v[208:209], v[128:131], off
	v_lshlrev_b32_e32 v137, 16, v129
	v_lshlrev_b32_e32 v138, 16, v130
	v_and_b32_e32 v128, 0xffff0000, v128
	v_and_b32_e32 v129, 0xffff0000, v129
	v_and_b32_e32 v130, 0xffff0000, v130
	v_mul_f32_e32 v128, v128, v128
	v_mul_f32_e32 v129, v129, v129
	v_pk_fma_f32 v[132:133], v[132:133], v[60:61], v[224:225]
	v_lshlrev_b32_e32 v139, 16, v131
	v_and_b32_e32 v131, 0xffff0000, v131
	v_mul_f32_e32 v130, v130, v130
	v_fmac_f32_e32 v128, v136, v136
	v_fmac_f32_e32 v129, v137, v137
	v_cvt_pk_bf16_f32 v132, v132, v133
	v_mul_f32_e32 v131, v131, v131
	v_and_b32_e32 v141, 0xffff0000, v132
	v_fmac_f32_e32 v130, v138, v138
	v_add_f32_e32 v128, v128, v129
	v_cvt_pk_bf16_f32 v133, v134, v135
	v_lshlrev_b32_e32 v140, 16, v132
	v_and_b32_e32 v143, 0xffff0000, v133
	v_fmac_f32_e32 v131, v139, v139
	v_mul_f32_e32 v136, v141, v141
	v_add_f32_e32 v128, v128, v130
	v_cvt_pk_bf16_f32 v134, v170, v171
	v_cvt_pk_bf16_f32 v135, v168, v169
	v_lshlrev_b32_e32 v142, 16, v133
	v_and_b32_e32 v169, 0xffff0000, v134
	v_mul_f32_e32 v137, v143, v143
	v_fmac_f32_e32 v136, v140, v140
	v_add_f32_e32 v128, v128, v131
	v_lshlrev_b32_e32 v168, 16, v134
	v_mul_f32_e32 v138, v169, v169
	v_fmac_f32_e32 v137, v142, v142
	v_add_f32_e32 v128, v128, v136
	v_and_b32_e32 v129, 0xffff0000, v135
	v_lshlrev_b32_e32 v170, 16, v135
	v_fmac_f32_e32 v138, v168, v168
	v_add_f32_e32 v128, v128, v137
	v_mul_f32_e32 v129, v129, v129
	v_add_f32_e32 v128, v128, v138
	v_fmac_f32_e32 v129, v170, v170
	v_and_b32_e32 v130, 64, v213
	v_add_f32_e32 v129, v128, v129
	v_xor_b32_e32 v128, 16, v213
	v_add_u32_e32 v131, 64, v130
	v_cmp_lt_i32_e32 vcc, v128, v131
	global_store_dwordx4 v[208:209], v[132:135], off offset:256
	s_nop 0
	v_cndmask_b32_e32 v128, v213, v128, vcc
	v_lshlrev_b32_e32 v128, 2, v128
	ds_bpermute_b32 v130, v128, v129
	s_waitcnt lgkmcnt(0)
	v_add_f32_e32 v130, v129, v130
	v_xor_b32_e32 v129, 32, v213
	v_cmp_lt_i32_e32 vcc, v129, v131
	s_nop 1
	v_cndmask_b32_e32 v129, v213, v129, vcc
	v_lshlrev_b32_e32 v129, 2, v129
	ds_bpermute_b32 v131, v129, v130
	s_and_saveexec_b64 s[38:39], s[40:41]
	s_cbranch_execz .LBB0_1654
	v_lshlrev_b64 v[132:133], 6, v[194:195]
	v_lshl_add_u64 v[132:133], s[6:7], 0, v[132:133]
	v_lshl_add_u64 v[132:133], s[0:1], 2, v[132:133]
	s_lshl_b32 s16, s71, 2
	v_lshl_add_u64 v[132:133], v[132:133], 0, s[16:17]
	s_waitcnt lgkmcnt(0)
	v_add_f32_e32 v130, v130, v131
	global_store_dword v[132:133], v130, off

; #define PG8_STAGE(bufoff, gbase, voff) do { _Pragma("unroll") for (int _i = 0; _i < 2; ++_i) \
;         __builtin_amdgcn_global_load_lds((const unsigned*)((const char*)(gbase) + (voff)[_i]), (PG8_LAS unsigned*)(lds + (bufoff) + ldsw + _i * 8192), 16, 0, 0); } while (0)
; #define PG8_LDA(dst, b, h) do { _Pragma("unroll") for (int m = 0; m < 4; ++m) _Pragma("unroll") for (int k = 0; k < 2; ++k) dst[m][k] = *(const PG8_LAS bf16x8*)(lds + PG8_SA(b, h) + aoff + m * 2048 + k * 1024); } while (0)
; #define PG8_LDB(dst, b, h) do { _Pragma("unroll") for (int n = 0; n < 2; ++n) _Pragma("unroll") for (int k = 0; k < 2; ++k) dst[n][k] = *(const PG8_LAS bf16x8*)(lds + PG8_SB(b, h) + boff + n * 2048 + k * 1024); } while (0)
; template <class Epi, class Sched, bool ALIGN_EPI = false, bool SP2 = false>
; __device__ __forceinline__ void gemm_phase(PG8_LAS unsigned char* lds, const Gemm g, const Sched& S, const Epi& E) {
;     ...
;         for (int t = 0; t < nt; t += 2) {
;             const bool last = (t == nt - 2);
;             const char* a1 = cA + (size_t)(t + 1) * kstep;
;             const char* a2 = last ? nA : cA + (size_t)(t + 2) * kstep; const char* b2 = last ? nB : cB + (size_t)(t + 2) * kstep;
;             const char* a3 = a2 + kstep; const char* b3 = b2 + kstep;
;             if (last && has_next) S.a_ready(nxt);
;             if constexpr (SP2) {
;             PG8_LDB(B0, 0, 0); PG8_LDB(B1, 0, 1); PG8_SCHED; PG8_LDA(At, 0, 0); PG8_STAGE(PG8_SA(1, 1), a1 + hstep, voffA);
;             PG8_WAIT_V(8); PG8_WAIT_L(0); PG8_BAR; PG8_MMA(0, 0, At, B0); PG8_MMA(0, 1, At, B1); PG8_BAR; PG8_SCHED;
;             PG8_LDA(At, 0, 1); PG8_STAGE(PG8_SB(0, 0), b2, voffB); PG8_STAGE(PG8_SB(0, 1), b2 + hstep, voffB); PG8_STAGE(PG8_SA(0, 0), a2, voffA);
;             PG8_WAIT_V(8); PG8_WAIT_L(0); PG8_BAR; PG8_MMA(1, 0, At, B0); PG8_MMA(1, 1, At, B1); PG8_BAR; PG8_SCHED;
;             PG8_LDB(B0, 1, 0); PG8_LDB(B1, 1, 1); PG8_SCHED; PG8_LDA(At, 1, 0); PG8_STAGE(PG8_SA(0, 1), a2 + hstep, voffA);
;             PG8_WAIT_V(8); PG8_WAIT_L(0); PG8_BAR; PG8_MMA(0, 0, At, B0); PG8_MMA(0, 1, At, B1); PG8_BAR; PG8_SCHED;
;             PG8_LDA(At, 1, 1); PG8_STAGE(PG8_SB(1, 0), b3, voffB); PG8_STAGE(PG8_SB(1, 1), b3 + hstep, voffB); PG8_STAGE(PG8_SA(1, 0), a3, voffA);
;             PG8_WAIT_V(8); PG8_WAIT_L(0); PG8_BAR; PG8_MMA(1, 0, At, B0); PG8_MMA(1, 1, At, B1); PG8_BAR; PG8_SCHED;
.LBB0_1752:
	s_add_u32 s38, s0, 0xfffc0080
	s_addc_u32 s39, s1, -1
	s_add_i32 s74, 0, 0x10000
	s_cmp_eq_u32 s73, 12
	s_cselect_b32 s57, s51, s39
	s_cselect_b32 s56, s69, s38
	v_add_u32_e32 v151, s74, v147
	s_cselect_b32 s39, s49, s72
	s_cselect_b32 s38, s70, s71
	s_add_i32 s76, 0, 0x14000
	ds_read_b128 v[138:141], v151
	ds_read_b128 v[142:145], v151 offset:1024
	ds_read_b128 v[152:155], v151 offset:2048
	ds_read_b128 v[156:159], v151 offset:3072
	v_add_u32_e32 v151, s76, v147
	ds_read_b128 v[160:163], v151
	ds_read_b128 v[164:167], v151 offset:1024
	ds_read_b128 v[168:171], v151 offset:2048
	ds_read_b128 v[176:179], v151 offset:3072
	v_lshl_add_u64 v[172:173], s[0:1], 0, v[134:135]
	s_add_i32 m0, s58, 0xc000
	ds_read_b128 v[180:183], v150
	ds_read_b128 v[184:187], v150 offset:1024
	ds_read_b128 v[188:191], v150 offset:2048
	ds_read_b128 v[192:195], v150 offset:3072
	ds_read_b128 v[196:199], v150 offset:4096
	ds_read_b128 v[200:203], v150 offset:5120
	ds_read_b128 v[204:207], v150 offset:6144
	ds_read_b128 v[218:221], v150 offset:7168
	global_load_lds_dwordx4 v[172:173], off
	v_lshl_add_u64 v[172:173], s[0:1], 0, v[136:137]
	s_add_i32 m0, s58, 0xe000
	s_nop 0
	global_load_lds_dwordx4 v[172:173], off
	s_waitcnt vmcnt(8)
	s_waitcnt lgkmcnt(0)
	s_setprio 1
	s_barrier
	v_mfma_f32_16x16x32_bf16 v[124:127], v[138:141], v[180:183], v[124:127]
	v_mfma_f32_16x16x32_bf16 v[120:123], v[152:155], v[180:183], v[120:123]
	v_mfma_f32_16x16x32_bf16 v[108:111], v[138:141], v[188:191], v[108:111]
	v_mfma_f32_16x16x32_bf16 v[104:107], v[152:155], v[188:191], v[104:107]
	v_mfma_f32_16x16x32_bf16 v[92:95], v[138:141], v[196:199], v[92:95]
	v_mfma_f32_16x16x32_bf16 v[88:91], v[152:155], v[196:199], v[88:91]
	v_mfma_f32_16x16x32_bf16 v[76:79], v[138:141], v[204:207], v[76:79]
	v_mfma_f32_16x16x32_bf16 v[72:75], v[152:155], v[204:207], v[72:75]
	v_mfma_f32_16x16x32_bf16 v[124:127], v[142:145], v[184:187], v[124:127]
	v_mfma_f32_16x16x32_bf16 v[120:123], v[156:159], v[184:187], v[120:123]
	v_mfma_f32_16x16x32_bf16 v[108:111], v[142:145], v[192:195], v[108:111]
	v_mfma_f32_16x16x32_bf16 v[104:107], v[156:159], v[192:195], v[104:107]
	v_mfma_f32_16x16x32_bf16 v[92:95], v[142:145], v[200:203], v[92:95]
	v_mfma_f32_16x16x32_bf16 v[88:91], v[156:159], v[200:203], v[88:91]
	v_mfma_f32_16x16x32_bf16 v[76:79], v[142:145], v[218:221], v[76:79]
	v_mfma_f32_16x16x32_bf16 v[72:75], v[156:159], v[218:221], v[72:75]
	v_mfma_f32_16x16x32_bf16 v[116:119], v[160:163], v[180:183], v[116:119]
	v_mfma_f32_16x16x32_bf16 v[112:115], v[168:171], v[180:183], v[112:115]
	v_mfma_f32_16x16x32_bf16 v[100:103], v[160:163], v[188:191], v[100:103]
	v_mfma_f32_16x16x32_bf16 v[96:99], v[168:171], v[188:191], v[96:99]
	v_mfma_f32_16x16x32_bf16 v[84:87], v[160:163], v[196:199], v[84:87]
	v_mfma_f32_16x16x32_bf16 v[80:83], v[168:171], v[196:199], v[80:83]
	v_mfma_f32_16x16x32_bf16 v[68:71], v[160:163], v[204:207], v[68:71]
	v_mfma_f32_16x16x32_bf16 v[64:67], v[168:171], v[204:207], v[64:67]
	v_mfma_f32_16x16x32_bf16 v[116:119], v[164:167], v[184:187], v[116:119]
	v_mfma_f32_16x16x32_bf16 v[112:115], v[176:179], v[184:187], v[112:115]
	v_mfma_f32_16x16x32_bf16 v[100:103], v[164:167], v[192:195], v[100:103]
	v_mfma_f32_16x16x32_bf16 v[96:99], v[176:179], v[192:195], v[96:99]
	v_mfma_f32_16x16x32_bf16 v[84:87], v[164:167], v[200:203], v[84:87]
	v_mfma_f32_16x16x32_bf16 v[80:83], v[176:179], v[200:203], v[80:83]
	v_mfma_f32_16x16x32_bf16 v[68:71], v[164:167], v[218:221], v[68:71]
	v_mfma_f32_16x16x32_bf16 v[64:67], v[176:179], v[218:221], v[64:67]
	s_barrier
	s_setprio 0
	s_add_i32 s74, s74, s8
	v_lshl_add_u64 v[172:173], s[38:39], 0, v[174:175]
	s_mov_b32 m0, s74
	ds_read_b128 v[180:183], v150 offset:16384
	ds_read_b128 v[184:187], v150 offset:17408
	ds_read_b128 v[188:191], v150 offset:18432
	ds_read_b128 v[192:195], v150 offset:19456
	ds_read_b128 v[196:199], v150 offset:20480
	ds_read_b128 v[200:203], v150 offset:21504
	ds_read_b128 v[204:207], v150 offset:22528
	ds_read_b128 v[218:221], v150 offset:23552
	global_load_lds_dwordx4 v[172:173], off
	s_add_i32 m0, s74, 0x2000
	s_add_u32 s74, s38, 0x40000
	v_lshl_add_u64 v[208:209], s[38:39], 0, v[128:129]
	s_addc_u32 s75, s39, 0
	s_add_i32 s76, s76, s8
	global_load_lds_dwordx4 v[208:209], off
	v_lshl_add_u64 v[222:223], s[74:75], 0, v[174:175]
	s_mov_b32 m0, s76
	v_lshl_add_u64 v[224:225], s[56:57], 0, v[130:131]
	global_load_lds_dwordx4 v[222:223], off
	v_lshl_add_u64 v[222:223], s[74:75], 0, v[128:129]
	s_add_i32 m0, s76, 0x2000
	s_nop 0
	global_load_lds_dwordx4 v[222:223], off
	v_lshl_add_u64 v[222:223], s[56:57], 0, v[132:133]
	s_mov_b32 m0, s58
	s_nop 0
	global_load_lds_dwordx4 v[222:223], off
	s_mov_b32 m0, s59
	s_nop 0
	global_load_lds_dwordx4 v[224:225], off
	s_waitcnt vmcnt(8)
	s_waitcnt lgkmcnt(0)
	s_setprio 1
	s_barrier
; #define PG8_STAGE(bufoff, gbase, voff) do { _Pragma("unroll") for (int _i = 0; _i < 2; ++_i) \
;         __builtin_amdgcn_global_load_lds((const unsigned*)((const char*)(gbase) + (voff)[_i]), (PG8_LAS unsigned*)(lds + (bufoff) + ldsw + _i * 8192), 16, 0, 0); } while (0)
; #define PG8_LDA(dst, b, h) do { _Pragma("unroll") for (int m = 0; m < 4; ++m) _Pragma("unroll") for (int k = 0; k < 2; ++k) dst[m][k] = *(const PG8_LAS bf16x8*)(lds + PG8_SA(b, h) + aoff + m * 2048 + k * 1024); } while (0)
; #define PG8_LDB(dst, b, h) do { _Pragma("unroll") for (int n = 0; n < 2; ++n) _Pragma("unroll") for (int k = 0; k < 2; ++k) dst[n][k] = *(const PG8_LAS bf16x8*)(lds + PG8_SB(b, h) + boff + n * 2048 + k * 1024); } while (0)
; template <class Epi, class Sched, bool ALIGN_EPI = false, bool SP2 = false>
; __device__ __forceinline__ void gemm_phase(PG8_LAS unsigned char* lds, const Gemm g, const Sched& S, const Epi& E) {
;     ...
;         for (int t = 0; t < nt; t += 2) {
;             const bool last = (t == nt - 2);
;             const char* a1 = cA + (size_t)(t + 1) * kstep;
;             const char* a2 = last ? nA : cA + (size_t)(t + 2) * kstep; const char* b2 = last ? nB : cB + (size_t)(t + 2) * kstep;
;             const char* a3 = a2 + kstep; const char* b3 = b2 + kstep;
;             if (last && has_next) S.a_ready(nxt);
;             if constexpr (SP2) {
;             PG8_LDB(B0, 0, 0); PG8_LDB(B1, 0, 1); PG8_SCHED; PG8_LDA(At, 0, 0); PG8_STAGE(PG8_SA(1, 1), a1 + hstep, voffA);
;             PG8_WAIT_V(8); PG8_WAIT_L(0); PG8_BAR; PG8_MMA(0, 0, At, B0); PG8_MMA(0, 1, At, B1); PG8_BAR; PG8_SCHED;
;             PG8_LDA(At, 0, 1); PG8_STAGE(PG8_SB(0, 0), b2, voffB); PG8_STAGE(PG8_SB(0, 1), b2 + hstep, voffB); PG8_STAGE(PG8_SA(0, 0), a2, voffA);
;             PG8_WAIT_V(8); PG8_WAIT_L(0); PG8_BAR; PG8_MMA(1, 0, At, B0); PG8_MMA(1, 1, At, B1); PG8_BAR; PG8_SCHED;
;             PG8_LDB(B0, 1, 0); PG8_LDB(B1, 1, 1); PG8_SCHED; PG8_LDA(At, 1, 0); PG8_STAGE(PG8_SA(0, 1), a2 + hstep, voffA);
;             PG8_WAIT_V(8); PG8_WAIT_L(0); PG8_BAR; PG8_MMA(0, 0, At, B0); PG8_MMA(0, 1, At, B1); PG8_BAR; PG8_SCHED;
;             PG8_LDA(At, 1, 1); PG8_STAGE(PG8_SB(1, 0), b3, voffB); PG8_STAGE(PG8_SB(1, 1), b3 + hstep, voffB); PG8_STAGE(PG8_SA(1, 0), a3, voffA);
;             PG8_WAIT_V(8); PG8_WAIT_L(0); PG8_BAR; PG8_MMA(1, 0, At, B0); PG8_MMA(1, 1, At, B1); PG8_BAR; PG8_SCHED;
	v_mfma_f32_16x16x32_bf16 v[60:63], v[138:141], v[180:183], v[60:63]
	v_mfma_f32_16x16x32_bf16 v[56:59], v[152:155], v[180:183], v[56:59]
	v_mfma_f32_16x16x32_bf16 v[44:47], v[138:141], v[188:191], v[44:47]
	v_mfma_f32_16x16x32_bf16 v[40:43], v[152:155], v[188:191], v[40:43]
	v_mfma_f32_16x16x32_bf16 v[28:31], v[138:141], v[196:199], v[28:31]
	v_mfma_f32_16x16x32_bf16 v[24:27], v[152:155], v[196:199], v[24:27]
	v_mfma_f32_16x16x32_bf16 v[12:15], v[138:141], v[204:207], v[12:15]
	v_mfma_f32_16x16x32_bf16 v[8:11], v[152:155], v[204:207], v[8:11]
	v_mfma_f32_16x16x32_bf16 v[60:63], v[142:145], v[184:187], v[60:63]
	v_mfma_f32_16x16x32_bf16 v[56:59], v[156:159], v[184:187], v[56:59]
	v_mfma_f32_16x16x32_bf16 v[44:47], v[142:145], v[192:195], v[44:47]
	v_mfma_f32_16x16x32_bf16 v[40:43], v[156:159], v[192:195], v[40:43]
	v_mfma_f32_16x16x32_bf16 v[28:31], v[142:145], v[200:203], v[28:31]
	v_mfma_f32_16x16x32_bf16 v[24:27], v[156:159], v[200:203], v[24:27]
	v_mfma_f32_16x16x32_bf16 v[12:15], v[142:145], v[218:221], v[12:15]
	v_mfma_f32_16x16x32_bf16 v[8:11], v[156:159], v[218:221], v[8:11]
	v_mfma_f32_16x16x32_bf16 v[52:55], v[160:163], v[180:183], v[52:55]
	v_mfma_f32_16x16x32_bf16 v[48:51], v[168:171], v[180:183], v[48:51]
	v_mfma_f32_16x16x32_bf16 v[36:39], v[160:163], v[188:191], v[36:39]
	v_mfma_f32_16x16x32_bf16 v[32:35], v[168:171], v[188:191], v[32:35]
	v_mfma_f32_16x16x32_bf16 v[20:23], v[160:163], v[196:199], v[20:23]
	v_mfma_f32_16x16x32_bf16 v[16:19], v[168:171], v[196:199], v[16:19]
	v_mfma_f32_16x16x32_bf16 v[4:7], v[160:163], v[204:207], v[4:7]
	v_mfma_f32_16x16x32_bf16 v[0:3], v[168:171], v[204:207], v[0:3]
	v_mfma_f32_16x16x32_bf16 v[52:55], v[164:167], v[184:187], v[52:55]
	v_mfma_f32_16x16x32_bf16 v[48:51], v[176:179], v[184:187], v[48:51]
	v_mfma_f32_16x16x32_bf16 v[36:39], v[164:167], v[192:195], v[36:39]
	v_mfma_f32_16x16x32_bf16 v[32:35], v[176:179], v[192:195], v[32:35]
	v_mfma_f32_16x16x32_bf16 v[20:23], v[164:167], v[200:203], v[20:23]
	v_mfma_f32_16x16x32_bf16 v[16:19], v[176:179], v[200:203], v[16:19]
	v_mfma_f32_16x16x32_bf16 v[4:7], v[164:167], v[218:221], v[4:7]
	v_mfma_f32_16x16x32_bf16 v[0:3], v[176:179], v[218:221], v[0:3]
	s_barrier
	s_setprio 0
	s_add_i32 s74, 0, 0x18000
	v_add_u32_e32 v151, s74, v147
	s_add_i32 s75, 0, 0x1c000
	ds_read_b128 v[138:141], v151
	ds_read_b128 v[142:145], v151 offset:1024
	ds_read_b128 v[152:155], v151 offset:2048
	ds_read_b128 v[156:159], v151 offset:3072
	v_add_u32_e32 v151, s75, v147
	ds_read_b128 v[160:163], v151
	ds_read_b128 v[164:167], v151 offset:1024
	ds_read_b128 v[168:171], v151 offset:2048
	ds_read_b128 v[176:179], v151 offset:3072
	s_add_u32 s56, s56, 0x40000
	s_addc_u32 s57, s57, 0
	s_mov_b32 m0, s60
	v_lshl_add_u64 v[226:227], s[56:57], 0, v[132:133]
	ds_read_b128 v[180:183], v150 offset:32768
	ds_read_b128 v[184:187], v150 offset:33792
	ds_read_b128 v[188:191], v150 offset:34816
	ds_read_b128 v[192:195], v150 offset:35840
	ds_read_b128 v[196:199], v150 offset:36864
	ds_read_b128 v[200:203], v150 offset:37888
	ds_read_b128 v[204:207], v150 offset:38912
	ds_read_b128 v[218:221], v150 offset:39936
	global_load_lds_dwordx4 v[226:227], off
	v_lshl_add_u64 v[226:227], s[56:57], 0, v[130:131]
	s_mov_b32 m0, s61
	s_nop 0
	global_load_lds_dwordx4 v[226:227], off
	s_waitcnt vmcnt(8)
	s_waitcnt lgkmcnt(0)
	s_setprio 1
	s_barrier
	v_mfma_f32_16x16x32_bf16 v[124:127], v[138:141], v[180:183], v[124:127]
	v_mfma_f32_16x16x32_bf16 v[120:123], v[152:155], v[180:183], v[120:123]
	v_mfma_f32_16x16x32_bf16 v[108:111], v[138:141], v[188:191], v[108:111]
	v_mfma_f32_16x16x32_bf16 v[104:107], v[152:155], v[188:191], v[104:107]
	v_mfma_f32_16x16x32_bf16 v[92:95], v[138:141], v[196:199], v[92:95]
	v_mfma_f32_16x16x32_bf16 v[88:91], v[152:155], v[196:199], v[88:91]
	v_mfma_f32_16x16x32_bf16 v[76:79], v[138:141], v[204:207], v[76:79]
	v_mfma_f32_16x16x32_bf16 v[72:75], v[152:155], v[204:207], v[72:75]
	v_mfma_f32_16x16x32_bf16 v[124:127], v[142:145], v[184:187], v[124:127]
	v_mfma_f32_16x16x32_bf16 v[120:123], v[156:159], v[184:187], v[120:123]
	v_mfma_f32_16x16x32_bf16 v[108:111], v[142:145], v[192:195], v[108:111]
	v_mfma_f32_16x16x32_bf16 v[104:107], v[156:159], v[192:195], v[104:107]
	v_mfma_f32_16x16x32_bf16 v[92:95], v[142:145], v[200:203], v[92:95]
	v_mfma_f32_16x16x32_bf16 v[88:91], v[156:159], v[200:203], v[88:91]
	v_mfma_f32_16x16x32_bf16 v[76:79], v[142:145], v[218:221], v[76:79]
	v_mfma_f32_16x16x32_bf16 v[72:75], v[156:159], v[218:221], v[72:75]
	v_mfma_f32_16x16x32_bf16 v[116:119], v[160:163], v[180:183], v[116:119]
	v_mfma_f32_16x16x32_bf16 v[112:115], v[168:171], v[180:183], v[112:115]
	v_mfma_f32_16x16x32_bf16 v[100:103], v[160:163], v[188:191], v[100:103]
	v_mfma_f32_16x16x32_bf16 v[96:99], v[168:171], v[188:191], v[96:99]
	v_mfma_f32_16x16x32_bf16 v[84:87], v[160:163], v[196:199], v[84:87]
	v_mfma_f32_16x16x32_bf16 v[80:83], v[168:171], v[196:199], v[80:83]
	v_mfma_f32_16x16x32_bf16 v[68:71], v[160:163], v[204:207], v[68:71]
	v_mfma_f32_16x16x32_bf16 v[64:67], v[168:171], v[204:207], v[64:67]
	v_mfma_f32_16x16x32_bf16 v[116:119], v[164:167], v[184:187], v[116:119]
	v_mfma_f32_16x16x32_bf16 v[112:115], v[176:179], v[184:187], v[112:115]
	v_mfma_f32_16x16x32_bf16 v[100:103], v[164:167], v[192:195], v[100:103]
	v_mfma_f32_16x16x32_bf16 v[96:99], v[176:179], v[192:195], v[96:99]
	v_mfma_f32_16x16x32_bf16 v[84:87], v[164:167], v[200:203], v[84:87]
	v_mfma_f32_16x16x32_bf16 v[80:83], v[176:179], v[200:203], v[80:83]
	v_mfma_f32_16x16x32_bf16 v[68:71], v[164:167], v[218:221], v[68:71]
	v_mfma_f32_16x16x32_bf16 v[64:67], v[176:179], v[218:221], v[64:67]
	s_barrier
; #define PG8_LAS __attribute__((address_space(3)))
; #define PG8_STAGE(bufoff, gbase, voff) do { _Pragma("unroll") for (int _i = 0; _i < 2; ++_i) \
;         __builtin_amdgcn_global_load_lds((const unsigned*)((const char*)(gbase) + (voff)[_i]), (PG8_LAS unsigned*)(lds + (bufoff) + ldsw + _i * 8192), 16, 0, 0); } while (0)
; #define PG8_LDA(dst, b, h) do { _Pragma("unroll") for (int m = 0; m < 4; ++m) _Pragma("unroll") for (int k = 0; k < 2; ++k) dst[m][k] = *(const PG8_LAS bf16x8*)(lds + PG8_SA(b, h) + aoff + m * 2048 + k * 1024); } while (0)
; #define PG8_WAIT_V(n) asm volatile("s_waitcnt vmcnt(" #n ")" ::: "memory")
; #define PG8_WAIT_L(n) asm volatile("s_waitcnt lgkmcnt(" #n ")" ::: "memory")
; #define PG8_BAR __builtin_amdgcn_s_barrier()
;     __device__ __forceinline__ void operator()(const f32x4 (&acc)[2][2][4][2], const Unit& u, int wr, int wc, int fr, int fq, int ui, PG8_LAS unsigned char* lds) const {
;         const int row0 = u.pm * BM + wr * 64 + fr, col0 = u.pn * BM + wc * 32 + 8 * fq;
;         const PG8_LAS float* tab = (const PG8_LAS float*)(lds + RSTD_TAB) + ui * 256 + wr * 64 + fr;
;         const int sec = (u.pn * BM) >> 10;
;         int act = 0; float sc = 1.f;
;         if (mode == 0) act = (sec == 0 || sec == 3) ? 1 : (sec == 1 ? 2 : 0);
;         else if (mode == 1) sc = (sec == 0) ? qscale : 1.f;
;         else act = 3;
;         const bool ksum = (mode == 1) && (sec == 1);
;         f32x4 csum[2][2] = {{(f32x4){0.f, 0.f, 0.f, 0.f}, (f32x4){0.f, 0.f, 0.f, 0.f}}, {(f32x4){0.f, 0.f, 0.f, 0.f}, (f32x4){0.f, 0.f, 0.f, 0.f}}};
; #pragma unroll
;         for (int ai = 0; ai < 2; ++ai) {
;             float rs4[4];
; #pragma unroll
;             for (int m = 0; m < 4; ++m) {
;                 if ((m & 1) == 0) {
;                     if (use_tab) { rs4[m] = tab[ai * HALF + m * 16] * sc; rs4[m + 1] = tab[ai * HALF + (m + 1) * 16] * sc; }
; template <class Epi, class Sched, bool ALIGN_EPI = false, bool SP2 = false>
; __device__ __forceinline__ void gemm_phase(PG8_LAS unsigned char* lds, const Gemm g, const Sched& S, const Epi& E) {
;     ...
;             PG8_LDA(At, 1, 1); PG8_STAGE(PG8_SB(1, 0), b3, voffB); PG8_STAGE(PG8_SB(1, 1), b3 + hstep, voffB); PG8_STAGE(PG8_SA(1, 0), a3, voffA);
;             PG8_WAIT_V(8); PG8_WAIT_L(0); PG8_BAR; PG8_MMA(1, 0, At, B0); PG8_MMA(1, 1, At, B1); PG8_BAR; PG8_SCHED;
	s_setprio 0
	s_add_i32 s56, s74, s8
	v_lshl_add_u64 v[172:173], v[172:173], 0, s[4:5]
	s_mov_b32 m0, s56
	ds_read_b128 v[180:183], v150 offset:49152
	ds_read_b128 v[184:187], v150 offset:50176
	ds_read_b128 v[188:191], v150 offset:51200
	ds_read_b128 v[192:195], v150 offset:52224
	ds_read_b128 v[196:199], v150 offset:53248
	ds_read_b128 v[200:203], v150 offset:54272
	ds_read_b128 v[204:207], v150 offset:55296
	ds_read_b128 v[218:221], v150 offset:56320
	global_load_lds_dwordx4 v[172:173], off
	s_add_i32 m0, s56, 0x2000
	s_add_u32 s38, s38, 0x40080
	v_lshl_add_u64 v[172:173], v[208:209], 0, s[4:5]
	s_addc_u32 s39, s39, 0
	s_add_i32 s56, s75, s8
	global_load_lds_dwordx4 v[172:173], off
	v_lshl_add_u64 v[172:173], s[38:39], 0, v[174:175]
	s_mov_b32 m0, s56
	s_nop 0
	global_load_lds_dwordx4 v[172:173], off
	v_lshl_add_u64 v[172:173], s[38:39], 0, v[128:129]
	s_add_i32 m0, s56, 0x2000
	s_nop 0
	global_load_lds_dwordx4 v[172:173], off
	v_lshl_add_u64 v[172:173], v[222:223], 0, s[4:5]
	s_mov_b32 m0, s62
	s_nop 0
	global_load_lds_dwordx4 v[172:173], off
	v_lshl_add_u64 v[172:173], v[224:225], 0, s[4:5]
	s_mov_b32 m0, s63
	s_nop 0
	global_load_lds_dwordx4 v[172:173], off
	s_waitcnt vmcnt(8)
	s_waitcnt lgkmcnt(0)
	s_setprio 1
	s_barrier
	v_mfma_f32_16x16x32_bf16 v[60:63], v[138:141], v[180:183], v[60:63]
	v_mfma_f32_16x16x32_bf16 v[56:59], v[152:155], v[180:183], v[56:59]
	v_mfma_f32_16x16x32_bf16 v[44:47], v[138:141], v[188:191], v[44:47]
	v_mfma_f32_16x16x32_bf16 v[40:43], v[152:155], v[188:191], v[40:43]
	v_mfma_f32_16x16x32_bf16 v[28:31], v[138:141], v[196:199], v[28:31]
	v_mfma_f32_16x16x32_bf16 v[24:27], v[152:155], v[196:199], v[24:27]
	v_mfma_f32_16x16x32_bf16 v[12:15], v[138:141], v[204:207], v[12:15]
	v_mfma_f32_16x16x32_bf16 v[8:11], v[152:155], v[204:207], v[8:11]
	v_mfma_f32_16x16x32_bf16 v[60:63], v[142:145], v[184:187], v[60:63]
	v_mfma_f32_16x16x32_bf16 v[56:59], v[156:159], v[184:187], v[56:59]
	v_mfma_f32_16x16x32_bf16 v[44:47], v[142:145], v[192:195], v[44:47]
	v_mfma_f32_16x16x32_bf16 v[40:43], v[156:159], v[192:195], v[40:43]
	v_mfma_f32_16x16x32_bf16 v[28:31], v[142:145], v[200:203], v[28:31]
	v_mfma_f32_16x16x32_bf16 v[24:27], v[156:159], v[200:203], v[24:27]
	v_mfma_f32_16x16x32_bf16 v[12:15], v[142:145], v[218:221], v[12:15]
	v_mfma_f32_16x16x32_bf16 v[8:11], v[156:159], v[218:221], v[8:11]
	v_mfma_f32_16x16x32_bf16 v[52:55], v[160:163], v[180:183], v[52:55]
	v_mfma_f32_16x16x32_bf16 v[48:51], v[168:171], v[180:183], v[48:51]
	v_mfma_f32_16x16x32_bf16 v[36:39], v[160:163], v[188:191], v[36:39]
	v_mfma_f32_16x16x32_bf16 v[32:35], v[168:171], v[188:191], v[32:35]
	v_mfma_f32_16x16x32_bf16 v[20:23], v[160:163], v[196:199], v[20:23]
	v_mfma_f32_16x16x32_bf16 v[16:19], v[168:171], v[196:199], v[16:19]
	v_mfma_f32_16x16x32_bf16 v[4:7], v[160:163], v[204:207], v[4:7]
	v_mfma_f32_16x16x32_bf16 v[0:3], v[168:171], v[204:207], v[0:3]
	v_mfma_f32_16x16x32_bf16 v[52:55], v[164:167], v[184:187], v[52:55]
	v_mfma_f32_16x16x32_bf16 v[48:51], v[176:179], v[184:187], v[48:51]
	v_mfma_f32_16x16x32_bf16 v[36:39], v[164:167], v[192:195], v[36:39]
	v_mfma_f32_16x16x32_bf16 v[32:35], v[176:179], v[192:195], v[32:35]
	v_mfma_f32_16x16x32_bf16 v[20:23], v[164:167], v[200:203], v[20:23]
	v_mfma_f32_16x16x32_bf16 v[16:19], v[176:179], v[200:203], v[16:19]
	v_mfma_f32_16x16x32_bf16 v[4:7], v[164:167], v[218:221], v[4:7]
	v_mfma_f32_16x16x32_bf16 v[0:3], v[176:179], v[218:221], v[0:3]
	s_barrier
	s_setprio 0
	s_add_i32 s73, s73, 2
	s_add_u32 s0, s0, 0x100
	s_addc_u32 s1, s1, 0
	s_add_u32 s71, s71, 0x100
	s_addc_u32 s72, s72, 0
	s_cmp_gt_u32 s73, 13
	s_cbranch_scc0 .LBB0_1752
.LBB0_1755:
	v_lshl_add_u32 v140, s67, 8, v146
	s_lshl_b32 s38, s68, 10
	v_or_b32_e32 v144, 16, v140
	s_mov_b64 s[0:1], -1
	s_and_b64 vcc, exec, s[40:41]
	v_add_u32_e32 v151, s38, v148
	v_ashrrev_i32_e32 v141, 31, v140
	v_ashrrev_i32_e32 v145, 31, v144
	s_cbranch_vccnz .LBB0_1757
	ds_read2_b32 v[142:143], v151 offset1:16
	s_mov_b64 s[0:1], 0

; __device__ __forceinline__ unsigned cvt_pk_bf16(float lo, float hi) { unsigned r; asm volatile("v_cvt_pk_bf16_f32 %0, %1, %2" : "=v"(r) : "v"(lo), "v"(hi)); return r; }
;     __device__ __forceinline__ void operator()(const f32x4 (&acc)[2][2][4][2], const Unit& u, int wr, int wc, int fr, int fq, int ui, PG8_LAS unsigned char* lds) const {
;     ...
;             for (int m = 0; m < 4; ++m) {
;                 if ((m & 1) == 0) {
;                     if (use_tab) { rs4[m] = tab[ai * HALF + m * 16] * sc; rs4[m + 1] = tab[ai * HALF + (m + 1) * 16] * sc; }
;                     else {
;                         asm volatile("" ::: "memory");
;                         rs4[m] = __builtin_amdgcn_rsqf(ssq_row(ssq, row0 + ai * HALF + m * 16) * (1.0f / 1024.0f) + RMS_EPS) * sc;
;                         rs4[m + 1] = __builtin_amdgcn_rsqf(ssq_row(ssq, row0 + ai * HALF + (m + 1) * 16) * (1.0f / 1024.0f) + RMS_EPS) * sc;
;                     }
;                 }
;                 const int row = row0 + ai * HALF + m * 16;
;                 const float rs = rs4[m];
;                 bf16_t* rowp = O + (size_t)row * ldc + col0;
; #pragma unroll
;                 for (int bj = 0; bj < 2; ++bj) {
;                     f32x4 v[2] = {acc[ai][bj][m][0] * rs, acc[ai][bj][m][1] * rs};
;                     if (ksum) { csum[bj][0] += v[0]; csum[bj][1] += v[1]; }
; #pragma unroll
;                     for (int n = 0; n < 2; ++n) {
;                         f32x4 lbv = (f32x4){0.f, 0.f, 0.f, 0.f};
;                         if (act == 2) lbv = *(const f32x4*)(lb + (col0 - 1024) + bj * HALF + 4 * n);
; #pragma unroll
;                         for (int e = 0; e < 4; ++e) {
;                             float x = v[n][e];
;                             if (act == 1) x = silu_f(x);
;                             else if (act == 2) { const float l = lbv[e]; x = __logf(l + (1.f - l) * __builtin_amdgcn_rcpf(1.f + __expf(-x))); }
;                             else if (act == 3) { x = fmaxf(x, 0.f); x = x * x; }
;                             v[n][e] = x;
;                         }
;                     }
;                     u32x4 w; w.x = cvt_pk_bf16(v[0][0], v[0][1]); w.y = cvt_pk_bf16(v[0][2], v[0][3]); w.z = cvt_pk_bf16(v[1][0], v[1][1]); w.w = cvt_pk_bf16(v[1][2], v[1][3]);
;                     *(u32x4*)(rowp + bj * HALF) = w;
.LBB0_1759:
	s_waitcnt lgkmcnt(0)
	v_pk_mul_f32 v[120:121], v[120:121], v[142:143] op_sel_hi:[1,0]
	v_lshl_or_b32 v138, s65, 8, v149
	v_max_f32_e32 v120, 0, v120
	v_lshlrev_b64 v[152:153], 13, v[140:141]
	v_pk_mul_f32 v[122:123], v[122:123], v[142:143] op_sel_hi:[1,0]
	v_mul_f32_e32 v141, v120, v120
	v_max_f32_e32 v120, 0, v121
	v_ashrrev_i32_e32 v139, 31, v138
	v_pk_mul_f32 v[124:125], v[124:125], v[142:143] op_sel_hi:[1,0]
	v_mul_f32_e32 v154, v120, v120
	v_max_f32_e32 v120, 0, v122
	v_lshl_add_u64 v[152:153], s[14:15], 0, v[152:153]
	v_lshlrev_b64 v[138:139], 1, v[138:139]
	v_pk_mul_f32 v[126:127], v[126:127], v[142:143] op_sel_hi:[1,0]
	v_max_f32_e32 v124, 0, v124
	v_max_f32_e32 v125, 0, v125
	v_mul_f32_e32 v155, v120, v120
	v_max_f32_e32 v120, 0, v123
	v_pk_mul_f32 v[112:113], v[112:113], v[142:143] op_sel_hi:[1,0]
	v_lshl_add_u64 v[152:153], v[152:153], 0, v[138:139]
	v_mul_f32_e32 v124, v124, v124
	v_mul_f32_e32 v125, v125, v125
	v_max_f32_e32 v126, 0, v126
	v_max_f32_e32 v127, 0, v127
	v_mul_f32_e32 v123, v120, v120
	v_cvt_pk_bf16_f32 v120, v124, v125
	v_max_f32_e32 v112, 0, v112
	v_mul_f32_e32 v126, v126, v126
	v_mul_f32_e32 v127, v127, v127
	v_cvt_pk_bf16_f32 v121, v126, v127
	v_cvt_pk_bf16_f32 v122, v141, v154
	v_cvt_pk_bf16_f32 v123, v155, v123
	global_store_dwordx4 v[152:153], v[120:123], off
	v_pk_mul_f32 v[114:115], v[114:115], v[142:143] op_sel_hi:[1,0]
	v_pk_mul_f32 v[118:119], v[118:119], v[142:143] op_sel_hi:[1,0]
	v_mul_f32_e32 v120, v112, v112
	v_max_f32_e32 v112, 0, v113
	v_pk_mul_f32 v[116:117], v[116:117], v[142:143] op_sel_hi:[1,0]
	v_mul_f32_e32 v121, v112, v112
	v_max_f32_e32 v112, 0, v114
	v_max_f32_e32 v116, 0, v116
	v_max_f32_e32 v117, 0, v117
	v_max_f32_e32 v118, 0, v118
	v_max_f32_e32 v119, 0, v119
	v_mul_f32_e32 v122, v112, v112
	v_max_f32_e32 v112, 0, v115
	v_mul_f32_e32 v116, v116, v116
	v_mul_f32_e32 v117, v117, v117
	v_mul_f32_e32 v118, v118, v118
	v_mul_f32_e32 v119, v119, v119
	v_mul_f32_e32 v115, v112, v112
	v_cvt_pk_bf16_f32 v112, v116, v117
	v_cvt_pk_bf16_f32 v113, v118, v119
	v_cvt_pk_bf16_f32 v114, v120, v121
	v_cvt_pk_bf16_f32 v115, v122, v115
	global_store_dwordx4 v[152:153], v[112:115], off offset:256
	s_and_b64 vcc, exec, s[46:47]
	s_cbranch_vccz .Lal3_skip
	s_barrier
.Lal3_skip:
	s_mov_b64 s[0:1], -1
	s_and_b64 vcc, exec, s[40:41]
	v_mov_b32_e32 v114, v143
	v_pk_mul_f32 v[104:105], v[104:105], v[114:115] op_sel_hi:[1,0]
	v_pk_mul_f32 v[110:111], v[110:111], v[114:115] op_sel_hi:[1,0]
	v_max_f32_e32 v104, 0, v104
	v_pk_mul_f32 v[108:109], v[108:109], v[114:115] op_sel_hi:[1,0]
	v_pk_mul_f32 v[106:107], v[106:107], v[114:115] op_sel_hi:[1,0]
	v_mul_f32_e32 v115, v104, v104
	v_max_f32_e32 v104, 0, v105
	v_lshlrev_b64 v[112:113], 13, v[144:145]
	v_mul_f32_e32 v116, v104, v104
	v_max_f32_e32 v104, 0, v106
	v_lshl_add_u64 v[112:113], s[14:15], 0, v[112:113]
	v_max_f32_e32 v108, 0, v108
	v_max_f32_e32 v109, 0, v109
	v_mul_f32_e32 v117, v104, v104
	v_max_f32_e32 v104, 0, v107
	v_pk_mul_f32 v[96:97], v[96:97], v[114:115] op_sel_hi:[1,0]
	v_lshl_add_u64 v[112:113], v[112:113], 0, v[138:139]
	v_mul_f32_e32 v108, v108, v108
	v_mul_f32_e32 v109, v109, v109
	v_max_f32_e32 v110, 0, v110
	v_max_f32_e32 v111, 0, v111
	v_mul_f32_e32 v107, v104, v104
	v_cvt_pk_bf16_f32 v104, v108, v109
	v_max_f32_e32 v96, 0, v96
	v_mul_f32_e32 v110, v110, v110
	v_mul_f32_e32 v111, v111, v111
	v_cvt_pk_bf16_f32 v105, v110, v111
	v_cvt_pk_bf16_f32 v106, v115, v116
	v_cvt_pk_bf16_f32 v107, v117, v107
	global_store_dwordx4 v[112:113], v[104:107], off
	v_pk_mul_f32 v[98:99], v[98:99], v[114:115] op_sel_hi:[1,0]
	v_pk_mul_f32 v[102:103], v[102:103], v[114:115] op_sel_hi:[1,0]
	v_mul_f32_e32 v104, v96, v96
	v_max_f32_e32 v96, 0, v97
	v_pk_mul_f32 v[100:101], v[100:101], v[114:115] op_sel_hi:[1,0]
	v_mul_f32_e32 v105, v96, v96
	v_max_f32_e32 v96, 0, v98
	v_max_f32_e32 v100, 0, v100
	v_max_f32_e32 v101, 0, v101
	v_max_f32_e32 v102, 0, v102
	v_max_f32_e32 v103, 0, v103
	v_mul_f32_e32 v106, v96, v96
	v_max_f32_e32 v96, 0, v99
	v_mul_f32_e32 v100, v100, v100
	v_mul_f32_e32 v101, v101, v101
	v_mul_f32_e32 v102, v102, v102
	v_mul_f32_e32 v103, v103, v103
	v_mul_f32_e32 v99, v96, v96
	v_cvt_pk_bf16_f32 v96, v100, v101
	v_cvt_pk_bf16_f32 v97, v102, v103
	v_cvt_pk_bf16_f32 v98, v104, v105
	v_cvt_pk_bf16_f32 v99, v106, v99
	global_store_dwordx4 v[112:113], v[96:99], off offset:256
	s_nop 1
	v_or_b32_e32 v98, 32, v140
	v_or_b32_e32 v96, 48, v140
	v_ashrrev_i32_e32 v99, 31, v98
	v_ashrrev_i32_e32 v97, 31, v96
	s_cbranch_vccnz .LBB0_1761
	ds_read2_b32 v[100:101], v151 offset0:32 offset1:48
	s_mov_b64 s[0:1], 0
	s_waitcnt lgkmcnt(0)
	v_mov_b32_e32 v102, v101

; __device__ __forceinline__ unsigned cvt_pk_bf16(float lo, float hi) { unsigned r; asm volatile("v_cvt_pk_bf16_f32 %0, %1, %2" : "=v"(r) : "v"(lo), "v"(hi)); return r; }
;     __device__ __forceinline__ void operator()(const f32x4 (&acc)[2][2][4][2], const Unit& u, int wr, int wc, int fr, int fq, int, PG8_LAS unsigned char*) const {
;     ...
;         for (int ai = 0; ai < 2; ++ai) {
;             u32x4 xw[4][2];
; #pragma unroll
;             for (int m = 0; m < 4; ++m)
; #pragma unroll
;                 for (int bj = 0; bj < 2; ++bj) xw[m][bj] = *(const u32x4*)(xb + (size_t)(row0 + ai * HALF + m * 16) * 1024 + col0 + bj * HALF);
; #pragma unroll
;             for (int m = 0; m < 4; ++m) {
;                 const int row = row0 + ai * HALF + m * 16; const size_t off = (size_t)row * 1024 + col0;
;                 float s = 0.f;
; #pragma unroll
;                 for (int bj = 0; bj < 2; ++bj) {
;                     const u32x4 xv = xw[m][bj];
;                     const f32x4 xo0 = {__builtin_bit_cast(float, xv.x << 16), __builtin_bit_cast(float, xv.x & 0xffff0000u), __builtin_bit_cast(float, xv.y << 16), __builtin_bit_cast(float, xv.y & 0xffff0000u)};
;                     const f32x4 xo1 = {__builtin_bit_cast(float, xv.z << 16), __builtin_bit_cast(float, xv.z & 0xffff0000u), __builtin_bit_cast(float, xv.w << 16), __builtin_bit_cast(float, xv.w & 0xffff0000u)};
;                     const f32x4 o0 = xo0 + acc[ai][bj][m][0] * csv[bj][0], o1 = xo1 + acc[ai][bj][m][1] * csv[bj][1];
;                     u32x4 w; w.x = cvt_pk_bf16(o0[0], o0[1]); w.y = cvt_pk_bf16(o0[2], o0[3]); w.z = cvt_pk_bf16(o1[0], o1[1]); w.w = cvt_pk_bf16(o1[2], o1[3]);
;                     if (!dry) *(u32x4*)(xb + off + bj * HALF) = w;
; #pragma unroll
;                     for (int q = 0; q < 4; ++q) { const unsigned ww = w[q]; const float ra = __builtin_bit_cast(float, ww << 16), rb = __builtin_bit_cast(float, ww & 0xffff0000u); s += ra * ra + rb * rb; }
;                 }
;                 s += __shfl_xor(s, 16); s += __shfl_xor(s, 32);
;                 if (fq == 0 && !dry) ssq_next[(size_t)row * 16 + u.pn * 4 + wc] = s;
.LBB0_1848:
	v_lshl_or_b32 v162, s16, 8, v190
	v_ashrrev_i32_e32 v163, 31, v162
	v_lshl_add_u32 v166, s68, 8, v188
	v_lshlrev_b64 v[128:129], 1, v[162:163]
	v_ashrrev_i32_e32 v167, 31, v166
	v_lshl_add_u64 v[164:165], s[10:11], 0, v[128:129]
	v_lshlrev_b64 v[130:131], 11, v[166:167]
	v_lshl_add_u64 v[132:133], v[164:165], 0, v[130:131]
	global_load_dwordx4 v[176:179], v[132:133], off
	global_load_dwordx4 v[192:195], v[132:133], off offset:256
	v_or_b32_e32 v184, 16, v166
	v_or_b32_e32 v180, 32, v166
	v_or_b32_e32 v168, 48, v166
	v_ashrrev_i32_e32 v185, 31, v184
	v_ashrrev_i32_e32 v181, 31, v180
	v_ashrrev_i32_e32 v169, 31, v168
	v_lshlrev_b64 v[186:187], 11, v[184:185]
	v_lshlrev_b64 v[182:183], 11, v[180:181]
	v_lshlrev_b64 v[170:171], 11, v[168:169]
	v_lshl_add_u64 v[130:131], s[10:11], 0, v[130:131]
	v_lshl_add_u64 v[132:133], v[164:165], 0, v[186:187]
	v_lshl_add_u64 v[134:135], v[164:165], 0, v[182:183]
	v_lshl_add_u64 v[172:173], v[164:165], 0, v[170:171]
	v_lshl_add_u64 v[196:197], v[130:131], 0, v[128:129]
	global_load_dwordx4 v[148:151], v[132:133], off
	global_load_dwordx4 v[144:147], v[132:133], off offset:256
	global_load_dwordx4 v[140:143], v[134:135], off
	global_load_dwordx4 v[136:139], v[134:135], off offset:256
	s_nop 0
	global_load_dwordx4 v[132:135], v[172:173], off
	global_load_dwordx4 v[128:131], v[172:173], off offset:256
	s_lshl_b32 s0, s16, 2
	s_ashr_i32 s1, s0, 31
	s_and_b64 vcc, exec, s[38:39]
	s_cbranch_vccz .Lal4_skip
	s_barrier
.Lal4_skip:
	s_waitcnt vmcnt(0)
	v_lshlrev_b32_e32 v172, 16, v176
	v_and_b32_e32 v173, 0xffff0000, v176
	v_lshlrev_b32_e32 v176, 16, v177
	v_and_b32_e32 v177, 0xffff0000, v177
	v_lshlrev_b32_e32 v198, 16, v178
	v_and_b32_e32 v199, 0xffff0000, v178
	v_lshlrev_b32_e32 v202, 16, v194
	v_and_b32_e32 v203, 0xffff0000, v194
	v_lshlrev_b32_e32 v178, 16, v179
	v_and_b32_e32 v179, 0xffff0000, v179
	v_lshlrev_b32_e32 v194, 16, v195
	v_and_b32_e32 v195, 0xffff0000, v195
	v_pk_add_f32 v[126:127], v[126:127], v[176:177]
	v_pk_add_f32 v[124:125], v[124:125], v[172:173]
	v_pk_add_f32 v[120:121], v[120:121], v[198:199]
	v_pk_add_f32 v[176:177], v[112:113], v[202:203]
	v_cvt_pk_bf16_f32 v112, v124, v125
	v_cvt_pk_bf16_f32 v113, v126, v127
	v_pk_add_f32 v[122:123], v[122:123], v[178:179]
	v_pk_add_f32 v[172:173], v[114:115], v[194:195]
	v_cvt_pk_bf16_f32 v114, v120, v121
	v_cvt_pk_bf16_f32 v115, v122, v123
	global_store_dwordx4 v[196:197], v[112:115], off
	v_lshlrev_b32_e32 v120, 16, v112
	v_lshlrev_b32_e32 v121, 16, v113
	v_and_b32_e32 v112, 0xffff0000, v112
	v_and_b32_e32 v113, 0xffff0000, v113
	v_lshlrev_b32_e32 v200, 16, v192
	v_and_b32_e32 v201, 0xffff0000, v192
	v_lshlrev_b32_e32 v122, 16, v114
	v_and_b32_e32 v114, 0xffff0000, v114
	v_mul_f32_e32 v112, v112, v112
	v_mul_f32_e32 v113, v113, v113
	v_pk_add_f32 v[116:117], v[116:117], v[200:201]
	v_lshlrev_b32_e32 v123, 16, v115
	v_and_b32_e32 v115, 0xffff0000, v115
	v_mul_f32_e32 v114, v114, v114
	v_fmac_f32_e32 v112, v120, v120
	v_fmac_f32_e32 v113, v121, v121
	v_lshlrev_b32_e32 v192, 16, v193
	v_and_b32_e32 v193, 0xffff0000, v193
	v_cvt_pk_bf16_f32 v116, v116, v117
	v_mul_f32_e32 v115, v115, v115
	v_and_b32_e32 v125, 0xffff0000, v116
	v_fmac_f32_e32 v114, v122, v122
	v_add_f32_e32 v112, v112, v113
	v_pk_add_f32 v[118:119], v[118:119], v[192:193]
	v_lshlrev_b32_e32 v124, 16, v116
	v_cvt_pk_bf16_f32 v117, v118, v119
	v_fmac_f32_e32 v115, v123, v123
	v_and_b32_e32 v127, 0xffff0000, v117
	v_mul_f32_e32 v120, v125, v125
	v_add_f32_e32 v112, v112, v114
	v_cvt_pk_bf16_f32 v118, v176, v177
	v_cvt_pk_bf16_f32 v119, v172, v173
	v_lshlrev_b32_e32 v126, 16, v117
	v_and_b32_e32 v173, 0xffff0000, v118
	v_mul_f32_e32 v121, v127, v127
	v_fmac_f32_e32 v120, v124, v124
	v_add_f32_e32 v112, v112, v115
	v_lshlrev_b32_e32 v172, 16, v118
	v_mul_f32_e32 v122, v173, v173
	v_fmac_f32_e32 v121, v126, v126
	v_add_f32_e32 v112, v112, v120
	v_and_b32_e32 v114, 0xffff0000, v119
	v_fmac_f32_e32 v122, v172, v172
	v_add_f32_e32 v112, v112, v121
	v_lshlrev_b32_e32 v113, 16, v119
	v_mul_f32_e32 v114, v114, v114
	v_add_f32_e32 v112, v112, v122
	v_fmac_f32_e32 v114, v113, v113
	v_add_f32_e32 v113, v112, v114
	v_and_b32_e32 v114, 64, v213
	v_xor_b32_e32 v112, 16, v213
	v_add_u32_e32 v115, 64, v114
	v_cmp_lt_i32_e32 vcc, v112, v115
	global_store_dwordx4 v[196:197], v[116:119], off offset:256
	s_nop 0
	v_cndmask_b32_e32 v112, v213, v112, vcc
	v_lshlrev_b32_e32 v112, 2, v112
	ds_bpermute_b32 v114, v112, v113
	s_waitcnt lgkmcnt(0)
	v_add_f32_e32 v114, v113, v114
	v_xor_b32_e32 v113, 32, v213
	v_cmp_lt_i32_e32 vcc, v113, v115
	s_nop 1
	v_cndmask_b32_e32 v113, v213, v113, vcc
	v_lshlrev_b32_e32 v113, 2, v113
	ds_bpermute_b32 v115, v113, v114
	s_and_saveexec_b64 s[54:55], s[40:41]
	s_cbranch_execz .LBB0_1850
	v_lshlrev_b64 v[116:117], 6, v[166:167]
	v_lshl_add_u64 v[116:117], s[24:25], 0, v[116:117]
	v_lshl_add_u64 v[116:117], s[0:1], 2, v[116:117]
	s_lshl_b32 s16, s63, 2
	v_lshl_add_u64 v[116:117], v[116:117], 0, s[16:17]
	s_waitcnt lgkmcnt(0)
	v_add_f32_e32 v114, v114, v115
	global_store_dword v[116:117], v114, off
